# compute segments of all GEMM loops: mid-segment priority toggle pair and the redundant post-barrier lgkmcnt wait removed (guide 6.4: bare MFMA head)
# speedup vs baseline: 1.0133x; 1.0133x over previous
;     __host__ __device__ bool next(int i, Unit& u) const { if (!b.next(i >> 1, u)) return false; u.sel = i & 1; return true; }
; #define PG8_STAGE(bufoff, gbase, voff) do { _Pragma("unroll") for (int _i = 0; _i < 2; ++_i) \
;         __builtin_amdgcn_global_load_lds((const unsigned*)((const char*)(gbase) + (voff)[_i]), (PG8_LAS unsigned*)(lds + (bufoff) + ldsw + _i * 8192), 16, 0, 0); } while (0)
; #define PG8_BAR __builtin_amdgcn_s_barrier()
;     __host__ __device__ bool next(int i, Unit& u) const {
;         const long L = (long)i * G + c; if (L >= nwg) return false;
;         int wgid = (int)L; { const int q = nwg / NXCD, r = nwg % NXCD, xcd = wgid % NXCD, off = wgid / NXCD; wgid = (xcd < r ? xcd * (q + 1) : r * (q + 1) + (xcd - r) * q) + off; }
;         const int nig = WGM * nN, gid = wgid / nig, fm = gid * WGM, gsz = (nM - fm) < WGM ? (nM - fm) : WGM;
;         u.pm = fm + ((wgid % nig) % gsz); u.pn = (wgid % nig) / gsz; u.sel = 0; return true;
; template <class Epi, class Sched, bool ALIGN_EPI = false, bool SP2 = false>
; __device__ __forceinline__ void gemm_phase(PG8_LAS unsigned char* lds, const Gemm g, const Sched& S, const Epi& E) {
;     ...
;         const bool has_next = S.next(ui + 1, nxt);
;         const char* nA = has_next ? PG8_ABASE(nxt) : cA; const char* nB = has_next ? PG8_BBASE(nxt) : cB;
;         for (int t = 0; t < nt; t += 2) {
;             const bool last = (t == nt - 2);
;             const char* a1 = cA + (size_t)(t + 1) * kstepA;
;             const char* a2 = last ? nA : cA + (size_t)(t + 2) * kstepA; const char* b2 = last ? nB : cB + (size_t)(t + 2) * kstep;
;             const char* a3 = a2 + kstepA; const char* b3 = b2 + kstep;
;             if (last && has_next) S.a_ready(nxt);
;             if constexpr (SP2) {
;             PG8_LDB(B0, 0, 0); PG8_LDB(B1, 0, 1); PG8_SCHED; PG8_LDA(At, 0, 0); PG8_STAGE(PG8_SA(1, 1), a1 + hstep, voffA);
;             PG8_WAIT_V(8); PG8_WAIT_L(0); PG8_BAR; PG8_MMA(0, 0, At, B0); PG8_MMA(0, 1, At, B1); PG8_BAR; PG8_SCHED;
;             if constexpr (Epi::PREFETCH) { if (t == tpf) E.prefetch(cur, wid, lane); }
;             PG8_LDA(At, 0, 1); PG8_STAGE(PG8_SB(0, 0), b2, voffB); PG8_STAGE(PG8_SB(0, 1), b2 + hstep, voffB); PG8_STAGE(PG8_SA(0, 0), a2, voffA);
;             PG8_WAIT_V(8); PG8_WAIT_L(0); PG8_BAR; PG8_MMA(1, 0, At, B0); PG8_MMA(1, 1, At, B1); PG8_BAR; PG8_SCHED;
.LBB0_205:
	s_add_u32 s22, s22, 0x40080
	s_addc_u32 s23, s23, 0
	s_add_u32 s52, s24, 0x100
	s_addc_u32 s53, s25, 0
	s_mov_b32 s54, -2
	ds_read_b128 v[154:157], v150
	ds_read_b128 v[158:161], v150 offset:1024
	ds_read_b128 v[162:165], v150 offset:2048
	ds_read_b128 v[166:169], v150 offset:3072
	ds_read_b128 v[170:173], v151
	ds_read_b128 v[174:177], v151 offset:1024
	ds_read_b128 v[178:181], v151 offset:2048
	ds_read_b128 v[182:185], v151 offset:3072
	s_add_u32 s24, s22, 0xfffc0080
	s_addc_u32 s25, s23, -1
	s_cmp_eq_u32 s54, 12
	s_cselect_b32 s27, s15, s25
	s_cselect_b32 s26, s50, s24
	s_cselect_b32 s25, s13, s53
	s_cselect_b32 s24, s51, s52
	v_lshl_add_u64 v[218:219], s[22:23], 0, v[140:141]
	s_add_i32 m0, s37, 0xc000
	ds_read_b128 v[186:189], v152
	ds_read_b128 v[190:193], v152 offset:1024
	ds_read_b128 v[194:197], v152 offset:2048
	ds_read_b128 v[198:201], v152 offset:3072
	ds_read_b128 v[202:205], v152 offset:4096
	ds_read_b128 v[206:209], v152 offset:5120
	ds_read_b128 v[210:213], v152 offset:6144
	ds_read_b128 v[214:217], v152 offset:7168
	global_load_lds_dwordx4 v[218:219], off
	v_lshl_add_u64 v[218:219], s[22:23], 0, v[142:143]
	s_add_i32 m0, s37, 0xe000
	s_nop 0
	global_load_lds_dwordx4 v[218:219], off
	s_add_i32 s44, s44, 1
	s_mul_i32 s0, s44, s46
	s_mul_hi_u32 s1, s44, s33
	s_add_i32 s1, s1, s0
	s_mul_i32 s0, s44, s33
	s_add_u32 s16, s0, s87
	s_addc_u32 s17, s1, s35
	v_cmp_lt_i64_e64 s[0:1], s[16:17], v[144:145]
	s_ashr_i32 s12, s16, 31
	s_lshr_b32 s12, s12, 29
	s_add_i32 s12, s16, s12
	s_ashr_i32 s13, s12, 3
	s_and_b32 s12, s12, -8
	s_sub_i32 s12, s16, s12
	s_cmp_lt_i32 s12, 0
	s_cselect_b32 s14, s36, 0x160
	s_mul_i32 s12, s12, s14
	s_add_i32 s12, s12, s13
	s_mul_hi_i32 s13, s12, 0x2e8ba2e9
	s_lshr_b32 s14, s13, 31
	s_ashr_i32 s13, s13, 3
	s_add_i32 s13, s13, s14
	s_lshl_b32 s14, s13, 1
	s_mul_i32 s13, s13, 44
	s_sub_i32 s13, s12, s13
	s_lshr_b32 s12, s13, 1
	s_and_b32 s13, s13, 1
	s_add_i32 s14, s14, s13
	s_ashr_i32 s15, s14, 31
	s_lshl_b64 s[16:17], s[14:15], 19
	s_add_u32 s16, s28, s16
	s_addc_u32 s17, s29, s17
	s_and_b64 s[18:19], s[0:1], exec
	s_cselect_b32 s15, s17, s29
	s_cselect_b32 s50, s16, s28
	s_ashr_i32 s13, s12, 31
	s_lshl_b64 s[18:19], s[12:13], 19
	s_add_u32 s18, s30, s18
	s_addc_u32 s19, s31, s19
	s_and_b64 s[98:99], s[0:1], exec
	s_cselect_b32 s13, s19, s31
	s_cselect_b32 s51, s18, s30
	s_waitcnt vmcnt(8)
	s_waitcnt lgkmcnt(0)
	s_barrier
	s_setprio 1
	v_mfma_f32_16x16x32_bf16 v[126:129], v[154:157], v[186:189], 0
	v_mfma_f32_16x16x32_bf16 v[122:125], v[162:165], v[186:189], 0
	v_mfma_f32_16x16x32_bf16 v[110:113], v[154:157], v[194:197], 0
	v_mfma_f32_16x16x32_bf16 v[106:109], v[162:165], v[194:197], 0
	v_mfma_f32_16x16x32_bf16 v[94:97], v[154:157], v[202:205], 0
	v_mfma_f32_16x16x32_bf16 v[90:93], v[162:165], v[202:205], 0
	v_mfma_f32_16x16x32_bf16 v[78:81], v[154:157], v[210:213], 0
	v_mfma_f32_16x16x32_bf16 v[74:77], v[162:165], v[210:213], 0
	v_mfma_f32_16x16x32_bf16 v[126:129], v[158:161], v[190:193], v[126:129]
	v_mfma_f32_16x16x32_bf16 v[122:125], v[166:169], v[190:193], v[122:125]
	v_mfma_f32_16x16x32_bf16 v[110:113], v[158:161], v[198:201], v[110:113]
	v_mfma_f32_16x16x32_bf16 v[106:109], v[166:169], v[198:201], v[106:109]
	v_mfma_f32_16x16x32_bf16 v[94:97], v[158:161], v[206:209], v[94:97]
	v_mfma_f32_16x16x32_bf16 v[90:93], v[166:169], v[206:209], v[90:93]
	v_mfma_f32_16x16x32_bf16 v[78:81], v[158:161], v[214:217], v[78:81]
	v_mfma_f32_16x16x32_bf16 v[74:77], v[166:169], v[214:217], v[74:77]
	v_mfma_f32_16x16x32_bf16 v[118:121], v[170:173], v[186:189], 0
	v_mfma_f32_16x16x32_bf16 v[114:117], v[178:181], v[186:189], 0
	v_mfma_f32_16x16x32_bf16 v[102:105], v[170:173], v[194:197], 0
	v_mfma_f32_16x16x32_bf16 v[98:101], v[178:181], v[194:197], 0
	v_mfma_f32_16x16x32_bf16 v[86:89], v[170:173], v[202:205], 0
	v_mfma_f32_16x16x32_bf16 v[82:85], v[178:181], v[202:205], 0
	v_mfma_f32_16x16x32_bf16 v[70:73], v[170:173], v[210:213], 0
	v_mfma_f32_16x16x32_bf16 v[66:69], v[178:181], v[210:213], 0
	v_mfma_f32_16x16x32_bf16 v[118:121], v[174:177], v[190:193], v[118:121]
	v_mfma_f32_16x16x32_bf16 v[114:117], v[182:185], v[190:193], v[114:117]
	v_mfma_f32_16x16x32_bf16 v[102:105], v[174:177], v[198:201], v[102:105]
	v_mfma_f32_16x16x32_bf16 v[98:101], v[182:185], v[198:201], v[98:101]
	v_mfma_f32_16x16x32_bf16 v[86:89], v[174:177], v[206:209], v[86:89]
	v_mfma_f32_16x16x32_bf16 v[82:85], v[182:185], v[206:209], v[82:85]
	v_mfma_f32_16x16x32_bf16 v[70:73], v[174:177], v[214:217], v[70:73]
	v_mfma_f32_16x16x32_bf16 v[66:69], v[182:185], v[214:217], v[66:69]
	s_setprio 0
	s_barrier
	s_add_i32 s55, s47, s34
	v_lshl_add_u64 v[218:219], s[24:25], 0, v[134:135]
	s_mov_b32 m0, s55
	ds_read_b128 v[186:189], v152 offset:16384
	ds_read_b128 v[190:193], v152 offset:17408
	ds_read_b128 v[194:197], v152 offset:18432
	ds_read_b128 v[198:201], v152 offset:19456
	ds_read_b128 v[202:205], v152 offset:20480
	ds_read_b128 v[206:209], v152 offset:21504
	ds_read_b128 v[210:213], v152 offset:22528
	ds_read_b128 v[214:217], v152 offset:23552
	global_load_lds_dwordx4 v[218:219], off
	s_add_i32 m0, s55, 0x2000
	s_add_u32 s56, s24, 0x40000
	v_lshl_add_u64 v[222:223], s[24:25], 0, v[130:131]
	s_addc_u32 s57, s25, 0
	s_add_i32 s55, s48, s34
	global_load_lds_dwordx4 v[222:223], off
	v_lshl_add_u64 v[224:225], s[56:57], 0, v[134:135]
	s_mov_b32 m0, s55
	v_lshl_add_u64 v[226:227], s[26:27], 0, v[132:133]
	global_load_lds_dwordx4 v[224:225], off
	v_lshl_add_u64 v[224:225], s[56:57], 0, v[130:131]
	s_add_i32 m0, s55, 0x2000
	s_nop 0
	global_load_lds_dwordx4 v[224:225], off
	v_lshl_add_u64 v[224:225], s[26:27], 0, v[136:137]
	s_mov_b32 m0, s37
	s_nop 0
	global_load_lds_dwordx4 v[224:225], off
	s_mov_b32 m0, s38
	s_nop 0
	global_load_lds_dwordx4 v[226:227], off
	s_waitcnt vmcnt(8)
	s_waitcnt lgkmcnt(0)
	s_barrier
; #define PG8_STAGE(bufoff, gbase, voff) do { _Pragma("unroll") for (int _i = 0; _i < 2; ++_i) \
;         __builtin_amdgcn_global_load_lds((const unsigned*)((const char*)(gbase) + (voff)[_i]), (PG8_LAS unsigned*)(lds + (bufoff) + ldsw + _i * 8192), 16, 0, 0); } while (0)
; #define PG8_LDA(dst, b, h) do { _Pragma("unroll") for (int m = 0; m < 4; ++m) _Pragma("unroll") for (int k = 0; k < 2; ++k) dst[m][k] = *(const PG8_LAS bf16x8*)(lds + PG8_SA(b, h) + aoff + m * 2048 + k * 1024); } while (0)
; #define PG8_LDB(dst, b, h) do { _Pragma("unroll") for (int n = 0; n < 2; ++n) _Pragma("unroll") for (int k = 0; k < 2; ++k) dst[n][k] = *(const PG8_LAS bf16x8*)(lds + PG8_SB(b, h) + boff + n * 2048 + k * 1024); } while (0)
; #define PG8_MMA(ai, bj, At, Bt) do { __builtin_amdgcn_s_setprio(1); _Pragma("unroll") for (int m = 0; m < 4; ++m) _Pragma("unroll") for (int n = 0; n < 2; ++n) _Pragma("unroll") for (int k = 0; k < 2; ++k) \
;         acc[ai][bj][m][n] = __builtin_amdgcn_mfma_f32_16x16x32_bf16(Bt[n][k], At[m][k], acc[ai][bj][m][n], 0, 0, 0); __builtin_amdgcn_s_setprio(0); } while (0)
; #define PG8_WAIT_V(n) asm volatile("s_waitcnt vmcnt(" #n ")" ::: "memory")
; #define PG8_WAIT_L(n) asm volatile("s_waitcnt lgkmcnt(" #n ")" ::: "memory")
; #define PG8_BAR __builtin_amdgcn_s_barrier()
; #define PG8_SCHED __builtin_amdgcn_sched_barrier(0)
;     __device__ __forceinline__ void prefetch(const Unit& u, int wid, int lane) const { epi_prefetch(scr, ssq, bias + (size_t)(u.pm >> 5) * NGU + u.pn * BM, u, wid, lane); }
; template <class Epi, class Sched, bool ALIGN_EPI = false, bool SP2 = false>
; __device__ __forceinline__ void gemm_phase(PG8_LAS unsigned char* lds, const Gemm g, const Sched& S, const Epi& E) {
;     ...
;             PG8_LDB(B0, 0, 0); PG8_LDB(B1, 0, 1); PG8_SCHED; PG8_LDA(At, 0, 0); PG8_STAGE(PG8_SA(1, 1), a1 + hstep, voffA);
;             PG8_WAIT_V(8); PG8_WAIT_L(0); PG8_BAR; PG8_MMA(0, 0, At, B0); PG8_MMA(0, 1, At, B1); PG8_BAR; PG8_SCHED;
;             if constexpr (Epi::PREFETCH) { if (t == tpf) E.prefetch(cur, wid, lane); }
;             PG8_LDA(At, 0, 1); PG8_STAGE(PG8_SB(0, 0), b2, voffB); PG8_STAGE(PG8_SB(0, 1), b2 + hstep, voffB); PG8_STAGE(PG8_SA(0, 0), a2, voffA);
;             PG8_WAIT_V(8); PG8_WAIT_L(0); PG8_BAR; PG8_MMA(1, 0, At, B0); PG8_MMA(1, 1, At, B1); PG8_BAR; PG8_SCHED;
	s_setprio 1
	v_mfma_f32_16x16x32_bf16 v[62:65], v[154:157], v[186:189], 0
	v_mfma_f32_16x16x32_bf16 v[58:61], v[162:165], v[186:189], 0
	v_mfma_f32_16x16x32_bf16 v[46:49], v[154:157], v[194:197], 0
	v_mfma_f32_16x16x32_bf16 v[42:45], v[162:165], v[194:197], 0
	v_mfma_f32_16x16x32_bf16 v[30:33], v[154:157], v[202:205], 0
	v_mfma_f32_16x16x32_bf16 v[26:29], v[162:165], v[202:205], 0
	v_mfma_f32_16x16x32_bf16 v[14:17], v[154:157], v[210:213], 0
	v_mfma_f32_16x16x32_bf16 v[10:13], v[162:165], v[210:213], 0
	v_mfma_f32_16x16x32_bf16 v[62:65], v[158:161], v[190:193], v[62:65]
	v_mfma_f32_16x16x32_bf16 v[58:61], v[166:169], v[190:193], v[58:61]
	v_mfma_f32_16x16x32_bf16 v[46:49], v[158:161], v[198:201], v[46:49]
	v_mfma_f32_16x16x32_bf16 v[42:45], v[166:169], v[198:201], v[42:45]
	v_mfma_f32_16x16x32_bf16 v[30:33], v[158:161], v[206:209], v[30:33]
	v_mfma_f32_16x16x32_bf16 v[26:29], v[166:169], v[206:209], v[26:29]
	v_mfma_f32_16x16x32_bf16 v[14:17], v[158:161], v[214:217], v[14:17]
	v_mfma_f32_16x16x32_bf16 v[10:13], v[166:169], v[214:217], v[10:13]
	v_mfma_f32_16x16x32_bf16 v[54:57], v[170:173], v[186:189], 0
	v_mfma_f32_16x16x32_bf16 v[50:53], v[178:181], v[186:189], 0
	v_mfma_f32_16x16x32_bf16 v[38:41], v[170:173], v[194:197], 0
	v_mfma_f32_16x16x32_bf16 v[34:37], v[178:181], v[194:197], 0
	v_mfma_f32_16x16x32_bf16 v[22:25], v[170:173], v[202:205], 0
	v_mfma_f32_16x16x32_bf16 v[18:21], v[178:181], v[202:205], 0
	v_mfma_f32_16x16x32_bf16 v[6:9], v[170:173], v[210:213], 0
	v_mfma_f32_16x16x32_bf16 v[2:5], v[178:181], v[210:213], 0
	v_mfma_f32_16x16x32_bf16 v[54:57], v[174:177], v[190:193], v[54:57]
	v_mfma_f32_16x16x32_bf16 v[50:53], v[182:185], v[190:193], v[50:53]
	v_mfma_f32_16x16x32_bf16 v[38:41], v[174:177], v[198:201], v[38:41]
	v_mfma_f32_16x16x32_bf16 v[34:37], v[182:185], v[198:201], v[34:37]
	v_mfma_f32_16x16x32_bf16 v[22:25], v[174:177], v[206:209], v[22:25]
	v_mfma_f32_16x16x32_bf16 v[18:21], v[182:185], v[206:209], v[18:21]
	v_mfma_f32_16x16x32_bf16 v[6:9], v[174:177], v[214:217], v[6:9]
	v_mfma_f32_16x16x32_bf16 v[2:5], v[182:185], v[214:217], v[2:5]
	s_setprio 0
	s_barrier
	s_branch .Lpz1_mid
.LBB0_208:
	ds_read_b128 v[154:157], v150
	ds_read_b128 v[158:161], v150 offset:1024
	ds_read_b128 v[162:165], v150 offset:2048
	ds_read_b128 v[166:169], v150 offset:3072
	ds_read_b128 v[170:173], v151
	ds_read_b128 v[174:177], v151 offset:1024
	ds_read_b128 v[178:181], v151 offset:2048
	ds_read_b128 v[182:185], v151 offset:3072
	s_add_u32 s24, s22, 0xfffc0080
	s_addc_u32 s25, s23, -1
	s_cmp_eq_u32 s54, 12
	s_cselect_b32 s27, s15, s25
	s_cselect_b32 s26, s50, s24
	s_cselect_b32 s25, s13, s53
	s_cselect_b32 s24, s51, s52
	v_lshl_add_u64 v[218:219], s[22:23], 0, v[140:141]
	s_add_i32 m0, s37, 0xc000
	ds_read_b128 v[186:189], v152
	ds_read_b128 v[190:193], v152 offset:1024
	ds_read_b128 v[194:197], v152 offset:2048
	ds_read_b128 v[198:201], v152 offset:3072
	ds_read_b128 v[202:205], v152 offset:4096
	ds_read_b128 v[206:209], v152 offset:5120
	ds_read_b128 v[210:213], v152 offset:6144
	ds_read_b128 v[214:217], v152 offset:7168
	global_load_lds_dwordx4 v[218:219], off
	v_lshl_add_u64 v[218:219], s[22:23], 0, v[142:143]
	s_add_i32 m0, s37, 0xe000
	s_nop 0
	global_load_lds_dwordx4 v[218:219], off
	s_waitcnt vmcnt(8)
	s_waitcnt lgkmcnt(0)
	s_barrier
	s_setprio 1
	v_mfma_f32_16x16x32_bf16 v[126:129], v[154:157], v[186:189], v[126:129]
	v_mfma_f32_16x16x32_bf16 v[122:125], v[162:165], v[186:189], v[122:125]
	v_mfma_f32_16x16x32_bf16 v[110:113], v[154:157], v[194:197], v[110:113]
	v_mfma_f32_16x16x32_bf16 v[106:109], v[162:165], v[194:197], v[106:109]
	v_mfma_f32_16x16x32_bf16 v[94:97], v[154:157], v[202:205], v[94:97]
	v_mfma_f32_16x16x32_bf16 v[90:93], v[162:165], v[202:205], v[90:93]
	v_mfma_f32_16x16x32_bf16 v[78:81], v[154:157], v[210:213], v[78:81]
	v_mfma_f32_16x16x32_bf16 v[74:77], v[162:165], v[210:213], v[74:77]
	v_mfma_f32_16x16x32_bf16 v[126:129], v[158:161], v[190:193], v[126:129]
	v_mfma_f32_16x16x32_bf16 v[122:125], v[166:169], v[190:193], v[122:125]
	v_mfma_f32_16x16x32_bf16 v[110:113], v[158:161], v[198:201], v[110:113]
	v_mfma_f32_16x16x32_bf16 v[106:109], v[166:169], v[198:201], v[106:109]
	v_mfma_f32_16x16x32_bf16 v[94:97], v[158:161], v[206:209], v[94:97]
	v_mfma_f32_16x16x32_bf16 v[90:93], v[166:169], v[206:209], v[90:93]
	v_mfma_f32_16x16x32_bf16 v[78:81], v[158:161], v[214:217], v[78:81]
	v_mfma_f32_16x16x32_bf16 v[74:77], v[166:169], v[214:217], v[74:77]
	v_mfma_f32_16x16x32_bf16 v[118:121], v[170:173], v[186:189], v[118:121]
	v_mfma_f32_16x16x32_bf16 v[114:117], v[178:181], v[186:189], v[114:117]
	v_mfma_f32_16x16x32_bf16 v[102:105], v[170:173], v[194:197], v[102:105]
	v_mfma_f32_16x16x32_bf16 v[98:101], v[178:181], v[194:197], v[98:101]
	v_mfma_f32_16x16x32_bf16 v[86:89], v[170:173], v[202:205], v[86:89]
	v_mfma_f32_16x16x32_bf16 v[82:85], v[178:181], v[202:205], v[82:85]
	v_mfma_f32_16x16x32_bf16 v[70:73], v[170:173], v[210:213], v[70:73]
	v_mfma_f32_16x16x32_bf16 v[66:69], v[178:181], v[210:213], v[66:69]
	v_mfma_f32_16x16x32_bf16 v[118:121], v[174:177], v[190:193], v[118:121]
	v_mfma_f32_16x16x32_bf16 v[114:117], v[182:185], v[190:193], v[114:117]
	v_mfma_f32_16x16x32_bf16 v[102:105], v[174:177], v[198:201], v[102:105]
	v_mfma_f32_16x16x32_bf16 v[98:101], v[182:185], v[198:201], v[98:101]
	v_mfma_f32_16x16x32_bf16 v[86:89], v[174:177], v[206:209], v[86:89]
	v_mfma_f32_16x16x32_bf16 v[82:85], v[182:185], v[206:209], v[82:85]
	v_mfma_f32_16x16x32_bf16 v[70:73], v[174:177], v[214:217], v[70:73]
	v_mfma_f32_16x16x32_bf16 v[66:69], v[182:185], v[214:217], v[66:69]
	s_setprio 0
	s_barrier
; #define PG8_STAGE(bufoff, gbase, voff) do { _Pragma("unroll") for (int _i = 0; _i < 2; ++_i) \
;         __builtin_amdgcn_global_load_lds((const unsigned*)((const char*)(gbase) + (voff)[_i]), (PG8_LAS unsigned*)(lds + (bufoff) + ldsw + _i * 8192), 16, 0, 0); } while (0)
; #define PG8_LDA(dst, b, h) do { _Pragma("unroll") for (int m = 0; m < 4; ++m) _Pragma("unroll") for (int k = 0; k < 2; ++k) dst[m][k] = *(const PG8_LAS bf16x8*)(lds + PG8_SA(b, h) + aoff + m * 2048 + k * 1024); } while (0)
; #define PG8_LDB(dst, b, h) do { _Pragma("unroll") for (int n = 0; n < 2; ++n) _Pragma("unroll") for (int k = 0; k < 2; ++k) dst[n][k] = *(const PG8_LAS bf16x8*)(lds + PG8_SB(b, h) + boff + n * 2048 + k * 1024); } while (0)
; #define PG8_MMA(ai, bj, At, Bt) do { __builtin_amdgcn_s_setprio(1); _Pragma("unroll") for (int m = 0; m < 4; ++m) _Pragma("unroll") for (int n = 0; n < 2; ++n) _Pragma("unroll") for (int k = 0; k < 2; ++k) \
;         acc[ai][bj][m][n] = __builtin_amdgcn_mfma_f32_16x16x32_bf16(Bt[n][k], At[m][k], acc[ai][bj][m][n], 0, 0, 0); __builtin_amdgcn_s_setprio(0); } while (0)
; #define PG8_WAIT_V(n) asm volatile("s_waitcnt vmcnt(" #n ")" ::: "memory")
; #define PG8_WAIT_L(n) asm volatile("s_waitcnt lgkmcnt(" #n ")" ::: "memory")
; #define PG8_BAR __builtin_amdgcn_s_barrier()
; #define PG8_SCHED __builtin_amdgcn_sched_barrier(0)
; template <class Epi, class Sched, bool ALIGN_EPI = false, bool SP2 = false>
; __device__ __forceinline__ void gemm_phase(PG8_LAS unsigned char* lds, const Gemm g, const Sched& S, const Epi& E) {
;     ...
;             PG8_LDA(At, 0, 1); PG8_STAGE(PG8_SB(0, 0), b2, voffB); PG8_STAGE(PG8_SB(0, 1), b2 + hstep, voffB); PG8_STAGE(PG8_SA(0, 0), a2, voffA);
;             PG8_WAIT_V(8); PG8_WAIT_L(0); PG8_BAR; PG8_MMA(1, 0, At, B0); PG8_MMA(1, 1, At, B1); PG8_BAR; PG8_SCHED;
;             PG8_LDB(B0, 1, 0); PG8_LDB(B1, 1, 1); PG8_SCHED; PG8_LDA(At, 1, 0); PG8_STAGE(PG8_SA(0, 1), a2 + hstep, voffA);
;             PG8_WAIT_V(8); PG8_WAIT_L(0); PG8_BAR; PG8_MMA(0, 0, At, B0); PG8_MMA(0, 1, At, B1); PG8_BAR; PG8_SCHED;
	s_add_i32 s55, s47, s34
	v_lshl_add_u64 v[218:219], s[24:25], 0, v[134:135]
	s_mov_b32 m0, s55
	ds_read_b128 v[186:189], v152 offset:16384
	ds_read_b128 v[190:193], v152 offset:17408
	ds_read_b128 v[194:197], v152 offset:18432
	ds_read_b128 v[198:201], v152 offset:19456
	ds_read_b128 v[202:205], v152 offset:20480
	ds_read_b128 v[206:209], v152 offset:21504
	ds_read_b128 v[210:213], v152 offset:22528
	ds_read_b128 v[214:217], v152 offset:23552
	global_load_lds_dwordx4 v[218:219], off
	s_add_i32 m0, s55, 0x2000
	s_add_u32 s56, s24, 0x40000
	v_lshl_add_u64 v[222:223], s[24:25], 0, v[130:131]
	s_addc_u32 s57, s25, 0
	s_add_i32 s55, s48, s34
	global_load_lds_dwordx4 v[222:223], off
	v_lshl_add_u64 v[224:225], s[56:57], 0, v[134:135]
	s_mov_b32 m0, s55
	v_lshl_add_u64 v[226:227], s[26:27], 0, v[132:133]
	global_load_lds_dwordx4 v[224:225], off
	v_lshl_add_u64 v[224:225], s[56:57], 0, v[130:131]
	s_add_i32 m0, s55, 0x2000
	s_nop 0
	global_load_lds_dwordx4 v[224:225], off
	v_lshl_add_u64 v[224:225], s[26:27], 0, v[136:137]
	s_mov_b32 m0, s37
	s_nop 0
	global_load_lds_dwordx4 v[224:225], off
	s_mov_b32 m0, s38
	s_nop 0
	global_load_lds_dwordx4 v[226:227], off
	s_waitcnt vmcnt(8)
	s_waitcnt lgkmcnt(0)
	s_barrier
	s_setprio 1
	v_mfma_f32_16x16x32_bf16 v[62:65], v[154:157], v[186:189], v[62:65]
	v_mfma_f32_16x16x32_bf16 v[58:61], v[162:165], v[186:189], v[58:61]
	v_mfma_f32_16x16x32_bf16 v[46:49], v[154:157], v[194:197], v[46:49]
	v_mfma_f32_16x16x32_bf16 v[42:45], v[162:165], v[194:197], v[42:45]
	v_mfma_f32_16x16x32_bf16 v[30:33], v[154:157], v[202:205], v[30:33]
	v_mfma_f32_16x16x32_bf16 v[26:29], v[162:165], v[202:205], v[26:29]
	v_mfma_f32_16x16x32_bf16 v[14:17], v[154:157], v[210:213], v[14:17]
	v_mfma_f32_16x16x32_bf16 v[10:13], v[162:165], v[210:213], v[10:13]
	v_mfma_f32_16x16x32_bf16 v[62:65], v[158:161], v[190:193], v[62:65]
	v_mfma_f32_16x16x32_bf16 v[58:61], v[166:169], v[190:193], v[58:61]
	v_mfma_f32_16x16x32_bf16 v[46:49], v[158:161], v[198:201], v[46:49]
	v_mfma_f32_16x16x32_bf16 v[42:45], v[166:169], v[198:201], v[42:45]
	v_mfma_f32_16x16x32_bf16 v[30:33], v[158:161], v[206:209], v[30:33]
	v_mfma_f32_16x16x32_bf16 v[26:29], v[166:169], v[206:209], v[26:29]
	v_mfma_f32_16x16x32_bf16 v[14:17], v[158:161], v[214:217], v[14:17]
	v_mfma_f32_16x16x32_bf16 v[10:13], v[166:169], v[214:217], v[10:13]
	v_mfma_f32_16x16x32_bf16 v[54:57], v[170:173], v[186:189], v[54:57]
	v_mfma_f32_16x16x32_bf16 v[50:53], v[178:181], v[186:189], v[50:53]
	v_mfma_f32_16x16x32_bf16 v[38:41], v[170:173], v[194:197], v[38:41]
	v_mfma_f32_16x16x32_bf16 v[34:37], v[178:181], v[194:197], v[34:37]
	v_mfma_f32_16x16x32_bf16 v[22:25], v[170:173], v[202:205], v[22:25]
	v_mfma_f32_16x16x32_bf16 v[18:21], v[178:181], v[202:205], v[18:21]
	v_mfma_f32_16x16x32_bf16 v[6:9], v[170:173], v[210:213], v[6:9]
	v_mfma_f32_16x16x32_bf16 v[2:5], v[178:181], v[210:213], v[2:5]
	v_mfma_f32_16x16x32_bf16 v[54:57], v[174:177], v[190:193], v[54:57]
	v_mfma_f32_16x16x32_bf16 v[50:53], v[182:185], v[190:193], v[50:53]
	v_mfma_f32_16x16x32_bf16 v[38:41], v[174:177], v[198:201], v[38:41]
	v_mfma_f32_16x16x32_bf16 v[34:37], v[182:185], v[198:201], v[34:37]
	v_mfma_f32_16x16x32_bf16 v[22:25], v[174:177], v[206:209], v[22:25]
	v_mfma_f32_16x16x32_bf16 v[18:21], v[182:185], v[206:209], v[18:21]
	v_mfma_f32_16x16x32_bf16 v[6:9], v[174:177], v[214:217], v[6:9]
	v_mfma_f32_16x16x32_bf16 v[2:5], v[182:185], v[214:217], v[2:5]
	s_setprio 0
	s_barrier
.Lpz1_mid:
	s_add_i32 s55, 0, 0x18000
	v_add_u32_e32 v138, s55, v149
	s_add_i32 s56, 0, 0x1c000
	ds_read_b128 v[154:157], v138
	ds_read_b128 v[158:161], v138 offset:1024
	ds_read_b128 v[162:165], v138 offset:2048
	ds_read_b128 v[166:169], v138 offset:3072
	v_add_u32_e32 v138, s56, v149
	ds_read_b128 v[170:173], v138
	ds_read_b128 v[174:177], v138 offset:1024
	ds_read_b128 v[178:181], v138 offset:2048
	ds_read_b128 v[182:185], v138 offset:3072
	s_add_u32 s26, s26, 0x40000
	s_addc_u32 s27, s27, 0
	s_mov_b32 m0, s39
	v_lshl_add_u64 v[228:229], s[26:27], 0, v[136:137]
	ds_read_b128 v[186:189], v152 offset:32768
	ds_read_b128 v[190:193], v152 offset:33792
	ds_read_b128 v[194:197], v152 offset:34816
	ds_read_b128 v[198:201], v152 offset:35840
	ds_read_b128 v[202:205], v152 offset:36864
	ds_read_b128 v[206:209], v152 offset:37888
	ds_read_b128 v[210:213], v152 offset:38912
	ds_read_b128 v[214:217], v152 offset:39936
	global_load_lds_dwordx4 v[228:229], off
	v_lshl_add_u64 v[228:229], s[26:27], 0, v[132:133]
	s_mov_b32 m0, s40
	s_nop 0
	global_load_lds_dwordx4 v[228:229], off
	s_waitcnt vmcnt(8)
	s_waitcnt lgkmcnt(0)
	s_barrier
; #define PG8_STAGE(bufoff, gbase, voff) do { _Pragma("unroll") for (int _i = 0; _i < 2; ++_i) \
;         __builtin_amdgcn_global_load_lds((const unsigned*)((const char*)(gbase) + (voff)[_i]), (PG8_LAS unsigned*)(lds + (bufoff) + ldsw + _i * 8192), 16, 0, 0); } while (0)
; #define PG8_WAIT_V(n) asm volatile("s_waitcnt vmcnt(" #n ")" ::: "memory")
; #define PG8_WAIT_L(n) asm volatile("s_waitcnt lgkmcnt(" #n ")" ::: "memory")
; template <class Epi, class Sched, bool ALIGN_EPI = false, bool SP2 = false>
; __device__ __forceinline__ void gemm_phase(PG8_LAS unsigned char* lds, const Gemm g, const Sched& S, const Epi& E) {
;     ...
;             PG8_WAIT_V(8); PG8_WAIT_L(0); PG8_BAR; PG8_MMA(0, 0, At, B0); PG8_MMA(0, 1, At, B1); PG8_BAR; PG8_SCHED;
;             PG8_LDA(At, 1, 1); PG8_STAGE(PG8_SB(1, 0), b3, voffB); PG8_STAGE(PG8_SB(1, 1), b3 + hstep, voffB); PG8_STAGE(PG8_SA(1, 0), a3, voffA);
;             PG8_WAIT_V(8); PG8_WAIT_L(0); PG8_BAR; PG8_MMA(1, 0, At, B0); PG8_MMA(1, 1, At, B1); PG8_BAR; PG8_SCHED;
;             } else {
;             PG8_LDB(B0, 0, 0); PG8_SCHED; PG8_LDA(At, 0, 0); PG8_STAGE(PG8_SA(1, 1), a1 + hstep, voffA);
;             PG8_WAIT_L(8); PG8_BAR; PG8_WAIT_L(0); PG8_MMA(0, 0, At, B0); PG8_BAR; PG8_SCHED;
;             PG8_LDB(B1, 0, 1); PG8_STAGE(PG8_SB(0, 0), b2, voffB);
;             PG8_BAR; PG8_WAIT_L(0); PG8_MMA(0, 1, At, B1); PG8_BAR;
;             PG8_LDA(At, 0, 1); PG8_STAGE(PG8_SA(0, 0), a2, voffA);
;             PG8_BAR; PG8_WAIT_L(0); PG8_MMA(1, 0, At, B0); PG8_BAR; PG8_SCHED;
;             PG8_STAGE(PG8_SB(0, 1), b2 + hstep, voffB);
;             PG8_WAIT_V(6); PG8_BAR; PG8_MMA(1, 1, At, B1); PG8_BAR;
;             PG8_LDB(B0, 1, 0); PG8_SCHED; PG8_LDA(At, 1, 0); PG8_STAGE(PG8_SA(0, 1), a2 + hstep, voffA);
;             PG8_WAIT_L(8); PG8_BAR; PG8_WAIT_L(0); PG8_MMA(0, 0, At, B0); PG8_BAR; PG8_SCHED;
;             PG8_LDB(B1, 1, 1); PG8_STAGE(PG8_SB(1, 0), b3, voffB);
;             PG8_BAR; PG8_WAIT_L(0); PG8_MMA(0, 1, At, B1); PG8_BAR;
;             PG8_LDA(At, 1, 1); PG8_STAGE(PG8_SA(1, 0), a3, voffA);
;             PG8_BAR; PG8_WAIT_L(0); PG8_MMA(1, 0, At, B0); PG8_BAR; PG8_SCHED;
;             PG8_STAGE(PG8_SB(1, 1), b3 + hstep, voffB);
;             PG8_WAIT_V(6); PG8_BAR; PG8_MMA(1, 1, At, B1); PG8_BAR;
;             }
;         }
;         if constexpr (ALIGN_EPI) { if (wr == 0) PG8_BAR; }
	s_setprio 1
	v_mfma_f32_16x16x32_bf16 v[126:129], v[154:157], v[186:189], v[126:129]
	v_mfma_f32_16x16x32_bf16 v[122:125], v[162:165], v[186:189], v[122:125]
	v_mfma_f32_16x16x32_bf16 v[110:113], v[154:157], v[194:197], v[110:113]
	v_mfma_f32_16x16x32_bf16 v[106:109], v[162:165], v[194:197], v[106:109]
	v_mfma_f32_16x16x32_bf16 v[94:97], v[154:157], v[202:205], v[94:97]
	v_mfma_f32_16x16x32_bf16 v[90:93], v[162:165], v[202:205], v[90:93]
	v_mfma_f32_16x16x32_bf16 v[78:81], v[154:157], v[210:213], v[78:81]
	v_mfma_f32_16x16x32_bf16 v[74:77], v[162:165], v[210:213], v[74:77]
	v_mfma_f32_16x16x32_bf16 v[126:129], v[158:161], v[190:193], v[126:129]
	v_mfma_f32_16x16x32_bf16 v[122:125], v[166:169], v[190:193], v[122:125]
	v_mfma_f32_16x16x32_bf16 v[110:113], v[158:161], v[198:201], v[110:113]
	v_mfma_f32_16x16x32_bf16 v[106:109], v[166:169], v[198:201], v[106:109]
	v_mfma_f32_16x16x32_bf16 v[94:97], v[158:161], v[206:209], v[94:97]
	v_mfma_f32_16x16x32_bf16 v[90:93], v[166:169], v[206:209], v[90:93]
	v_mfma_f32_16x16x32_bf16 v[78:81], v[158:161], v[214:217], v[78:81]
	v_mfma_f32_16x16x32_bf16 v[74:77], v[166:169], v[214:217], v[74:77]
	v_mfma_f32_16x16x32_bf16 v[118:121], v[170:173], v[186:189], v[118:121]
	v_mfma_f32_16x16x32_bf16 v[114:117], v[178:181], v[186:189], v[114:117]
	v_mfma_f32_16x16x32_bf16 v[102:105], v[170:173], v[194:197], v[102:105]
	v_mfma_f32_16x16x32_bf16 v[98:101], v[178:181], v[194:197], v[98:101]
	v_mfma_f32_16x16x32_bf16 v[86:89], v[170:173], v[202:205], v[86:89]
	v_mfma_f32_16x16x32_bf16 v[82:85], v[178:181], v[202:205], v[82:85]
	v_mfma_f32_16x16x32_bf16 v[70:73], v[170:173], v[210:213], v[70:73]
	v_mfma_f32_16x16x32_bf16 v[66:69], v[178:181], v[210:213], v[66:69]
	v_mfma_f32_16x16x32_bf16 v[118:121], v[174:177], v[190:193], v[118:121]
	v_mfma_f32_16x16x32_bf16 v[114:117], v[182:185], v[190:193], v[114:117]
	v_mfma_f32_16x16x32_bf16 v[102:105], v[174:177], v[198:201], v[102:105]
	v_mfma_f32_16x16x32_bf16 v[98:101], v[182:185], v[198:201], v[98:101]
	v_mfma_f32_16x16x32_bf16 v[86:89], v[174:177], v[206:209], v[86:89]
	v_mfma_f32_16x16x32_bf16 v[82:85], v[182:185], v[206:209], v[82:85]
	v_mfma_f32_16x16x32_bf16 v[70:73], v[174:177], v[214:217], v[70:73]
	v_mfma_f32_16x16x32_bf16 v[66:69], v[182:185], v[214:217], v[66:69]
	s_setprio 0
	s_barrier
	s_add_i32 s26, s55, s34
	v_lshl_add_u64 v[218:219], v[218:219], 0, s[8:9]
	s_mov_b32 m0, s26
	ds_read_b128 v[186:189], v152 offset:49152
	ds_read_b128 v[190:193], v152 offset:50176
	ds_read_b128 v[194:197], v152 offset:51200
	ds_read_b128 v[198:201], v152 offset:52224
	ds_read_b128 v[202:205], v152 offset:53248
	ds_read_b128 v[206:209], v152 offset:54272
	ds_read_b128 v[210:213], v152 offset:55296
	ds_read_b128 v[214:217], v152 offset:56320
	global_load_lds_dwordx4 v[218:219], off
	s_add_i32 m0, s26, 0x2000
	s_add_u32 s24, s24, 0x40080
	v_lshl_add_u64 v[218:219], v[222:223], 0, s[8:9]
	s_addc_u32 s25, s25, 0
	s_add_i32 s26, s56, s34
	global_load_lds_dwordx4 v[218:219], off
	v_lshl_add_u64 v[218:219], s[24:25], 0, v[134:135]
	s_mov_b32 m0, s26
	s_nop 0
	global_load_lds_dwordx4 v[218:219], off
	v_lshl_add_u64 v[218:219], s[24:25], 0, v[130:131]
	s_add_i32 m0, s26, 0x2000
	s_nop 0
	global_load_lds_dwordx4 v[218:219], off
	v_lshl_add_u64 v[218:219], v[224:225], 0, s[8:9]
	s_mov_b32 m0, s42
	s_nop 0
	global_load_lds_dwordx4 v[218:219], off
	v_lshl_add_u64 v[218:219], v[226:227], 0, s[8:9]
	s_mov_b32 m0, s43
	s_nop 0
	global_load_lds_dwordx4 v[218:219], off
	s_waitcnt vmcnt(8)
	s_waitcnt lgkmcnt(0)
	s_barrier
	s_setprio 1
	v_mfma_f32_16x16x32_bf16 v[62:65], v[154:157], v[186:189], v[62:65]
	v_mfma_f32_16x16x32_bf16 v[58:61], v[162:165], v[186:189], v[58:61]
	v_mfma_f32_16x16x32_bf16 v[46:49], v[154:157], v[194:197], v[46:49]
	v_mfma_f32_16x16x32_bf16 v[42:45], v[162:165], v[194:197], v[42:45]
	v_mfma_f32_16x16x32_bf16 v[30:33], v[154:157], v[202:205], v[30:33]
	v_mfma_f32_16x16x32_bf16 v[26:29], v[162:165], v[202:205], v[26:29]
	v_mfma_f32_16x16x32_bf16 v[14:17], v[154:157], v[210:213], v[14:17]
	v_mfma_f32_16x16x32_bf16 v[10:13], v[162:165], v[210:213], v[10:13]
	v_mfma_f32_16x16x32_bf16 v[62:65], v[158:161], v[190:193], v[62:65]
	v_mfma_f32_16x16x32_bf16 v[58:61], v[166:169], v[190:193], v[58:61]
	v_mfma_f32_16x16x32_bf16 v[46:49], v[158:161], v[198:201], v[46:49]
	v_mfma_f32_16x16x32_bf16 v[42:45], v[166:169], v[198:201], v[42:45]
	v_mfma_f32_16x16x32_bf16 v[30:33], v[158:161], v[206:209], v[30:33]
	v_mfma_f32_16x16x32_bf16 v[26:29], v[166:169], v[206:209], v[26:29]
	v_mfma_f32_16x16x32_bf16 v[14:17], v[158:161], v[214:217], v[14:17]
	v_mfma_f32_16x16x32_bf16 v[10:13], v[166:169], v[214:217], v[10:13]
	v_mfma_f32_16x16x32_bf16 v[54:57], v[170:173], v[186:189], v[54:57]
	v_mfma_f32_16x16x32_bf16 v[50:53], v[178:181], v[186:189], v[50:53]
	v_mfma_f32_16x16x32_bf16 v[38:41], v[170:173], v[194:197], v[38:41]
	v_mfma_f32_16x16x32_bf16 v[34:37], v[178:181], v[194:197], v[34:37]
	v_mfma_f32_16x16x32_bf16 v[22:25], v[170:173], v[202:205], v[22:25]
	v_mfma_f32_16x16x32_bf16 v[18:21], v[178:181], v[202:205], v[18:21]
	v_mfma_f32_16x16x32_bf16 v[6:9], v[170:173], v[210:213], v[6:9]
	v_mfma_f32_16x16x32_bf16 v[2:5], v[178:181], v[210:213], v[2:5]
	v_mfma_f32_16x16x32_bf16 v[54:57], v[174:177], v[190:193], v[54:57]
	v_mfma_f32_16x16x32_bf16 v[50:53], v[182:185], v[190:193], v[50:53]
	v_mfma_f32_16x16x32_bf16 v[38:41], v[174:177], v[198:201], v[38:41]
	v_mfma_f32_16x16x32_bf16 v[34:37], v[182:185], v[198:201], v[34:37]
	v_mfma_f32_16x16x32_bf16 v[22:25], v[174:177], v[206:209], v[22:25]
	v_mfma_f32_16x16x32_bf16 v[18:21], v[182:185], v[206:209], v[18:21]
	v_mfma_f32_16x16x32_bf16 v[6:9], v[174:177], v[214:217], v[6:9]
	v_mfma_f32_16x16x32_bf16 v[2:5], v[182:185], v[214:217], v[2:5]
	s_setprio 0
	s_barrier
	s_add_i32 s54, s54, 2
	s_add_u32 s22, s22, 0x100
	s_addc_u32 s23, s23, 0
	s_add_u32 s52, s52, 0x100
	s_addc_u32 s53, s53, 0
	s_cmp_gt_u32 s54, 13
	s_cbranch_scc0 .LBB0_208
	s_and_b64 vcc, exec, s[10:11]
	s_cbranch_vccz .LBB0_211
	s_barrier

; #define PG8_STAGE(bufoff, gbase, voff) do { _Pragma("unroll") for (int _i = 0; _i < 2; ++_i) \
;         __builtin_amdgcn_global_load_lds((const unsigned*)((const char*)(gbase) + (voff)[_i]), (PG8_LAS unsigned*)(lds + (bufoff) + ldsw + _i * 8192), 16, 0, 0); } while (0)
; #define PG8_LDA(dst, b, h) do { _Pragma("unroll") for (int m = 0; m < 4; ++m) _Pragma("unroll") for (int k = 0; k < 2; ++k) dst[m][k] = *(const PG8_LAS bf16x8*)(lds + PG8_SA(b, h) + aoff + m * 2048 + k * 1024); } while (0)
; #define PG8_LDB(dst, b, h) do { _Pragma("unroll") for (int n = 0; n < 2; ++n) _Pragma("unroll") for (int k = 0; k < 2; ++k) dst[n][k] = *(const PG8_LAS bf16x8*)(lds + PG8_SB(b, h) + boff + n * 2048 + k * 1024); } while (0)
; #define PG8_MMA(ai, bj, At, Bt) do { __builtin_amdgcn_s_setprio(1); _Pragma("unroll") for (int m = 0; m < 4; ++m) _Pragma("unroll") for (int n = 0; n < 2; ++n) _Pragma("unroll") for (int k = 0; k < 2; ++k) \
;         acc[ai][bj][m][n] = __builtin_amdgcn_mfma_f32_16x16x32_bf16(Bt[n][k], At[m][k], acc[ai][bj][m][n], 0, 0, 0); __builtin_amdgcn_s_setprio(0); } while (0)
; #define PG8_WAIT_V(n) asm volatile("s_waitcnt vmcnt(" #n ")" ::: "memory")
; #define PG8_BAR __builtin_amdgcn_s_barrier()
; template <class Epi, class Sched, bool ALIGN_EPI = false, bool SP2 = false>
; __device__ __forceinline__ void gemm_phase(PG8_LAS unsigned char* lds, const Gemm g, const Sched& S, const Epi& E) {
;     ...
;             const char* a1 = cA + (size_t)(t + 1) * kstepA;
;             const char* a2 = last ? nA : cA + (size_t)(t + 2) * kstepA; const char* b2 = last ? nB : cB + (size_t)(t + 2) * kstep;
;             const char* a3 = a2 + kstepA; const char* b3 = b2 + kstep;
;             if (last && has_next) S.a_ready(nxt);
;             if constexpr (SP2) {
;             PG8_LDB(B0, 0, 0); PG8_LDB(B1, 0, 1); PG8_SCHED; PG8_LDA(At, 0, 0); PG8_STAGE(PG8_SA(1, 1), a1 + hstep, voffA);
;             PG8_WAIT_V(8); PG8_WAIT_L(0); PG8_BAR; PG8_MMA(0, 0, At, B0); PG8_MMA(0, 1, At, B1); PG8_BAR; PG8_SCHED;
;             if constexpr (Epi::PREFETCH) { if (t == tpf) E.prefetch(cur, wid, lane); }
;             PG8_LDA(At, 0, 1); PG8_STAGE(PG8_SB(0, 0), b2, voffB); PG8_STAGE(PG8_SB(0, 1), b2 + hstep, voffB); PG8_STAGE(PG8_SA(0, 0), a2, voffA);
;             PG8_WAIT_V(8); PG8_WAIT_L(0); PG8_BAR; PG8_MMA(1, 0, At, B0); PG8_MMA(1, 1, At, B1); PG8_BAR; PG8_SCHED;
.LBB0_288:
	s_add_u32 s39, s6, 0x100
	s_addc_u32 s40, s7, 0
	s_mov_b32 s41, -2
	ds_read_b128 v[130:133], v223
	ds_read_b128 v[134:137], v223 offset:1024
	ds_read_b128 v[138:141], v223 offset:2048
	ds_read_b128 v[142:145], v223 offset:3072
	ds_read_b128 v[164:167], v224
	ds_read_b128 v[168:171], v224 offset:1024
	ds_read_b128 v[172:175], v224 offset:2048
	ds_read_b128 v[176:179], v224 offset:3072
	s_add_u32 s0, s4, 0x200
	s_addc_u32 s1, s5, 0
	s_cmp_eq_u32 s41, 40
	s_cselect_b32 s37, s31, s1
	s_cselect_b32 s36, s30, s0
	s_cselect_b32 s7, s35, s40
	s_cselect_b32 s6, s34, s39
	v_lshl_add_u64 v[160:161], s[4:5], 0, v[156:157]
	s_add_i32 m0, s51, 0xc000
	ds_read_b128 v[180:183], v225
	ds_read_b128 v[184:187], v225 offset:1024
	ds_read_b128 v[188:191], v225 offset:2048
	ds_read_b128 v[192:195], v225 offset:3072
	ds_read_b128 v[196:199], v225 offset:4096
	ds_read_b128 v[200:203], v225 offset:5120
	ds_read_b128 v[204:207], v225 offset:6144
	ds_read_b128 v[208:211], v225 offset:7168
	global_load_lds_dwordx4 v[160:161], off
	v_lshl_add_u64 v[160:161], s[4:5], 0, v[158:159]
	s_add_i32 m0, s51, 0xe000
	s_nop 0
	global_load_lds_dwordx4 v[160:161], off
	s_waitcnt vmcnt(8)
	s_waitcnt lgkmcnt(0)
	s_barrier
	s_setprio 1
	v_mfma_f32_16x16x32_bf16 v[126:129], v[130:133], v[180:183], 0
	v_mfma_f32_16x16x32_bf16 v[122:125], v[138:141], v[180:183], 0
	v_mfma_f32_16x16x32_bf16 v[110:113], v[130:133], v[188:191], 0
	v_mfma_f32_16x16x32_bf16 v[106:109], v[138:141], v[188:191], 0
	v_mfma_f32_16x16x32_bf16 v[94:97], v[130:133], v[196:199], 0
	v_mfma_f32_16x16x32_bf16 v[90:93], v[138:141], v[196:199], 0
	v_mfma_f32_16x16x32_bf16 v[78:81], v[130:133], v[204:207], 0
	v_mfma_f32_16x16x32_bf16 v[74:77], v[138:141], v[204:207], 0
	v_mfma_f32_16x16x32_bf16 v[126:129], v[134:137], v[184:187], v[126:129]
	v_mfma_f32_16x16x32_bf16 v[122:125], v[142:145], v[184:187], v[122:125]
	v_mfma_f32_16x16x32_bf16 v[110:113], v[134:137], v[192:195], v[110:113]
	v_mfma_f32_16x16x32_bf16 v[106:109], v[142:145], v[192:195], v[106:109]
	v_mfma_f32_16x16x32_bf16 v[94:97], v[134:137], v[200:203], v[94:97]
	v_mfma_f32_16x16x32_bf16 v[90:93], v[142:145], v[200:203], v[90:93]
	v_mfma_f32_16x16x32_bf16 v[78:81], v[134:137], v[208:211], v[78:81]
	v_mfma_f32_16x16x32_bf16 v[74:77], v[142:145], v[208:211], v[74:77]
	v_mfma_f32_16x16x32_bf16 v[118:121], v[164:167], v[180:183], 0
	v_mfma_f32_16x16x32_bf16 v[114:117], v[172:175], v[180:183], 0
	v_mfma_f32_16x16x32_bf16 v[102:105], v[164:167], v[188:191], 0
	v_mfma_f32_16x16x32_bf16 v[98:101], v[172:175], v[188:191], 0
	v_mfma_f32_16x16x32_bf16 v[86:89], v[164:167], v[196:199], 0
	v_mfma_f32_16x16x32_bf16 v[82:85], v[172:175], v[196:199], 0
	v_mfma_f32_16x16x32_bf16 v[70:73], v[164:167], v[204:207], 0
	v_mfma_f32_16x16x32_bf16 v[66:69], v[172:175], v[204:207], 0
	v_mfma_f32_16x16x32_bf16 v[118:121], v[168:171], v[184:187], v[118:121]
	v_mfma_f32_16x16x32_bf16 v[114:117], v[176:179], v[184:187], v[114:117]
	v_mfma_f32_16x16x32_bf16 v[102:105], v[168:171], v[192:195], v[102:105]
	v_mfma_f32_16x16x32_bf16 v[98:101], v[176:179], v[192:195], v[98:101]
	v_mfma_f32_16x16x32_bf16 v[86:89], v[168:171], v[200:203], v[86:89]
	v_mfma_f32_16x16x32_bf16 v[82:85], v[176:179], v[200:203], v[82:85]
	v_mfma_f32_16x16x32_bf16 v[70:73], v[168:171], v[208:211], v[70:73]
	v_mfma_f32_16x16x32_bf16 v[66:69], v[176:179], v[208:211], v[66:69]
	s_setprio 0
	s_barrier
	s_add_i32 s4, s68, s50
	v_lshl_add_u64 v[160:161], s[6:7], 0, v[148:149]
	s_mov_b32 m0, s4
	ds_read_b128 v[180:183], v225 offset:16384
	ds_read_b128 v[184:187], v225 offset:17408
	ds_read_b128 v[188:191], v225 offset:18432
	ds_read_b128 v[192:195], v225 offset:19456
	ds_read_b128 v[196:199], v225 offset:20480
	ds_read_b128 v[200:203], v225 offset:21504
	ds_read_b128 v[204:207], v225 offset:22528
	ds_read_b128 v[208:211], v225 offset:23552
	global_load_lds_dwordx4 v[160:161], off
	s_add_i32 m0, s4, 0x2000
	s_add_u32 s4, s6, 0xb0000
	v_lshl_add_u64 v[162:163], s[6:7], 0, v[152:153]
	s_addc_u32 s5, s7, 0
	s_add_i32 s42, s69, s50
	global_load_lds_dwordx4 v[162:163], off
	v_lshl_add_u64 v[212:213], s[4:5], 0, v[148:149]
	s_mov_b32 m0, s42
	v_lshl_add_u64 v[214:215], s[36:37], 0, v[150:151]
	global_load_lds_dwordx4 v[212:213], off
	v_lshl_add_u64 v[212:213], s[4:5], 0, v[152:153]
	s_add_i32 m0, s42, 0x2000
	s_nop 0
	global_load_lds_dwordx4 v[212:213], off
	v_lshl_add_u64 v[212:213], s[36:37], 0, v[146:147]
	s_mov_b32 m0, s51
	s_nop 0
	global_load_lds_dwordx4 v[212:213], off
	s_mov_b32 m0, s52
	s_nop 0
	global_load_lds_dwordx4 v[214:215], off
	s_waitcnt vmcnt(8)
	s_waitcnt lgkmcnt(0)
	s_barrier
	s_setprio 1
	v_mfma_f32_16x16x32_bf16 v[62:65], v[130:133], v[180:183], 0
	v_mfma_f32_16x16x32_bf16 v[58:61], v[138:141], v[180:183], 0
	v_mfma_f32_16x16x32_bf16 v[46:49], v[130:133], v[188:191], 0
	v_mfma_f32_16x16x32_bf16 v[42:45], v[138:141], v[188:191], 0
	v_mfma_f32_16x16x32_bf16 v[30:33], v[130:133], v[196:199], 0
	v_mfma_f32_16x16x32_bf16 v[26:29], v[138:141], v[196:199], 0
	v_mfma_f32_16x16x32_bf16 v[14:17], v[130:133], v[204:207], 0
	v_mfma_f32_16x16x32_bf16 v[10:13], v[138:141], v[204:207], 0
	v_mfma_f32_16x16x32_bf16 v[62:65], v[134:137], v[184:187], v[62:65]
	v_mfma_f32_16x16x32_bf16 v[58:61], v[142:145], v[184:187], v[58:61]
	v_mfma_f32_16x16x32_bf16 v[46:49], v[134:137], v[192:195], v[46:49]
	v_mfma_f32_16x16x32_bf16 v[42:45], v[142:145], v[192:195], v[42:45]
	v_mfma_f32_16x16x32_bf16 v[30:33], v[134:137], v[200:203], v[30:33]
	v_mfma_f32_16x16x32_bf16 v[26:29], v[142:145], v[200:203], v[26:29]
	v_mfma_f32_16x16x32_bf16 v[14:17], v[134:137], v[208:211], v[14:17]
	v_mfma_f32_16x16x32_bf16 v[10:13], v[142:145], v[208:211], v[10:13]
	v_mfma_f32_16x16x32_bf16 v[54:57], v[164:167], v[180:183], 0
	v_mfma_f32_16x16x32_bf16 v[50:53], v[172:175], v[180:183], 0
	v_mfma_f32_16x16x32_bf16 v[38:41], v[164:167], v[188:191], 0
	v_mfma_f32_16x16x32_bf16 v[34:37], v[172:175], v[188:191], 0
	v_mfma_f32_16x16x32_bf16 v[22:25], v[164:167], v[196:199], 0
	v_mfma_f32_16x16x32_bf16 v[18:21], v[172:175], v[196:199], 0
	v_mfma_f32_16x16x32_bf16 v[6:9], v[164:167], v[204:207], 0
	v_mfma_f32_16x16x32_bf16 v[2:5], v[172:175], v[204:207], 0
	v_mfma_f32_16x16x32_bf16 v[54:57], v[168:171], v[184:187], v[54:57]
	v_mfma_f32_16x16x32_bf16 v[50:53], v[176:179], v[184:187], v[50:53]
	v_mfma_f32_16x16x32_bf16 v[38:41], v[168:171], v[192:195], v[38:41]
	v_mfma_f32_16x16x32_bf16 v[34:37], v[176:179], v[192:195], v[34:37]
	v_mfma_f32_16x16x32_bf16 v[22:25], v[168:171], v[200:203], v[22:25]
	v_mfma_f32_16x16x32_bf16 v[18:21], v[176:179], v[200:203], v[18:21]
	v_mfma_f32_16x16x32_bf16 v[6:9], v[168:171], v[208:211], v[6:9]
	v_mfma_f32_16x16x32_bf16 v[2:5], v[176:179], v[208:211], v[2:5]
	s_setprio 0
	s_barrier
	s_branch .Lpz2_mid
; #define PG8_STAGE(bufoff, gbase, voff) do { _Pragma("unroll") for (int _i = 0; _i < 2; ++_i) \
;         __builtin_amdgcn_global_load_lds((const unsigned*)((const char*)(gbase) + (voff)[_i]), (PG8_LAS unsigned*)(lds + (bufoff) + ldsw + _i * 8192), 16, 0, 0); } while (0)
; #define PG8_LDA(dst, b, h) do { _Pragma("unroll") for (int m = 0; m < 4; ++m) _Pragma("unroll") for (int k = 0; k < 2; ++k) dst[m][k] = *(const PG8_LAS bf16x8*)(lds + PG8_SA(b, h) + aoff + m * 2048 + k * 1024); } while (0)
; #define PG8_LDB(dst, b, h) do { _Pragma("unroll") for (int n = 0; n < 2; ++n) _Pragma("unroll") for (int k = 0; k < 2; ++k) dst[n][k] = *(const PG8_LAS bf16x8*)(lds + PG8_SB(b, h) + boff + n * 2048 + k * 1024); } while (0)
; #define PG8_MMA(ai, bj, At, Bt) do { __builtin_amdgcn_s_setprio(1); _Pragma("unroll") for (int m = 0; m < 4; ++m) _Pragma("unroll") for (int n = 0; n < 2; ++n) _Pragma("unroll") for (int k = 0; k < 2; ++k) \
;         acc[ai][bj][m][n] = __builtin_amdgcn_mfma_f32_16x16x32_bf16(Bt[n][k], At[m][k], acc[ai][bj][m][n], 0, 0, 0); __builtin_amdgcn_s_setprio(0); } while (0)
; #define PG8_WAIT_V(n) asm volatile("s_waitcnt vmcnt(" #n ")" ::: "memory")
; #define PG8_WAIT_L(n) asm volatile("s_waitcnt lgkmcnt(" #n ")" ::: "memory")
; #define PG8_BAR __builtin_amdgcn_s_barrier()
; #define PG8_SCHED __builtin_amdgcn_sched_barrier(0)
;     __device__ __forceinline__ void prefetch(const Unit& u, int wid, int lane) const { epi_prefetch(scr, ssq, bias + (size_t)(u.pm >> 5) * NGU + u.pn * BM, u, wid, lane); }
; template <class Epi, class Sched, bool ALIGN_EPI = false, bool SP2 = false>
; __device__ __forceinline__ void gemm_phase(PG8_LAS unsigned char* lds, const Gemm g, const Sched& S, const Epi& E) {
;     ...
;             PG8_LDB(B0, 0, 0); PG8_LDB(B1, 0, 1); PG8_SCHED; PG8_LDA(At, 0, 0); PG8_STAGE(PG8_SA(1, 1), a1 + hstep, voffA);
;             PG8_WAIT_V(8); PG8_WAIT_L(0); PG8_BAR; PG8_MMA(0, 0, At, B0); PG8_MMA(0, 1, At, B1); PG8_BAR; PG8_SCHED;
;             if constexpr (Epi::PREFETCH) { if (t == tpf) E.prefetch(cur, wid, lane); }
;             PG8_LDA(At, 0, 1); PG8_STAGE(PG8_SB(0, 0), b2, voffB); PG8_STAGE(PG8_SB(0, 1), b2 + hstep, voffB); PG8_STAGE(PG8_SA(0, 0), a2, voffA);
;             PG8_WAIT_V(8); PG8_WAIT_L(0); PG8_BAR; PG8_MMA(1, 0, At, B0); PG8_MMA(1, 1, At, B1); PG8_BAR; PG8_SCHED;
.LBB0_289:
	ds_read_b128 v[130:133], v223
	ds_read_b128 v[134:137], v223 offset:1024
	ds_read_b128 v[138:141], v223 offset:2048
	ds_read_b128 v[142:145], v223 offset:3072
	ds_read_b128 v[164:167], v224
	ds_read_b128 v[168:171], v224 offset:1024
	ds_read_b128 v[172:175], v224 offset:2048
	ds_read_b128 v[176:179], v224 offset:3072
	s_add_u32 s0, s4, 0x200
	s_addc_u32 s1, s5, 0
	s_cmp_eq_u32 s41, 40
	s_cselect_b32 s37, s31, s1
	s_cselect_b32 s36, s30, s0
	s_cselect_b32 s7, s35, s40
	s_cselect_b32 s6, s34, s39
	v_lshl_add_u64 v[160:161], s[4:5], 0, v[156:157]
	s_add_i32 m0, s51, 0xc000
	ds_read_b128 v[180:183], v225
	ds_read_b128 v[184:187], v225 offset:1024
	ds_read_b128 v[188:191], v225 offset:2048
	ds_read_b128 v[192:195], v225 offset:3072
	ds_read_b128 v[196:199], v225 offset:4096
	ds_read_b128 v[200:203], v225 offset:5120
	ds_read_b128 v[204:207], v225 offset:6144
	ds_read_b128 v[208:211], v225 offset:7168
	global_load_lds_dwordx4 v[160:161], off
	v_lshl_add_u64 v[160:161], s[4:5], 0, v[158:159]
	s_add_i32 m0, s51, 0xe000
	s_nop 0
	global_load_lds_dwordx4 v[160:161], off
	s_waitcnt vmcnt(8)
	s_waitcnt lgkmcnt(0)
	s_barrier
	s_setprio 1
	v_mfma_f32_16x16x32_bf16 v[126:129], v[130:133], v[180:183], v[126:129]
	v_mfma_f32_16x16x32_bf16 v[122:125], v[138:141], v[180:183], v[122:125]
	v_mfma_f32_16x16x32_bf16 v[110:113], v[130:133], v[188:191], v[110:113]
	v_mfma_f32_16x16x32_bf16 v[106:109], v[138:141], v[188:191], v[106:109]
	v_mfma_f32_16x16x32_bf16 v[94:97], v[130:133], v[196:199], v[94:97]
	v_mfma_f32_16x16x32_bf16 v[90:93], v[138:141], v[196:199], v[90:93]
	v_mfma_f32_16x16x32_bf16 v[78:81], v[130:133], v[204:207], v[78:81]
	v_mfma_f32_16x16x32_bf16 v[74:77], v[138:141], v[204:207], v[74:77]
	v_mfma_f32_16x16x32_bf16 v[126:129], v[134:137], v[184:187], v[126:129]
	v_mfma_f32_16x16x32_bf16 v[122:125], v[142:145], v[184:187], v[122:125]
	v_mfma_f32_16x16x32_bf16 v[110:113], v[134:137], v[192:195], v[110:113]
	v_mfma_f32_16x16x32_bf16 v[106:109], v[142:145], v[192:195], v[106:109]
	v_mfma_f32_16x16x32_bf16 v[94:97], v[134:137], v[200:203], v[94:97]
	v_mfma_f32_16x16x32_bf16 v[90:93], v[142:145], v[200:203], v[90:93]
	v_mfma_f32_16x16x32_bf16 v[78:81], v[134:137], v[208:211], v[78:81]
	v_mfma_f32_16x16x32_bf16 v[74:77], v[142:145], v[208:211], v[74:77]
	v_mfma_f32_16x16x32_bf16 v[118:121], v[164:167], v[180:183], v[118:121]
	v_mfma_f32_16x16x32_bf16 v[114:117], v[172:175], v[180:183], v[114:117]
	v_mfma_f32_16x16x32_bf16 v[102:105], v[164:167], v[188:191], v[102:105]
	v_mfma_f32_16x16x32_bf16 v[98:101], v[172:175], v[188:191], v[98:101]
	v_mfma_f32_16x16x32_bf16 v[86:89], v[164:167], v[196:199], v[86:89]
	v_mfma_f32_16x16x32_bf16 v[82:85], v[172:175], v[196:199], v[82:85]
	v_mfma_f32_16x16x32_bf16 v[70:73], v[164:167], v[204:207], v[70:73]
	v_mfma_f32_16x16x32_bf16 v[66:69], v[172:175], v[204:207], v[66:69]
	v_mfma_f32_16x16x32_bf16 v[118:121], v[168:171], v[184:187], v[118:121]
	v_mfma_f32_16x16x32_bf16 v[114:117], v[176:179], v[184:187], v[114:117]
	v_mfma_f32_16x16x32_bf16 v[102:105], v[168:171], v[192:195], v[102:105]
	v_mfma_f32_16x16x32_bf16 v[98:101], v[176:179], v[192:195], v[98:101]
	v_mfma_f32_16x16x32_bf16 v[86:89], v[168:171], v[200:203], v[86:89]
	v_mfma_f32_16x16x32_bf16 v[82:85], v[176:179], v[200:203], v[82:85]
	v_mfma_f32_16x16x32_bf16 v[70:73], v[168:171], v[208:211], v[70:73]
	v_mfma_f32_16x16x32_bf16 v[66:69], v[176:179], v[208:211], v[66:69]
	s_setprio 0
	s_barrier
	s_add_i32 s4, s68, s50
	v_lshl_add_u64 v[160:161], s[6:7], 0, v[148:149]
	s_mov_b32 m0, s4
	ds_read_b128 v[180:183], v225 offset:16384
	ds_read_b128 v[184:187], v225 offset:17408
	ds_read_b128 v[188:191], v225 offset:18432
	ds_read_b128 v[192:195], v225 offset:19456
	ds_read_b128 v[196:199], v225 offset:20480
	ds_read_b128 v[200:203], v225 offset:21504
	ds_read_b128 v[204:207], v225 offset:22528
	ds_read_b128 v[208:211], v225 offset:23552
	global_load_lds_dwordx4 v[160:161], off
	s_add_i32 m0, s4, 0x2000
	s_add_u32 s4, s6, 0xb0000
	v_lshl_add_u64 v[162:163], s[6:7], 0, v[152:153]
	s_addc_u32 s5, s7, 0
	s_add_i32 s42, s69, s50
	global_load_lds_dwordx4 v[162:163], off
	v_lshl_add_u64 v[212:213], s[4:5], 0, v[148:149]
	s_mov_b32 m0, s42
	v_lshl_add_u64 v[214:215], s[36:37], 0, v[150:151]
	global_load_lds_dwordx4 v[212:213], off
	v_lshl_add_u64 v[212:213], s[4:5], 0, v[152:153]
	s_add_i32 m0, s42, 0x2000
	s_nop 0
	global_load_lds_dwordx4 v[212:213], off
	v_lshl_add_u64 v[212:213], s[36:37], 0, v[146:147]
	s_mov_b32 m0, s51
	s_nop 0
	global_load_lds_dwordx4 v[212:213], off
	s_mov_b32 m0, s52
	s_nop 0
	global_load_lds_dwordx4 v[214:215], off
	s_waitcnt vmcnt(8)
	s_waitcnt lgkmcnt(0)
	s_barrier
	s_setprio 1
	v_mfma_f32_16x16x32_bf16 v[62:65], v[130:133], v[180:183], v[62:65]
	v_mfma_f32_16x16x32_bf16 v[58:61], v[138:141], v[180:183], v[58:61]
	v_mfma_f32_16x16x32_bf16 v[46:49], v[130:133], v[188:191], v[46:49]
	v_mfma_f32_16x16x32_bf16 v[42:45], v[138:141], v[188:191], v[42:45]
	v_mfma_f32_16x16x32_bf16 v[30:33], v[130:133], v[196:199], v[30:33]
	v_mfma_f32_16x16x32_bf16 v[26:29], v[138:141], v[196:199], v[26:29]
	v_mfma_f32_16x16x32_bf16 v[14:17], v[130:133], v[204:207], v[14:17]
	v_mfma_f32_16x16x32_bf16 v[10:13], v[138:141], v[204:207], v[10:13]
	v_mfma_f32_16x16x32_bf16 v[62:65], v[134:137], v[184:187], v[62:65]
	v_mfma_f32_16x16x32_bf16 v[58:61], v[142:145], v[184:187], v[58:61]
	v_mfma_f32_16x16x32_bf16 v[46:49], v[134:137], v[192:195], v[46:49]
	v_mfma_f32_16x16x32_bf16 v[42:45], v[142:145], v[192:195], v[42:45]
	v_mfma_f32_16x16x32_bf16 v[30:33], v[134:137], v[200:203], v[30:33]
	v_mfma_f32_16x16x32_bf16 v[26:29], v[142:145], v[200:203], v[26:29]
	v_mfma_f32_16x16x32_bf16 v[14:17], v[134:137], v[208:211], v[14:17]
	v_mfma_f32_16x16x32_bf16 v[10:13], v[142:145], v[208:211], v[10:13]
	v_mfma_f32_16x16x32_bf16 v[54:57], v[164:167], v[180:183], v[54:57]
	v_mfma_f32_16x16x32_bf16 v[50:53], v[172:175], v[180:183], v[50:53]
	v_mfma_f32_16x16x32_bf16 v[38:41], v[164:167], v[188:191], v[38:41]
	v_mfma_f32_16x16x32_bf16 v[34:37], v[172:175], v[188:191], v[34:37]
	v_mfma_f32_16x16x32_bf16 v[22:25], v[164:167], v[196:199], v[22:25]
	v_mfma_f32_16x16x32_bf16 v[18:21], v[172:175], v[196:199], v[18:21]
	v_mfma_f32_16x16x32_bf16 v[6:9], v[164:167], v[204:207], v[6:9]
	v_mfma_f32_16x16x32_bf16 v[2:5], v[172:175], v[204:207], v[2:5]
	v_mfma_f32_16x16x32_bf16 v[54:57], v[168:171], v[184:187], v[54:57]
	v_mfma_f32_16x16x32_bf16 v[50:53], v[176:179], v[184:187], v[50:53]
	v_mfma_f32_16x16x32_bf16 v[38:41], v[168:171], v[192:195], v[38:41]
	v_mfma_f32_16x16x32_bf16 v[34:37], v[176:179], v[192:195], v[34:37]
	v_mfma_f32_16x16x32_bf16 v[22:25], v[168:171], v[200:203], v[22:25]
	v_mfma_f32_16x16x32_bf16 v[18:21], v[176:179], v[200:203], v[18:21]
	v_mfma_f32_16x16x32_bf16 v[6:9], v[168:171], v[208:211], v[6:9]
	v_mfma_f32_16x16x32_bf16 v[2:5], v[176:179], v[208:211], v[2:5]
	s_setprio 0
	s_barrier
; #define PG8_STAGE(bufoff, gbase, voff) do { _Pragma("unroll") for (int _i = 0; _i < 2; ++_i) \
;         __builtin_amdgcn_global_load_lds((const unsigned*)((const char*)(gbase) + (voff)[_i]), (PG8_LAS unsigned*)(lds + (bufoff) + ldsw + _i * 8192), 16, 0, 0); } while (0)
; #define PG8_LDA(dst, b, h) do { _Pragma("unroll") for (int m = 0; m < 4; ++m) _Pragma("unroll") for (int k = 0; k < 2; ++k) dst[m][k] = *(const PG8_LAS bf16x8*)(lds + PG8_SA(b, h) + aoff + m * 2048 + k * 1024); } while (0)
; #define PG8_LDB(dst, b, h) do { _Pragma("unroll") for (int n = 0; n < 2; ++n) _Pragma("unroll") for (int k = 0; k < 2; ++k) dst[n][k] = *(const PG8_LAS bf16x8*)(lds + PG8_SB(b, h) + boff + n * 2048 + k * 1024); } while (0)
; #define PG8_MMA(ai, bj, At, Bt) do { __builtin_amdgcn_s_setprio(1); _Pragma("unroll") for (int m = 0; m < 4; ++m) _Pragma("unroll") for (int n = 0; n < 2; ++n) _Pragma("unroll") for (int k = 0; k < 2; ++k) \
;         acc[ai][bj][m][n] = __builtin_amdgcn_mfma_f32_16x16x32_bf16(Bt[n][k], At[m][k], acc[ai][bj][m][n], 0, 0, 0); __builtin_amdgcn_s_setprio(0); } while (0)
; #define PG8_WAIT_V(n) asm volatile("s_waitcnt vmcnt(" #n ")" ::: "memory")
; #define PG8_WAIT_L(n) asm volatile("s_waitcnt lgkmcnt(" #n ")" ::: "memory")
; #define PG8_BAR __builtin_amdgcn_s_barrier()
; #define PG8_SCHED __builtin_amdgcn_sched_barrier(0)
; template <class Epi, class Sched, bool ALIGN_EPI = false, bool SP2 = false>
; __device__ __forceinline__ void gemm_phase(PG8_LAS unsigned char* lds, const Gemm g, const Sched& S, const Epi& E) {
;     ...
;             PG8_LDB(B0, 1, 0); PG8_LDB(B1, 1, 1); PG8_SCHED; PG8_LDA(At, 1, 0); PG8_STAGE(PG8_SA(0, 1), a2 + hstep, voffA);
;             PG8_WAIT_V(8); PG8_WAIT_L(0); PG8_BAR; PG8_MMA(0, 0, At, B0); PG8_MMA(0, 1, At, B1); PG8_BAR; PG8_SCHED;
.Lpz2_mid:
	s_add_i32 s42, 0, 0x18000
	s_add_i32 s43, 0, 0x1c000
	v_add_u32_e32 v142, s42, v222
	v_add_u32_e32 v154, s43, v222
	ds_read_b128 v[130:133], v142
	ds_read_b128 v[134:137], v142 offset:1024
	ds_read_b128 v[138:141], v142 offset:2048
	ds_read_b128 v[142:145], v142 offset:3072
	ds_read_b128 v[164:167], v154
	ds_read_b128 v[168:171], v154 offset:1024
	ds_read_b128 v[172:175], v154 offset:2048
	ds_read_b128 v[176:179], v154 offset:3072
	s_add_u32 s4, s36, 0xb0000
	s_addc_u32 s5, s37, 0
	s_mov_b32 m0, s53
	v_lshl_add_u64 v[216:217], s[4:5], 0, v[146:147]
	ds_read_b128 v[180:183], v225 offset:32768
	ds_read_b128 v[184:187], v225 offset:33792
	ds_read_b128 v[188:191], v225 offset:34816
	ds_read_b128 v[192:195], v225 offset:35840
	ds_read_b128 v[196:199], v225 offset:36864
	ds_read_b128 v[200:203], v225 offset:37888
	ds_read_b128 v[204:207], v225 offset:38912
	ds_read_b128 v[208:211], v225 offset:39936
	global_load_lds_dwordx4 v[216:217], off
	v_lshl_add_u64 v[216:217], s[4:5], 0, v[150:151]
	s_mov_b32 m0, s54
	s_nop 0
	global_load_lds_dwordx4 v[216:217], off
	s_waitcnt vmcnt(8)
	s_waitcnt lgkmcnt(0)
	s_barrier
	s_setprio 1
	v_mfma_f32_16x16x32_bf16 v[126:129], v[130:133], v[180:183], v[126:129]
	v_mfma_f32_16x16x32_bf16 v[122:125], v[138:141], v[180:183], v[122:125]
	v_mfma_f32_16x16x32_bf16 v[110:113], v[130:133], v[188:191], v[110:113]
	v_mfma_f32_16x16x32_bf16 v[106:109], v[138:141], v[188:191], v[106:109]
	v_mfma_f32_16x16x32_bf16 v[94:97], v[130:133], v[196:199], v[94:97]
	v_mfma_f32_16x16x32_bf16 v[90:93], v[138:141], v[196:199], v[90:93]
	v_mfma_f32_16x16x32_bf16 v[78:81], v[130:133], v[204:207], v[78:81]
	v_mfma_f32_16x16x32_bf16 v[74:77], v[138:141], v[204:207], v[74:77]
	v_mfma_f32_16x16x32_bf16 v[126:129], v[134:137], v[184:187], v[126:129]
	v_mfma_f32_16x16x32_bf16 v[122:125], v[142:145], v[184:187], v[122:125]
	v_mfma_f32_16x16x32_bf16 v[110:113], v[134:137], v[192:195], v[110:113]
	v_mfma_f32_16x16x32_bf16 v[106:109], v[142:145], v[192:195], v[106:109]
	v_mfma_f32_16x16x32_bf16 v[94:97], v[134:137], v[200:203], v[94:97]
	v_mfma_f32_16x16x32_bf16 v[90:93], v[142:145], v[200:203], v[90:93]
	v_mfma_f32_16x16x32_bf16 v[78:81], v[134:137], v[208:211], v[78:81]
	v_mfma_f32_16x16x32_bf16 v[74:77], v[142:145], v[208:211], v[74:77]
	v_mfma_f32_16x16x32_bf16 v[118:121], v[164:167], v[180:183], v[118:121]
	v_mfma_f32_16x16x32_bf16 v[114:117], v[172:175], v[180:183], v[114:117]
	v_mfma_f32_16x16x32_bf16 v[102:105], v[164:167], v[188:191], v[102:105]
	v_mfma_f32_16x16x32_bf16 v[98:101], v[172:175], v[188:191], v[98:101]
	v_mfma_f32_16x16x32_bf16 v[86:89], v[164:167], v[196:199], v[86:89]
	v_mfma_f32_16x16x32_bf16 v[82:85], v[172:175], v[196:199], v[82:85]
	v_mfma_f32_16x16x32_bf16 v[70:73], v[164:167], v[204:207], v[70:73]
	v_mfma_f32_16x16x32_bf16 v[66:69], v[172:175], v[204:207], v[66:69]
	v_mfma_f32_16x16x32_bf16 v[118:121], v[168:171], v[184:187], v[118:121]
	v_mfma_f32_16x16x32_bf16 v[114:117], v[176:179], v[184:187], v[114:117]
	v_mfma_f32_16x16x32_bf16 v[102:105], v[168:171], v[192:195], v[102:105]
	v_mfma_f32_16x16x32_bf16 v[98:101], v[176:179], v[192:195], v[98:101]
	v_mfma_f32_16x16x32_bf16 v[86:89], v[168:171], v[200:203], v[86:89]
	v_mfma_f32_16x16x32_bf16 v[82:85], v[176:179], v[200:203], v[82:85]
	v_mfma_f32_16x16x32_bf16 v[70:73], v[168:171], v[208:211], v[70:73]
	v_mfma_f32_16x16x32_bf16 v[66:69], v[176:179], v[208:211], v[66:69]
	s_setprio 0
	s_barrier
; #define PG8_STAGE(bufoff, gbase, voff) do { _Pragma("unroll") for (int _i = 0; _i < 2; ++_i) \
;         __builtin_amdgcn_global_load_lds((const unsigned*)((const char*)(gbase) + (voff)[_i]), (PG8_LAS unsigned*)(lds + (bufoff) + ldsw + _i * 8192), 16, 0, 0); } while (0)
; #define PG8_LDA(dst, b, h) do { _Pragma("unroll") for (int m = 0; m < 4; ++m) _Pragma("unroll") for (int k = 0; k < 2; ++k) dst[m][k] = *(const PG8_LAS bf16x8*)(lds + PG8_SA(b, h) + aoff + m * 2048 + k * 1024); } while (0)
; #define PG8_WAIT_V(n) asm volatile("s_waitcnt vmcnt(" #n ")" ::: "memory")
; template <class Epi, class Sched, bool ALIGN_EPI = false, bool SP2 = false>
; __device__ __forceinline__ void gemm_phase(PG8_LAS unsigned char* lds, const Gemm g, const Sched& S, const Epi& E) {
;     ...
;             PG8_LDA(At, 1, 1); PG8_STAGE(PG8_SB(1, 0), b3, voffB); PG8_STAGE(PG8_SB(1, 1), b3 + hstep, voffB); PG8_STAGE(PG8_SA(1, 0), a3, voffA);
;             PG8_WAIT_V(8); PG8_WAIT_L(0); PG8_BAR; PG8_MMA(1, 0, At, B0); PG8_MMA(1, 1, At, B1); PG8_BAR; PG8_SCHED;
;             } else {
;             PG8_LDB(B0, 0, 0); PG8_SCHED; PG8_LDA(At, 0, 0); PG8_STAGE(PG8_SA(1, 1), a1 + hstep, voffA);
;             PG8_WAIT_L(8); PG8_BAR; PG8_WAIT_L(0); PG8_MMA(0, 0, At, B0); PG8_BAR; PG8_SCHED;
;             PG8_LDB(B1, 0, 1); PG8_STAGE(PG8_SB(0, 0), b2, voffB);
;             PG8_BAR; PG8_WAIT_L(0); PG8_MMA(0, 1, At, B1); PG8_BAR;
;             PG8_LDA(At, 0, 1); PG8_STAGE(PG8_SA(0, 0), a2, voffA);
;             PG8_BAR; PG8_WAIT_L(0); PG8_MMA(1, 0, At, B0); PG8_BAR; PG8_SCHED;
;             PG8_STAGE(PG8_SB(0, 1), b2 + hstep, voffB);
;             PG8_WAIT_V(6); PG8_BAR; PG8_MMA(1, 1, At, B1); PG8_BAR;
;             PG8_LDB(B0, 1, 0); PG8_SCHED; PG8_LDA(At, 1, 0); PG8_STAGE(PG8_SA(0, 1), a2 + hstep, voffA);
;             PG8_WAIT_L(8); PG8_BAR; PG8_WAIT_L(0); PG8_MMA(0, 0, At, B0); PG8_BAR; PG8_SCHED;
;             PG8_LDB(B1, 1, 1); PG8_STAGE(PG8_SB(1, 0), b3, voffB);
;             PG8_BAR; PG8_WAIT_L(0); PG8_MMA(0, 1, At, B1); PG8_BAR;
;             PG8_LDA(At, 1, 1); PG8_STAGE(PG8_SA(1, 0), a3, voffA);
;             PG8_BAR; PG8_WAIT_L(0); PG8_MMA(1, 0, At, B0); PG8_BAR; PG8_SCHED;
;             PG8_STAGE(PG8_SB(1, 1), b3 + hstep, voffB);
;             PG8_WAIT_V(6); PG8_BAR; PG8_MMA(1, 1, At, B1); PG8_BAR;
;             }
;         }
;         if constexpr (ALIGN_EPI) { if (wr == 0) PG8_BAR; }
	s_add_i32 s4, s42, s50
	v_lshl_add_u64 v[160:161], v[160:161], 0, s[22:23]
	s_mov_b32 m0, s4
	ds_read_b128 v[180:183], v225 offset:49152
	ds_read_b128 v[184:187], v225 offset:50176
	ds_read_b128 v[188:191], v225 offset:51200
	ds_read_b128 v[192:195], v225 offset:52224
	ds_read_b128 v[196:199], v225 offset:53248
	ds_read_b128 v[200:203], v225 offset:54272
	ds_read_b128 v[204:207], v225 offset:55296
	ds_read_b128 v[208:211], v225 offset:56320
	global_load_lds_dwordx4 v[160:161], off
	s_add_i32 m0, s4, 0x2000
	s_add_u32 s4, s6, 0xb0080
	v_lshl_add_u64 v[160:161], v[162:163], 0, s[22:23]
	s_addc_u32 s5, s7, 0
	s_add_i32 s6, s43, s50
	global_load_lds_dwordx4 v[160:161], off
	v_lshl_add_u64 v[160:161], s[4:5], 0, v[148:149]
	s_mov_b32 m0, s6
	s_nop 0
	global_load_lds_dwordx4 v[160:161], off
	v_lshl_add_u64 v[160:161], s[4:5], 0, v[152:153]
	s_add_i32 m0, s6, 0x2000
	s_nop 0
	global_load_lds_dwordx4 v[160:161], off
	v_lshl_add_u64 v[160:161], v[212:213], 0, s[24:25]
	s_mov_b32 m0, s63
	s_nop 0
	global_load_lds_dwordx4 v[160:161], off
	v_lshl_add_u64 v[160:161], v[214:215], 0, s[24:25]
	s_mov_b32 m0, s64
	s_nop 0
	global_load_lds_dwordx4 v[160:161], off
	s_waitcnt vmcnt(8)
	s_waitcnt lgkmcnt(0)
	s_barrier
	s_setprio 1
	v_mfma_f32_16x16x32_bf16 v[62:65], v[130:133], v[180:183], v[62:65]
	v_mfma_f32_16x16x32_bf16 v[58:61], v[138:141], v[180:183], v[58:61]
	v_mfma_f32_16x16x32_bf16 v[46:49], v[130:133], v[188:191], v[46:49]
	v_mfma_f32_16x16x32_bf16 v[42:45], v[138:141], v[188:191], v[42:45]
	v_mfma_f32_16x16x32_bf16 v[30:33], v[130:133], v[196:199], v[30:33]
	v_mfma_f32_16x16x32_bf16 v[26:29], v[138:141], v[196:199], v[26:29]
	v_mfma_f32_16x16x32_bf16 v[14:17], v[130:133], v[204:207], v[14:17]
	v_mfma_f32_16x16x32_bf16 v[10:13], v[138:141], v[204:207], v[10:13]
	v_mfma_f32_16x16x32_bf16 v[62:65], v[134:137], v[184:187], v[62:65]
	v_mfma_f32_16x16x32_bf16 v[58:61], v[142:145], v[184:187], v[58:61]
	v_mfma_f32_16x16x32_bf16 v[46:49], v[134:137], v[192:195], v[46:49]
	v_mfma_f32_16x16x32_bf16 v[42:45], v[142:145], v[192:195], v[42:45]
	v_mfma_f32_16x16x32_bf16 v[30:33], v[134:137], v[200:203], v[30:33]
	v_mfma_f32_16x16x32_bf16 v[26:29], v[142:145], v[200:203], v[26:29]
	v_mfma_f32_16x16x32_bf16 v[14:17], v[134:137], v[208:211], v[14:17]
	v_mfma_f32_16x16x32_bf16 v[10:13], v[142:145], v[208:211], v[10:13]
	v_mfma_f32_16x16x32_bf16 v[54:57], v[164:167], v[180:183], v[54:57]
	v_mfma_f32_16x16x32_bf16 v[50:53], v[172:175], v[180:183], v[50:53]
	v_mfma_f32_16x16x32_bf16 v[38:41], v[164:167], v[188:191], v[38:41]
	v_mfma_f32_16x16x32_bf16 v[34:37], v[172:175], v[188:191], v[34:37]
	v_mfma_f32_16x16x32_bf16 v[22:25], v[164:167], v[196:199], v[22:25]
	v_mfma_f32_16x16x32_bf16 v[18:21], v[172:175], v[196:199], v[18:21]
	v_mfma_f32_16x16x32_bf16 v[6:9], v[164:167], v[204:207], v[6:9]
	v_mfma_f32_16x16x32_bf16 v[2:5], v[172:175], v[204:207], v[2:5]
	v_mfma_f32_16x16x32_bf16 v[54:57], v[168:171], v[184:187], v[54:57]
	v_mfma_f32_16x16x32_bf16 v[50:53], v[176:179], v[184:187], v[50:53]
	v_mfma_f32_16x16x32_bf16 v[38:41], v[168:171], v[192:195], v[38:41]
	v_mfma_f32_16x16x32_bf16 v[34:37], v[176:179], v[192:195], v[34:37]
	v_mfma_f32_16x16x32_bf16 v[22:25], v[168:171], v[200:203], v[22:25]
	v_mfma_f32_16x16x32_bf16 v[18:21], v[176:179], v[200:203], v[18:21]
	v_mfma_f32_16x16x32_bf16 v[6:9], v[168:171], v[208:211], v[6:9]
	v_mfma_f32_16x16x32_bf16 v[2:5], v[176:179], v[208:211], v[2:5]
	s_setprio 0
	s_barrier
	s_add_i32 s41, s41, 2
	s_add_u32 s39, s39, 0x100
	s_addc_u32 s40, s40, 0
	s_cmp_gt_u32 s41, 41
	s_mov_b64 s[4:5], s[0:1]
	s_cbranch_scc0 .LBB0_289
	s_and_b64 vcc, exec, s[26:27]
	s_cbranch_vccz .LBB0_292
	s_barrier

;     __host__ __device__ bool next(int i, Unit& u) const { if (!b.next(i >> 1, u)) return false; u.sel = i & 1; return true; }
; #define PG8_STAGE(bufoff, gbase, voff) do { _Pragma("unroll") for (int _i = 0; _i < 2; ++_i) \
;         __builtin_amdgcn_global_load_lds((const unsigned*)((const char*)(gbase) + (voff)[_i]), (PG8_LAS unsigned*)(lds + (bufoff) + ldsw + _i * 8192), 16, 0, 0); } while (0)
; #define PG8_LDA(dst, b, h) do { _Pragma("unroll") for (int m = 0; m < 4; ++m) _Pragma("unroll") for (int k = 0; k < 2; ++k) dst[m][k] = *(const PG8_LAS bf16x8*)(lds + PG8_SA(b, h) + aoff + m * 2048 + k * 1024); } while (0)
; #define PG8_WAIT_V(n) asm volatile("s_waitcnt vmcnt(" #n ")" ::: "memory")
;     __host__ __device__ bool next(int i, Unit& u) const {
;         const long L = (long)i * G + c; if (L >= nwg) return false;
;         int wgid = (int)L; { const int q = nwg / NXCD, r = nwg % NXCD, xcd = wgid % NXCD, off = wgid / NXCD; wgid = (xcd < r ? xcd * (q + 1) : r * (q + 1) + (xcd - r) * q) + off; }
;         const int nig = WGM * nN, gid = wgid / nig, fm = gid * WGM, gsz = (nM - fm) < WGM ? (nM - fm) : WGM;
;         u.pm = fm + ((wgid % nig) % gsz); u.pn = (wgid % nig) / gsz; u.sel = 0; return true;
; template <class Epi, class Sched, bool ALIGN_EPI = false, bool SP2 = false>
; __device__ __forceinline__ void gemm_phase(PG8_LAS unsigned char* lds, const Gemm g, const Sched& S, const Epi& E) {
;     ...
;         const bool has_next = S.next(ui + 1, nxt);
;         const char* nA = has_next ? PG8_ABASE(nxt) : cA; const char* nB = has_next ? PG8_BBASE(nxt) : cB;
;         for (int t = 0; t < nt; t += 2) {
;             const bool last = (t == nt - 2);
;             const char* a1 = cA + (size_t)(t + 1) * kstepA;
;             const char* a2 = last ? nA : cA + (size_t)(t + 2) * kstepA; const char* b2 = last ? nB : cB + (size_t)(t + 2) * kstep;
;             const char* a3 = a2 + kstepA; const char* b3 = b2 + kstep;
;             if (last && has_next) S.a_ready(nxt);
;             if constexpr (SP2) {
;             PG8_LDB(B0, 0, 0); PG8_LDB(B1, 0, 1); PG8_SCHED; PG8_LDA(At, 0, 0); PG8_STAGE(PG8_SA(1, 1), a1 + hstep, voffA);
;             PG8_WAIT_V(8); PG8_WAIT_L(0); PG8_BAR; PG8_MMA(0, 0, At, B0); PG8_MMA(0, 1, At, B1); PG8_BAR; PG8_SCHED;
;             if constexpr (Epi::PREFETCH) { if (t == tpf) E.prefetch(cur, wid, lane); }
.LBB0_435:
	s_ashr_i32 s5, s4, 31
	s_lshl_b32 s8, s6, 8
	s_lshl_b64 s[28:29], s[4:5], 14
	s_ashr_i32 s5, s4, 5
	s_ashr_i32 s9, s8, 31
	s_add_u32 s52, s14, s28
	s_mul_hi_i32 s54, s5, 0x6800
	s_mulk_i32 s5, 0x6800
	s_addc_u32 s53, s88, s29
	s_add_u32 s5, s77, s5
	s_addc_u32 s55, s78, s54
	s_lshl_b64 s[28:29], s[8:9], 2
	s_add_u32 s54, s5, s28
	s_addc_u32 s55, s55, s29
	s_add_u32 s5, s56, 0x100
	v_lshl_add_u64 v[196:197], s[10:11], 0, v[188:189]
	v_lshl_add_u64 v[198:199], s[10:11], 0, v[190:191]
	s_addc_u32 s9, s57, 0
	s_mov_b32 s28, 0
	s_mov_b64 s[56:57], 0
	ds_read_b128 v[162:165], v208
	ds_read_b128 v[166:169], v208 offset:1024
	ds_read_b128 v[170:173], v208 offset:2048
	ds_read_b128 v[174:177], v208 offset:3072
	ds_read_b128 v[146:149], v209
	ds_read_b128 v[150:153], v209 offset:1024
	ds_read_b128 v[154:157], v209 offset:2048
	ds_read_b128 v[158:161], v209 offset:3072
	v_lshl_add_u64 v[42:43], v[196:197], 0, s[56:57]
	s_add_i32 m0, s69, 0xc000
	ds_read_b128 v[212:215], v210
	ds_read_b128 v[216:219], v210 offset:1024
	ds_read_b128 v[222:225], v210 offset:2048
	ds_read_b128 v[226:229], v210 offset:3072
	ds_read_b128 v[230:233], v210 offset:4096
	ds_read_b128 v[234:237], v210 offset:5120
	ds_read_b128 v[238:241], v210 offset:6144
	ds_read_b128 v[242:245], v210 offset:7168
	global_load_lds_dwordx4 v[42:43], off
	v_lshl_add_u64 v[42:43], v[198:199], 0, s[56:57]
	s_add_i32 m0, s69, 0xe000
	s_nop 0
	global_load_lds_dwordx4 v[42:43], off
	s_add_i32 s15, s15, 1
	s_mul_i32 s2, s15, s86
	s_mul_hi_u32 s3, s15, s33
	s_add_i32 s3, s3, s2
	s_mul_i32 s2, s15, s33
	v_readlane_b32 s98, v254, 12
	s_add_u32 s100, s2, s98
	s_addc_u32 s101, s3, s87
	v_cmp_lt_i64_e64 s[2:3], s[100:101], v[192:193]
	s_ashr_i32 s98, s100, 31
	s_lshr_b32 s98, s98, 29
	s_add_i32 s98, s100, s98
	s_ashr_i32 s7, s98, 3
	s_and_b32 s98, s98, -8
	s_sub_i32 s98, s100, s98
	s_cmp_lt_i32 s98, 0
	s_movk_i32 s100, 0x1a1
	s_cselect_b32 s100, s100, 0x1a0
	s_mul_i32 s98, s98, s100
	s_add_i32 s98, s98, s7
	s_mul_hi_i32 s7, s98, 0x4ec4ec4f
	s_lshr_b32 s100, s7, 31
	s_ashr_i32 s7, s7, 4
	s_add_i32 s7, s7, s100
	s_lshl_b32 s100, s7, 1
	s_mul_i32 s7, s7, 52
	s_sub_i32 s98, s98, s7
	s_lshr_b32 s44, s98, 1
	s_and_b32 s98, s98, 1
	s_add_i32 s46, s100, s98
	s_ashr_i32 s47, s46, 31
	s_lshl_b64 s[100:101], s[46:47], 19
	s_add_u32 s48, s64, s100
	s_addc_u32 s49, s65, s101
	s_and_b64 s[100:101], s[2:3], exec
	s_cselect_b32 s7, s49, s65
	s_cselect_b32 s31, s48, s64
	s_ashr_i32 s45, s44, 31
	s_lshl_b64 s[100:101], s[44:45], 19
	s_add_u32 s50, s66, s100
	s_addc_u32 s51, s67, s101
	s_and_b64 s[100:101], s[2:3], exec
	s_cselect_b32 s45, s51, s67
	s_cselect_b32 s47, s50, s66
	s_waitcnt vmcnt(8)
	s_waitcnt lgkmcnt(0)
	s_barrier
	s_setprio 1
	v_mfma_f32_16x16x32_bf16 v[42:45], v[162:165], v[212:215], 0
	v_mfma_f32_16x16x32_bf16 v[46:49], v[170:173], v[212:215], 0
	v_mfma_f32_16x16x32_bf16 v[50:53], v[162:165], v[222:225], 0
	v_mfma_f32_16x16x32_bf16 v[54:57], v[170:173], v[222:225], 0
	v_mfma_f32_16x16x32_bf16 v[110:113], v[162:165], v[230:233], 0
	v_mfma_f32_16x16x32_bf16 v[106:109], v[170:173], v[230:233], 0
	v_mfma_f32_16x16x32_bf16 v[94:97], v[162:165], v[238:241], 0
	v_mfma_f32_16x16x32_bf16 v[90:93], v[170:173], v[238:241], 0
	v_mfma_f32_16x16x32_bf16 v[42:45], v[166:169], v[216:219], v[42:45]
	v_mfma_f32_16x16x32_bf16 v[46:49], v[174:177], v[216:219], v[46:49]
	v_mfma_f32_16x16x32_bf16 v[50:53], v[166:169], v[226:229], v[50:53]
	v_mfma_f32_16x16x32_bf16 v[54:57], v[174:177], v[226:229], v[54:57]
	v_mfma_f32_16x16x32_bf16 v[110:113], v[166:169], v[234:237], v[110:113]
	v_mfma_f32_16x16x32_bf16 v[106:109], v[174:177], v[234:237], v[106:109]
	v_mfma_f32_16x16x32_bf16 v[94:97], v[166:169], v[242:245], v[94:97]
	v_mfma_f32_16x16x32_bf16 v[90:93], v[174:177], v[242:245], v[90:93]
	v_mfma_f32_16x16x32_bf16 v[122:125], v[146:149], v[212:215], 0
	v_mfma_f32_16x16x32_bf16 v[134:137], v[150:153], v[216:219], v[122:125]
	v_mfma_f32_16x16x32_bf16 v[122:125], v[154:157], v[212:215], 0
	v_mfma_f32_16x16x32_bf16 v[118:121], v[146:149], v[222:225], 0
	v_mfma_f32_16x16x32_bf16 v[114:117], v[154:157], v[222:225], 0
	v_mfma_f32_16x16x32_bf16 v[102:105], v[146:149], v[230:233], 0
	v_mfma_f32_16x16x32_bf16 v[98:101], v[154:157], v[230:233], 0
	v_mfma_f32_16x16x32_bf16 v[86:89], v[146:149], v[238:241], 0
	v_mfma_f32_16x16x32_bf16 v[82:85], v[154:157], v[238:241], 0
	v_mfma_f32_16x16x32_bf16 v[130:133], v[158:161], v[216:219], v[122:125]
	v_mfma_f32_16x16x32_bf16 v[118:121], v[150:153], v[226:229], v[118:121]
	v_mfma_f32_16x16x32_bf16 v[114:117], v[158:161], v[226:229], v[114:117]
	v_mfma_f32_16x16x32_bf16 v[102:105], v[150:153], v[234:237], v[102:105]
	v_mfma_f32_16x16x32_bf16 v[98:101], v[158:161], v[234:237], v[98:101]
	v_mfma_f32_16x16x32_bf16 v[86:89], v[150:153], v[242:245], v[86:89]
	v_mfma_f32_16x16x32_bf16 v[82:85], v[158:161], v[242:245], v[82:85]
	s_setprio 0
	s_barrier
	s_cmp_lg_u32 s63, s28
	s_cbranch_scc1 .Lpz3_a
	v_mov_b32_e32 v186, v207
	s_add_i32 m0, s62, 0x20000
	v_lshl_add_u64 v[122:123], s[52:53], 0, v[186:187]
	s_mov_b64 s[58:59], 0x400
	global_load_lds_dwordx4 v186, s[52:53]
	v_lshl_add_u64 v[122:123], v[122:123], 0, s[58:59]
	s_add_i32 m0, s62, 0x20400
	s_andn2_b64 vcc, exec, s[40:41]
	global_load_lds_dwordx4 v[122:123], off
	s_cbranch_vccnz .Lpz3_a
	v_lshl_add_u64 v[122:123], s[54:55], 0, v[186:187]
	s_mov_b32 m0, s30
	s_nop 0
	global_load_lds_dwordx4 v[122:123], off
	s_branch .Lpz3_a
; #define PG8_STAGE(bufoff, gbase, voff) do { _Pragma("unroll") for (int _i = 0; _i < 2; ++_i) \
;         __builtin_amdgcn_global_load_lds((const unsigned*)((const char*)(gbase) + (voff)[_i]), (PG8_LAS unsigned*)(lds + (bufoff) + ldsw + _i * 8192), 16, 0, 0); } while (0)
; #define PG8_LDA(dst, b, h) do { _Pragma("unroll") for (int m = 0; m < 4; ++m) _Pragma("unroll") for (int k = 0; k < 2; ++k) dst[m][k] = *(const PG8_LAS bf16x8*)(lds + PG8_SA(b, h) + aoff + m * 2048 + k * 1024); } while (0)
; #define PG8_MMA(ai, bj, At, Bt) do { __builtin_amdgcn_s_setprio(1); _Pragma("unroll") for (int m = 0; m < 4; ++m) _Pragma("unroll") for (int n = 0; n < 2; ++n) _Pragma("unroll") for (int k = 0; k < 2; ++k) \
;         acc[ai][bj][m][n] = __builtin_amdgcn_mfma_f32_16x16x32_bf16(Bt[n][k], At[m][k], acc[ai][bj][m][n], 0, 0, 0); __builtin_amdgcn_s_setprio(0); } while (0)
; #define PG8_WAIT_V(n) asm volatile("s_waitcnt vmcnt(" #n ")" ::: "memory")
; #define PG8_WAIT_L(n) asm volatile("s_waitcnt lgkmcnt(" #n ")" ::: "memory")
; #define PG8_BAR __builtin_amdgcn_s_barrier()
; #define PG8_SCHED __builtin_amdgcn_sched_barrier(0)
; template <class Epi, class Sched, bool ALIGN_EPI = false, bool SP2 = false>
; __device__ __forceinline__ void gemm_phase(PG8_LAS unsigned char* lds, const Gemm g, const Sched& S, const Epi& E) {
;     ...
;             PG8_LDA(At, 0, 1); PG8_STAGE(PG8_SB(0, 0), b2, voffB); PG8_STAGE(PG8_SB(0, 1), b2 + hstep, voffB); PG8_STAGE(PG8_SA(0, 0), a2, voffA);
;             PG8_WAIT_V(8); PG8_WAIT_L(0); PG8_BAR; PG8_MMA(1, 0, At, B0); PG8_MMA(1, 1, At, B1); PG8_BAR; PG8_SCHED;
.Lpz3_a:
	s_add_u32 s29, s10, s56
	s_addc_u32 s58, s11, s57
	s_add_u32 s29, s29, 0x100
	s_addc_u32 s58, s58, 0
	s_add_u32 vcc_lo, s5, s56
	s_addc_u32 s59, s9, s57
	s_cmpk_eq_i32 s56, 0x700
	s_cselect_b32 s61, s7, s58
	s_cselect_b32 s59, s45, s59
	s_cselect_b32 s58, s47, vcc_lo
	s_mov_b32 m0, s70
	s_cselect_b32 s60, s31, s29
	v_lshl_add_u64 v[204:205], s[58:59], 0, v[180:181]
	s_add_u32 vcc_lo, s58, 0x40000
	ds_read_b128 v[122:125], v210 offset:16384
	ds_read_b128 v[126:129], v210 offset:17408
	ds_read_b128 v[138:141], v210 offset:18432
	ds_read_b128 v[142:145], v210 offset:19456
	ds_read_b128 v[212:215], v210 offset:20480
	ds_read_b128 v[216:219], v210 offset:21504
	ds_read_b128 v[222:225], v210 offset:22528
	ds_read_b128 v[226:229], v210 offset:23552
	global_load_lds_dwordx4 v[204:205], off
	v_lshl_add_u64 v[246:247], s[58:59], 0, v[184:185]
	s_mov_b32 m0, s71
	s_addc_u32 vcc_hi, s59, 0
	global_load_lds_dwordx4 v[246:247], off
	v_lshl_add_u64 v[230:231], vcc, 0, v[180:181]
	s_mov_b32 m0, s72
	v_lshl_add_u64 v[248:249], s[60:61], 0, v[178:179]
	global_load_lds_dwordx4 v[230:231], off
	v_lshl_add_u64 v[230:231], vcc, 0, v[184:185]
	s_mov_b32 m0, s73
	v_lshl_add_u64 v[250:251], s[60:61], 0, v[182:183]
	global_load_lds_dwordx4 v[230:231], off
	s_mov_b32 m0, s69
	s_nop 0
	global_load_lds_dwordx4 v[248:249], off
	s_mov_b32 m0, s74
	s_nop 0
	global_load_lds_dwordx4 v[250:251], off
	s_waitcnt vmcnt(8)
	s_waitcnt lgkmcnt(0)
	s_barrier
	s_setprio 1
	v_mfma_f32_16x16x32_bf16 v[78:81], v[162:165], v[122:125], 0
	v_mfma_f32_16x16x32_bf16 v[74:77], v[170:173], v[122:125], 0
	v_mfma_f32_16x16x32_bf16 v[62:65], v[162:165], v[138:141], 0
	v_mfma_f32_16x16x32_bf16 v[58:61], v[170:173], v[138:141], 0
	v_mfma_f32_16x16x32_bf16 v[30:33], v[162:165], v[212:215], 0
	v_mfma_f32_16x16x32_bf16 v[26:29], v[170:173], v[212:215], 0
	v_mfma_f32_16x16x32_bf16 v[14:17], v[162:165], v[222:225], 0
	v_mfma_f32_16x16x32_bf16 v[10:13], v[170:173], v[222:225], 0
	v_mfma_f32_16x16x32_bf16 v[78:81], v[166:169], v[126:129], v[78:81]
	v_mfma_f32_16x16x32_bf16 v[74:77], v[174:177], v[126:129], v[74:77]
	v_mfma_f32_16x16x32_bf16 v[62:65], v[166:169], v[142:145], v[62:65]
	v_mfma_f32_16x16x32_bf16 v[58:61], v[174:177], v[142:145], v[58:61]
	v_mfma_f32_16x16x32_bf16 v[30:33], v[166:169], v[216:219], v[30:33]
	v_mfma_f32_16x16x32_bf16 v[26:29], v[174:177], v[216:219], v[26:29]
	v_mfma_f32_16x16x32_bf16 v[14:17], v[166:169], v[226:229], v[14:17]
	v_mfma_f32_16x16x32_bf16 v[10:13], v[174:177], v[226:229], v[10:13]
	v_mfma_f32_16x16x32_bf16 v[70:73], v[146:149], v[122:125], 0
	v_mfma_f32_16x16x32_bf16 v[66:69], v[154:157], v[122:125], 0
	v_mfma_f32_16x16x32_bf16 v[38:41], v[146:149], v[138:141], 0
	v_mfma_f32_16x16x32_bf16 v[34:37], v[154:157], v[138:141], 0
	v_mfma_f32_16x16x32_bf16 v[22:25], v[146:149], v[212:215], 0
	v_mfma_f32_16x16x32_bf16 v[18:21], v[154:157], v[212:215], 0
	v_mfma_f32_16x16x32_bf16 v[6:9], v[146:149], v[222:225], 0
	v_mfma_f32_16x16x32_bf16 v[2:5], v[154:157], v[222:225], 0
	v_mfma_f32_16x16x32_bf16 v[70:73], v[150:153], v[126:129], v[70:73]
	v_mfma_f32_16x16x32_bf16 v[66:69], v[158:161], v[126:129], v[66:69]
	v_mfma_f32_16x16x32_bf16 v[38:41], v[150:153], v[142:145], v[38:41]
	v_mfma_f32_16x16x32_bf16 v[34:37], v[158:161], v[142:145], v[34:37]
	v_mfma_f32_16x16x32_bf16 v[22:25], v[150:153], v[216:219], v[22:25]
	v_mfma_f32_16x16x32_bf16 v[18:21], v[158:161], v[216:219], v[18:21]
	v_mfma_f32_16x16x32_bf16 v[6:9], v[150:153], v[226:229], v[6:9]
	v_mfma_f32_16x16x32_bf16 v[2:5], v[158:161], v[226:229], v[2:5]
	s_setprio 0
	s_barrier
	s_branch .Lpz3_mid
.LBB0_438:
	s_add_u32 s29, s10, s56
	s_addc_u32 s58, s11, s57
	s_add_u32 s29, s29, 0x100
	s_addc_u32 s58, s58, 0
	s_add_u32 vcc_lo, s5, s56
	s_addc_u32 s59, s9, s57
	s_cmpk_eq_i32 s56, 0x700
	s_cselect_b32 s61, s7, s58
	s_cselect_b32 s59, s45, s59
	s_cselect_b32 s58, s47, vcc_lo
	s_mov_b32 m0, s70
	s_cselect_b32 s60, s31, s29
	v_lshl_add_u64 v[204:205], s[58:59], 0, v[180:181]
	s_add_u32 vcc_lo, s58, 0x40000
	ds_read_b128 v[122:125], v210 offset:16384
	ds_read_b128 v[126:129], v210 offset:17408
	ds_read_b128 v[138:141], v210 offset:18432
	ds_read_b128 v[142:145], v210 offset:19456
	ds_read_b128 v[212:215], v210 offset:20480
	ds_read_b128 v[216:219], v210 offset:21504
	ds_read_b128 v[222:225], v210 offset:22528
	ds_read_b128 v[226:229], v210 offset:23552
	global_load_lds_dwordx4 v[204:205], off
	v_lshl_add_u64 v[246:247], s[58:59], 0, v[184:185]
	s_mov_b32 m0, s71
	s_addc_u32 vcc_hi, s59, 0
	global_load_lds_dwordx4 v[246:247], off
	v_lshl_add_u64 v[230:231], vcc, 0, v[180:181]
	s_mov_b32 m0, s72
	v_lshl_add_u64 v[248:249], s[60:61], 0, v[178:179]
	global_load_lds_dwordx4 v[230:231], off
	v_lshl_add_u64 v[230:231], vcc, 0, v[184:185]
	s_mov_b32 m0, s73
	v_lshl_add_u64 v[250:251], s[60:61], 0, v[182:183]
	global_load_lds_dwordx4 v[230:231], off
	s_mov_b32 m0, s69
	s_nop 0
	global_load_lds_dwordx4 v[248:249], off
	s_mov_b32 m0, s74
	s_nop 0
	global_load_lds_dwordx4 v[250:251], off
	s_waitcnt vmcnt(8)
	s_waitcnt lgkmcnt(0)
	s_barrier
; #define PG8_STAGE(bufoff, gbase, voff) do { _Pragma("unroll") for (int _i = 0; _i < 2; ++_i) \
;         __builtin_amdgcn_global_load_lds((const unsigned*)((const char*)(gbase) + (voff)[_i]), (PG8_LAS unsigned*)(lds + (bufoff) + ldsw + _i * 8192), 16, 0, 0); } while (0)
; #define PG8_LDA(dst, b, h) do { _Pragma("unroll") for (int m = 0; m < 4; ++m) _Pragma("unroll") for (int k = 0; k < 2; ++k) dst[m][k] = *(const PG8_LAS bf16x8*)(lds + PG8_SA(b, h) + aoff + m * 2048 + k * 1024); } while (0)
; #define PG8_LDB(dst, b, h) do { _Pragma("unroll") for (int n = 0; n < 2; ++n) _Pragma("unroll") for (int k = 0; k < 2; ++k) dst[n][k] = *(const PG8_LAS bf16x8*)(lds + PG8_SB(b, h) + boff + n * 2048 + k * 1024); } while (0)
; #define PG8_MMA(ai, bj, At, Bt) do { __builtin_amdgcn_s_setprio(1); _Pragma("unroll") for (int m = 0; m < 4; ++m) _Pragma("unroll") for (int n = 0; n < 2; ++n) _Pragma("unroll") for (int k = 0; k < 2; ++k) \
;         acc[ai][bj][m][n] = __builtin_amdgcn_mfma_f32_16x16x32_bf16(Bt[n][k], At[m][k], acc[ai][bj][m][n], 0, 0, 0); __builtin_amdgcn_s_setprio(0); } while (0)
; #define PG8_WAIT_V(n) asm volatile("s_waitcnt vmcnt(" #n ")" ::: "memory")
; #define PG8_WAIT_L(n) asm volatile("s_waitcnt lgkmcnt(" #n ")" ::: "memory")
; #define PG8_BAR __builtin_amdgcn_s_barrier()
; #define PG8_SCHED __builtin_amdgcn_sched_barrier(0)
; template <class Epi, class Sched, bool ALIGN_EPI = false, bool SP2 = false>
; __device__ __forceinline__ void gemm_phase(PG8_LAS unsigned char* lds, const Gemm g, const Sched& S, const Epi& E) {
;     ...
;             PG8_WAIT_V(8); PG8_WAIT_L(0); PG8_BAR; PG8_MMA(1, 0, At, B0); PG8_MMA(1, 1, At, B1); PG8_BAR; PG8_SCHED;
;             PG8_LDB(B0, 1, 0); PG8_LDB(B1, 1, 1); PG8_SCHED; PG8_LDA(At, 1, 0); PG8_STAGE(PG8_SA(0, 1), a2 + hstep, voffA);
;             PG8_WAIT_V(8); PG8_WAIT_L(0); PG8_BAR; PG8_MMA(0, 0, At, B0); PG8_MMA(0, 1, At, B1); PG8_BAR; PG8_SCHED;
	s_setprio 1
	v_mfma_f32_16x16x32_bf16 v[78:81], v[162:165], v[122:125], v[78:81]
	v_mfma_f32_16x16x32_bf16 v[74:77], v[170:173], v[122:125], v[74:77]
	v_mfma_f32_16x16x32_bf16 v[62:65], v[162:165], v[138:141], v[62:65]
	v_mfma_f32_16x16x32_bf16 v[58:61], v[170:173], v[138:141], v[58:61]
	v_mfma_f32_16x16x32_bf16 v[30:33], v[162:165], v[212:215], v[30:33]
	v_mfma_f32_16x16x32_bf16 v[26:29], v[170:173], v[212:215], v[26:29]
	v_mfma_f32_16x16x32_bf16 v[14:17], v[162:165], v[222:225], v[14:17]
	v_mfma_f32_16x16x32_bf16 v[10:13], v[170:173], v[222:225], v[10:13]
	v_mfma_f32_16x16x32_bf16 v[78:81], v[166:169], v[126:129], v[78:81]
	v_mfma_f32_16x16x32_bf16 v[74:77], v[174:177], v[126:129], v[74:77]
	v_mfma_f32_16x16x32_bf16 v[62:65], v[166:169], v[142:145], v[62:65]
	v_mfma_f32_16x16x32_bf16 v[58:61], v[174:177], v[142:145], v[58:61]
	v_mfma_f32_16x16x32_bf16 v[30:33], v[166:169], v[216:219], v[30:33]
	v_mfma_f32_16x16x32_bf16 v[26:29], v[174:177], v[216:219], v[26:29]
	v_mfma_f32_16x16x32_bf16 v[14:17], v[166:169], v[226:229], v[14:17]
	v_mfma_f32_16x16x32_bf16 v[10:13], v[174:177], v[226:229], v[10:13]
	v_mfma_f32_16x16x32_bf16 v[70:73], v[146:149], v[122:125], v[70:73]
	v_mfma_f32_16x16x32_bf16 v[66:69], v[154:157], v[122:125], v[66:69]
	v_mfma_f32_16x16x32_bf16 v[38:41], v[146:149], v[138:141], v[38:41]
	v_mfma_f32_16x16x32_bf16 v[34:37], v[154:157], v[138:141], v[34:37]
	v_mfma_f32_16x16x32_bf16 v[22:25], v[146:149], v[212:215], v[22:25]
	v_mfma_f32_16x16x32_bf16 v[18:21], v[154:157], v[212:215], v[18:21]
	v_mfma_f32_16x16x32_bf16 v[6:9], v[146:149], v[222:225], v[6:9]
	v_mfma_f32_16x16x32_bf16 v[2:5], v[154:157], v[222:225], v[2:5]
	v_mfma_f32_16x16x32_bf16 v[70:73], v[150:153], v[126:129], v[70:73]
	v_mfma_f32_16x16x32_bf16 v[66:69], v[158:161], v[126:129], v[66:69]
	v_mfma_f32_16x16x32_bf16 v[38:41], v[150:153], v[142:145], v[38:41]
	v_mfma_f32_16x16x32_bf16 v[34:37], v[158:161], v[142:145], v[34:37]
	v_mfma_f32_16x16x32_bf16 v[22:25], v[150:153], v[216:219], v[22:25]
	v_mfma_f32_16x16x32_bf16 v[18:21], v[158:161], v[216:219], v[18:21]
	v_mfma_f32_16x16x32_bf16 v[6:9], v[150:153], v[226:229], v[6:9]
	v_mfma_f32_16x16x32_bf16 v[2:5], v[158:161], v[226:229], v[2:5]
	s_setprio 0
	s_barrier
.Lpz3_mid:
	s_add_i32 s29, 0, 0x18000
	v_add_u32_e32 v122, s29, v203
	s_add_i32 vcc_lo, 0, 0x1c000
	ds_read_b128 v[146:149], v122
	ds_read_b128 v[150:153], v122 offset:1024
	ds_read_b128 v[154:157], v122 offset:2048
	ds_read_b128 v[158:161], v122 offset:3072
	v_add_u32_e32 v122, vcc_lo, v203
	ds_read_b128 v[162:165], v122
	ds_read_b128 v[166:169], v122 offset:1024
	ds_read_b128 v[170:173], v122 offset:2048
	ds_read_b128 v[174:177], v122 offset:3072
	s_add_u32 s60, s60, 0x40000
	s_addc_u32 s61, s61, 0
	s_mov_b32 m0, s75
	v_lshl_add_u64 v[122:123], s[60:61], 0, v[178:179]
	ds_read_b128 v[212:215], v210 offset:32768
	ds_read_b128 v[216:219], v210 offset:33792
	ds_read_b128 v[222:225], v210 offset:34816
	ds_read_b128 v[226:229], v210 offset:35840
	ds_read_b128 v[230:233], v210 offset:36864
	ds_read_b128 v[234:237], v210 offset:37888
	ds_read_b128 v[238:241], v210 offset:38912
	ds_read_b128 v[242:245], v210 offset:39936
	global_load_lds_dwordx4 v[122:123], off
	v_lshl_add_u64 v[122:123], s[60:61], 0, v[182:183]
	s_mov_b32 m0, s76
	s_nop 0
	global_load_lds_dwordx4 v[122:123], off
	s_waitcnt vmcnt(8)
	s_waitcnt lgkmcnt(0)
	s_barrier
	s_setprio 1
	v_mfma_f32_16x16x32_bf16 v[42:45], v[146:149], v[212:215], v[42:45]
	v_mfma_f32_16x16x32_bf16 v[142:145], v[150:153], v[216:219], v[42:45]
	v_mfma_f32_16x16x32_bf16 v[42:45], v[154:157], v[212:215], v[46:49]
	v_mfma_f32_16x16x32_bf16 v[138:141], v[158:161], v[216:219], v[42:45]
	v_mfma_f32_16x16x32_bf16 v[42:45], v[146:149], v[222:225], v[50:53]
	v_mfma_f32_16x16x32_bf16 v[126:129], v[150:153], v[226:229], v[42:45]
	v_mfma_f32_16x16x32_bf16 v[42:45], v[154:157], v[222:225], v[54:57]
	v_mfma_f32_16x16x32_bf16 v[122:125], v[158:161], v[226:229], v[42:45]
	v_mfma_f32_16x16x32_bf16 v[42:45], v[146:149], v[230:233], v[110:113]
	v_mfma_f32_16x16x32_bf16 v[110:113], v[150:153], v[234:237], v[42:45]
	v_mfma_f32_16x16x32_bf16 v[42:45], v[154:157], v[230:233], v[106:109]
	v_mfma_f32_16x16x32_bf16 v[106:109], v[158:161], v[234:237], v[42:45]
	v_mfma_f32_16x16x32_bf16 v[42:45], v[146:149], v[238:241], v[94:97]
	v_mfma_f32_16x16x32_bf16 v[94:97], v[150:153], v[242:245], v[42:45]
	v_mfma_f32_16x16x32_bf16 v[42:45], v[154:157], v[238:241], v[90:93]
	v_mfma_f32_16x16x32_bf16 v[90:93], v[158:161], v[242:245], v[42:45]
	v_mfma_f32_16x16x32_bf16 v[42:45], v[162:165], v[212:215], v[134:137]
	v_mfma_f32_16x16x32_bf16 v[134:137], v[166:169], v[216:219], v[42:45]
	v_mfma_f32_16x16x32_bf16 v[42:45], v[170:173], v[212:215], v[130:133]
	v_mfma_f32_16x16x32_bf16 v[130:133], v[174:177], v[216:219], v[42:45]
	v_mfma_f32_16x16x32_bf16 v[42:45], v[162:165], v[222:225], v[118:121]
	v_mfma_f32_16x16x32_bf16 v[118:121], v[166:169], v[226:229], v[42:45]
	v_mfma_f32_16x16x32_bf16 v[42:45], v[170:173], v[222:225], v[114:117]
	v_mfma_f32_16x16x32_bf16 v[114:117], v[174:177], v[226:229], v[42:45]
	v_mfma_f32_16x16x32_bf16 v[42:45], v[162:165], v[230:233], v[102:105]
	v_mfma_f32_16x16x32_bf16 v[102:105], v[166:169], v[234:237], v[42:45]
	v_mfma_f32_16x16x32_bf16 v[42:45], v[170:173], v[230:233], v[98:101]
	v_mfma_f32_16x16x32_bf16 v[98:101], v[174:177], v[234:237], v[42:45]
	v_mfma_f32_16x16x32_bf16 v[42:45], v[162:165], v[238:241], v[86:89]
	v_mfma_f32_16x16x32_bf16 v[86:89], v[166:169], v[242:245], v[42:45]
	v_mfma_f32_16x16x32_bf16 v[42:45], v[170:173], v[238:241], v[82:85]
	v_mfma_f32_16x16x32_bf16 v[82:85], v[174:177], v[242:245], v[42:45]
	s_setprio 0
	s_barrier
; #define PG8_STAGE(bufoff, gbase, voff) do { _Pragma("unroll") for (int _i = 0; _i < 2; ++_i) \
;         __builtin_amdgcn_global_load_lds((const unsigned*)((const char*)(gbase) + (voff)[_i]), (PG8_LAS unsigned*)(lds + (bufoff) + ldsw + _i * 8192), 16, 0, 0); } while (0)
; #define PG8_LDA(dst, b, h) do { _Pragma("unroll") for (int m = 0; m < 4; ++m) _Pragma("unroll") for (int k = 0; k < 2; ++k) dst[m][k] = *(const PG8_LAS bf16x8*)(lds + PG8_SA(b, h) + aoff + m * 2048 + k * 1024); } while (0)
; #define PG8_MMA(ai, bj, At, Bt) do { __builtin_amdgcn_s_setprio(1); _Pragma("unroll") for (int m = 0; m < 4; ++m) _Pragma("unroll") for (int n = 0; n < 2; ++n) _Pragma("unroll") for (int k = 0; k < 2; ++k) \
;         acc[ai][bj][m][n] = __builtin_amdgcn_mfma_f32_16x16x32_bf16(Bt[n][k], At[m][k], acc[ai][bj][m][n], 0, 0, 0); __builtin_amdgcn_s_setprio(0); } while (0)
; #define PG8_WAIT_V(n) asm volatile("s_waitcnt vmcnt(" #n ")" ::: "memory")
; #define PG8_WAIT_L(n) asm volatile("s_waitcnt lgkmcnt(" #n ")" ::: "memory")
; #define PG8_BAR __builtin_amdgcn_s_barrier()
; #define PG8_SCHED __builtin_amdgcn_sched_barrier(0)
; template <class Epi, class Sched, bool ALIGN_EPI = false, bool SP2 = false>
; __device__ __forceinline__ void gemm_phase(PG8_LAS unsigned char* lds, const Gemm g, const Sched& S, const Epi& E) {
;     ...
;             PG8_LDA(At, 1, 1); PG8_STAGE(PG8_SB(1, 0), b3, voffB); PG8_STAGE(PG8_SB(1, 1), b3 + hstep, voffB); PG8_STAGE(PG8_SA(1, 0), a3, voffA);
;             PG8_WAIT_V(8); PG8_WAIT_L(0); PG8_BAR; PG8_MMA(1, 0, At, B0); PG8_MMA(1, 1, At, B1); PG8_BAR; PG8_SCHED;
	s_add_i32 s29, s29, s68
	v_lshl_add_u64 v[204:205], v[204:205], 0, s[38:39]
	s_mov_b32 m0, s29
	s_nop 1
	ds_read_b128 v[42:45], v210 offset:49152
	ds_read_b128 v[46:49], v210 offset:50176
	ds_read_b128 v[50:53], v210 offset:51200
	ds_read_b128 v[54:57], v210 offset:52224
	ds_read_b128 v[212:215], v210 offset:53248
	ds_read_b128 v[216:219], v210 offset:54272
	ds_read_b128 v[222:225], v210 offset:55296
	ds_read_b128 v[226:229], v210 offset:56320
	global_load_lds_dwordx4 v[204:205], off
	s_add_i32 m0, s29, 0x2000
	s_add_u32 s58, s58, 0x40080
	v_lshl_add_u64 v[204:205], v[246:247], 0, s[38:39]
	s_addc_u32 s59, s59, 0
	s_add_i32 s29, vcc_lo, s68
	global_load_lds_dwordx4 v[204:205], off
	v_lshl_add_u64 v[204:205], s[58:59], 0, v[180:181]
	s_mov_b32 m0, s29
	s_nop 0
	global_load_lds_dwordx4 v[204:205], off
	v_lshl_add_u64 v[204:205], s[58:59], 0, v[184:185]
	s_add_i32 m0, s29, 0x2000
	s_nop 0
	global_load_lds_dwordx4 v[204:205], off
	v_lshl_add_u64 v[204:205], v[248:249], 0, s[38:39]
	s_mov_b32 m0, s81
	s_nop 0
	global_load_lds_dwordx4 v[204:205], off
	v_lshl_add_u64 v[204:205], v[250:251], 0, s[38:39]
	s_mov_b32 m0, s82
	s_nop 0
	global_load_lds_dwordx4 v[204:205], off
	s_waitcnt vmcnt(8)
	s_waitcnt lgkmcnt(0)
	s_barrier
	s_setprio 1
	v_mfma_f32_16x16x32_bf16 v[78:81], v[146:149], v[42:45], v[78:81]
	v_mfma_f32_16x16x32_bf16 v[74:77], v[154:157], v[42:45], v[74:77]
	v_mfma_f32_16x16x32_bf16 v[62:65], v[146:149], v[50:53], v[62:65]
	v_mfma_f32_16x16x32_bf16 v[58:61], v[154:157], v[50:53], v[58:61]
	v_mfma_f32_16x16x32_bf16 v[30:33], v[146:149], v[212:215], v[30:33]
	v_mfma_f32_16x16x32_bf16 v[26:29], v[154:157], v[212:215], v[26:29]
	v_mfma_f32_16x16x32_bf16 v[14:17], v[146:149], v[222:225], v[14:17]
	v_mfma_f32_16x16x32_bf16 v[10:13], v[154:157], v[222:225], v[10:13]
	v_mfma_f32_16x16x32_bf16 v[78:81], v[150:153], v[46:49], v[78:81]
	v_mfma_f32_16x16x32_bf16 v[74:77], v[158:161], v[46:49], v[74:77]
	v_mfma_f32_16x16x32_bf16 v[62:65], v[150:153], v[54:57], v[62:65]
	v_mfma_f32_16x16x32_bf16 v[58:61], v[158:161], v[54:57], v[58:61]
	v_mfma_f32_16x16x32_bf16 v[30:33], v[150:153], v[216:219], v[30:33]
	v_mfma_f32_16x16x32_bf16 v[26:29], v[158:161], v[216:219], v[26:29]
	v_mfma_f32_16x16x32_bf16 v[14:17], v[150:153], v[226:229], v[14:17]
	v_mfma_f32_16x16x32_bf16 v[10:13], v[158:161], v[226:229], v[10:13]
	v_mfma_f32_16x16x32_bf16 v[70:73], v[162:165], v[42:45], v[70:73]
	v_mfma_f32_16x16x32_bf16 v[42:45], v[170:173], v[42:45], v[66:69]
	v_mfma_f32_16x16x32_bf16 v[38:41], v[162:165], v[50:53], v[38:41]
	v_mfma_f32_16x16x32_bf16 v[34:37], v[170:173], v[50:53], v[34:37]
	v_mfma_f32_16x16x32_bf16 v[22:25], v[162:165], v[212:215], v[22:25]
	v_mfma_f32_16x16x32_bf16 v[18:21], v[170:173], v[212:215], v[18:21]
	v_mfma_f32_16x16x32_bf16 v[6:9], v[162:165], v[222:225], v[6:9]
	v_mfma_f32_16x16x32_bf16 v[2:5], v[170:173], v[222:225], v[2:5]
	v_mfma_f32_16x16x32_bf16 v[70:73], v[166:169], v[46:49], v[70:73]
	v_mfma_f32_16x16x32_bf16 v[66:69], v[174:177], v[46:49], v[42:45]
	v_mfma_f32_16x16x32_bf16 v[38:41], v[166:169], v[54:57], v[38:41]
	v_mfma_f32_16x16x32_bf16 v[34:37], v[174:177], v[54:57], v[34:37]
	v_mfma_f32_16x16x32_bf16 v[22:25], v[166:169], v[216:219], v[22:25]
	v_mfma_f32_16x16x32_bf16 v[18:21], v[174:177], v[216:219], v[18:21]
	v_mfma_f32_16x16x32_bf16 v[6:9], v[166:169], v[226:229], v[6:9]
	v_mfma_f32_16x16x32_bf16 v[2:5], v[174:177], v[226:229], v[2:5]
	s_setprio 0
	s_barrier
	s_add_i32 s29, s28, 2
	s_add_u32 s56, s56, 0x100
	s_addc_u32 s57, s57, 0
	s_cmp_gt_u32 s28, 13
	s_mov_b32 s28, s29
	s_cbranch_scc1 .LBB0_442
; #define PG8_LAS __attribute__((address_space(3)))
; #define PG8_STAGE(bufoff, gbase, voff) do { _Pragma("unroll") for (int _i = 0; _i < 2; ++_i) \
;         __builtin_amdgcn_global_load_lds((const unsigned*)((const char*)(gbase) + (voff)[_i]), (PG8_LAS unsigned*)(lds + (bufoff) + ldsw + _i * 8192), 16, 0, 0); } while (0)
; #define PG8_LDA(dst, b, h) do { _Pragma("unroll") for (int m = 0; m < 4; ++m) _Pragma("unroll") for (int k = 0; k < 2; ++k) dst[m][k] = *(const PG8_LAS bf16x8*)(lds + PG8_SA(b, h) + aoff + m * 2048 + k * 1024); } while (0)
; #define PG8_LDB(dst, b, h) do { _Pragma("unroll") for (int n = 0; n < 2; ++n) _Pragma("unroll") for (int k = 0; k < 2; ++k) dst[n][k] = *(const PG8_LAS bf16x8*)(lds + PG8_SB(b, h) + boff + n * 2048 + k * 1024); } while (0)
; #define PG8_MMA(ai, bj, At, Bt) do { __builtin_amdgcn_s_setprio(1); _Pragma("unroll") for (int m = 0; m < 4; ++m) _Pragma("unroll") for (int n = 0; n < 2; ++n) _Pragma("unroll") for (int k = 0; k < 2; ++k) \
;         acc[ai][bj][m][n] = __builtin_amdgcn_mfma_f32_16x16x32_bf16(Bt[n][k], At[m][k], acc[ai][bj][m][n], 0, 0, 0); __builtin_amdgcn_s_setprio(0); } while (0)
; #define PG8_WAIT_V(n) asm volatile("s_waitcnt vmcnt(" #n ")" ::: "memory")
; template <class Epi, class Sched, bool ALIGN_EPI = false, bool SP2 = false>
; __device__ __forceinline__ void gemm_phase(PG8_LAS unsigned char* lds, const Gemm g, const Sched& S, const Epi& E) {
;     ...
;             PG8_LDB(B0, 0, 0); PG8_LDB(B1, 0, 1); PG8_SCHED; PG8_LDA(At, 0, 0); PG8_STAGE(PG8_SA(1, 1), a1 + hstep, voffA);
;             PG8_WAIT_V(8); PG8_WAIT_L(0); PG8_BAR; PG8_MMA(0, 0, At, B0); PG8_MMA(0, 1, At, B1); PG8_BAR; PG8_SCHED;
;             if constexpr (Epi::PREFETCH) { if (t == tpf) E.prefetch(cur, wid, lane); }
; __device__ __forceinline__ void epi_prefetch(PG8_LAS unsigned char* scr, const float* ssq, const float* bias_tile, const Unit& u, int wid, int lane) {
;     unsigned lo = (unsigned)lane * 16u; asm volatile("" : "+v"(lo));
;     const char* src = (const char*)(ssq + (size_t)u.pm * BM * 16 + wid * 512);
; #pragma unroll
;     for (int j = 0; j < 2; ++j) __builtin_amdgcn_global_load_lds((const unsigned*)(src + j * 1024 + lo), (PG8_LAS unsigned*)(scr + (wid * 2 + j) * 1024), 16, 0, 0);
;     if (wid == 0) __builtin_amdgcn_global_load_lds((const unsigned*)((const char*)bias_tile + lo), (PG8_LAS unsigned*)(scr + 16384), 16, 0, 0);
; }
.LBB0_439:
	ds_read_b128 v[162:165], v208
	ds_read_b128 v[166:169], v208 offset:1024
	ds_read_b128 v[170:173], v208 offset:2048
	ds_read_b128 v[174:177], v208 offset:3072
	ds_read_b128 v[146:149], v209
	ds_read_b128 v[150:153], v209 offset:1024
	ds_read_b128 v[154:157], v209 offset:2048
	ds_read_b128 v[158:161], v209 offset:3072
	v_lshl_add_u64 v[42:43], v[196:197], 0, s[56:57]
	s_add_i32 m0, s69, 0xc000
	ds_read_b128 v[212:215], v210
	ds_read_b128 v[216:219], v210 offset:1024
	ds_read_b128 v[222:225], v210 offset:2048
	ds_read_b128 v[226:229], v210 offset:3072
	ds_read_b128 v[230:233], v210 offset:4096
	ds_read_b128 v[234:237], v210 offset:5120
	ds_read_b128 v[238:241], v210 offset:6144
	ds_read_b128 v[242:245], v210 offset:7168
	global_load_lds_dwordx4 v[42:43], off
	v_lshl_add_u64 v[42:43], v[198:199], 0, s[56:57]
	s_add_i32 m0, s69, 0xe000
	s_nop 0
	global_load_lds_dwordx4 v[42:43], off
	s_waitcnt vmcnt(8)
	s_waitcnt lgkmcnt(0)
	s_barrier
	s_setprio 1
	v_mfma_f32_16x16x32_bf16 v[42:45], v[162:165], v[212:215], v[142:145]
	v_mfma_f32_16x16x32_bf16 v[46:49], v[170:173], v[212:215], v[138:141]
	v_mfma_f32_16x16x32_bf16 v[50:53], v[162:165], v[222:225], v[126:129]
	v_mfma_f32_16x16x32_bf16 v[54:57], v[170:173], v[222:225], v[122:125]
	v_mfma_f32_16x16x32_bf16 v[110:113], v[162:165], v[230:233], v[110:113]
	v_mfma_f32_16x16x32_bf16 v[106:109], v[170:173], v[230:233], v[106:109]
	v_mfma_f32_16x16x32_bf16 v[94:97], v[162:165], v[238:241], v[94:97]
	v_mfma_f32_16x16x32_bf16 v[90:93], v[170:173], v[238:241], v[90:93]
	v_mfma_f32_16x16x32_bf16 v[42:45], v[166:169], v[216:219], v[42:45]
	v_mfma_f32_16x16x32_bf16 v[46:49], v[174:177], v[216:219], v[46:49]
	v_mfma_f32_16x16x32_bf16 v[50:53], v[166:169], v[226:229], v[50:53]
	v_mfma_f32_16x16x32_bf16 v[54:57], v[174:177], v[226:229], v[54:57]
	v_mfma_f32_16x16x32_bf16 v[110:113], v[166:169], v[234:237], v[110:113]
	v_mfma_f32_16x16x32_bf16 v[106:109], v[174:177], v[234:237], v[106:109]
	v_mfma_f32_16x16x32_bf16 v[94:97], v[166:169], v[242:245], v[94:97]
	v_mfma_f32_16x16x32_bf16 v[90:93], v[174:177], v[242:245], v[90:93]
	v_mfma_f32_16x16x32_bf16 v[122:125], v[146:149], v[212:215], v[134:137]
	v_mfma_f32_16x16x32_bf16 v[134:137], v[150:153], v[216:219], v[122:125]
	v_mfma_f32_16x16x32_bf16 v[122:125], v[154:157], v[212:215], v[130:133]
	v_mfma_f32_16x16x32_bf16 v[118:121], v[146:149], v[222:225], v[118:121]
	v_mfma_f32_16x16x32_bf16 v[114:117], v[154:157], v[222:225], v[114:117]
	v_mfma_f32_16x16x32_bf16 v[102:105], v[146:149], v[230:233], v[102:105]
	v_mfma_f32_16x16x32_bf16 v[98:101], v[154:157], v[230:233], v[98:101]
	v_mfma_f32_16x16x32_bf16 v[86:89], v[146:149], v[238:241], v[86:89]
	v_mfma_f32_16x16x32_bf16 v[82:85], v[154:157], v[238:241], v[82:85]
	v_mfma_f32_16x16x32_bf16 v[130:133], v[158:161], v[216:219], v[122:125]
	v_mfma_f32_16x16x32_bf16 v[118:121], v[150:153], v[226:229], v[118:121]
	v_mfma_f32_16x16x32_bf16 v[114:117], v[158:161], v[226:229], v[114:117]
	v_mfma_f32_16x16x32_bf16 v[102:105], v[150:153], v[234:237], v[102:105]
	v_mfma_f32_16x16x32_bf16 v[98:101], v[158:161], v[234:237], v[98:101]
	v_mfma_f32_16x16x32_bf16 v[86:89], v[150:153], v[242:245], v[86:89]
	v_mfma_f32_16x16x32_bf16 v[82:85], v[158:161], v[242:245], v[82:85]
	s_setprio 0
	s_barrier
	s_cmp_lg_u32 s63, s28
	s_cbranch_scc1 .LBB0_438
	v_mov_b32_e32 v186, v207
	s_add_i32 m0, s62, 0x20000
	v_lshl_add_u64 v[122:123], s[52:53], 0, v[186:187]
	s_mov_b64 s[58:59], 0x400
	global_load_lds_dwordx4 v186, s[52:53]
	v_lshl_add_u64 v[122:123], v[122:123], 0, s[58:59]
	s_add_i32 m0, s62, 0x20400
	s_andn2_b64 vcc, exec, s[40:41]
	global_load_lds_dwordx4 v[122:123], off
	s_cbranch_vccnz .LBB0_438
	v_lshl_add_u64 v[122:123], s[54:55], 0, v[186:187]
	s_mov_b32 m0, s30
	s_nop 0
	global_load_lds_dwordx4 v[122:123], off
	s_branch .LBB0_438

; #define PG8_STAGE(bufoff, gbase, voff) do { _Pragma("unroll") for (int _i = 0; _i < 2; ++_i) \
;         __builtin_amdgcn_global_load_lds((const unsigned*)((const char*)(gbase) + (voff)[_i]), (PG8_LAS unsigned*)(lds + (bufoff) + ldsw + _i * 8192), 16, 0, 0); } while (0)
; #define PG8_LDA(dst, b, h) do { _Pragma("unroll") for (int m = 0; m < 4; ++m) _Pragma("unroll") for (int k = 0; k < 2; ++k) dst[m][k] = *(const PG8_LAS bf16x8*)(lds + PG8_SA(b, h) + aoff + m * 2048 + k * 1024); } while (0)
; #define PG8_LDB(dst, b, h) do { _Pragma("unroll") for (int n = 0; n < 2; ++n) _Pragma("unroll") for (int k = 0; k < 2; ++k) dst[n][k] = *(const PG8_LAS bf16x8*)(lds + PG8_SB(b, h) + boff + n * 2048 + k * 1024); } while (0)
; #define PG8_MMA(ai, bj, At, Bt) do { __builtin_amdgcn_s_setprio(1); _Pragma("unroll") for (int m = 0; m < 4; ++m) _Pragma("unroll") for (int n = 0; n < 2; ++n) _Pragma("unroll") for (int k = 0; k < 2; ++k) \
;         acc[ai][bj][m][n] = __builtin_amdgcn_mfma_f32_16x16x32_bf16(Bt[n][k], At[m][k], acc[ai][bj][m][n], 0, 0, 0); __builtin_amdgcn_s_setprio(0); } while (0)
; #define PG8_WAIT_V(n) asm volatile("s_waitcnt vmcnt(" #n ")" ::: "memory")
; #define PG8_WAIT_L(n) asm volatile("s_waitcnt lgkmcnt(" #n ")" ::: "memory")
; #define PG8_BAR __builtin_amdgcn_s_barrier()
; #define PG8_SCHED __builtin_amdgcn_sched_barrier(0)
;     __device__ __forceinline__ void prefetch(const Unit& u, int wid, int lane) const { epi_prefetch(scr, ssq, bias + (size_t)(u.pm >> 5) * NGU + u.pn * BM, u, wid, lane); }
; template <class Epi, class Sched, bool ALIGN_EPI = false, bool SP2 = false>
; __device__ __forceinline__ void gemm_phase(PG8_LAS unsigned char* lds, const Gemm g, const Sched& S, const Epi& E) {
;     ...
;             PG8_LDB(B0, 0, 0); PG8_LDB(B1, 0, 1); PG8_SCHED; PG8_LDA(At, 0, 0); PG8_STAGE(PG8_SA(1, 1), a1 + hstep, voffA);
;             PG8_WAIT_V(8); PG8_WAIT_L(0); PG8_BAR; PG8_MMA(0, 0, At, B0); PG8_MMA(0, 1, At, B1); PG8_BAR; PG8_SCHED;
;             if constexpr (Epi::PREFETCH) { if (t == tpf) E.prefetch(cur, wid, lane); }
;             PG8_LDA(At, 0, 1); PG8_STAGE(PG8_SB(0, 0), b2, voffB); PG8_STAGE(PG8_SB(0, 1), b2 + hstep, voffB); PG8_STAGE(PG8_SA(0, 0), a2, voffA);
;             PG8_WAIT_V(8); PG8_WAIT_L(0); PG8_BAR; PG8_MMA(1, 0, At, B0); PG8_MMA(1, 1, At, B1); PG8_BAR; PG8_SCHED;
.LBB0_723:
	v_add_u32_e32 v2, s67, v177
	ds_read_b128 v[134:137], v2
	ds_read_b128 v[138:141], v2 offset:1024
	ds_read_b128 v[142:145], v2 offset:2048
	ds_read_b128 v[146:149], v2 offset:3072
	v_add_u32_e32 v2, s68, v177
	ds_read_b128 v[150:153], v2
	ds_read_b128 v[170:173], v2 offset:1024
	ds_read_b128 v[180:183], v2 offset:2048
	ds_read_b128 v[184:187], v2 offset:3072
	s_add_u32 s28, s0, 0xfffc0080
	s_addc_u32 s29, s1, -1
	s_cmp_eq_u32 s43, 12
	s_cselect_b32 s37, s23, s29
	s_cselect_b32 s36, s39, s28
	s_cselect_b32 s29, s21, s42
	s_cselect_b32 s28, s40, s41
	v_lshl_add_u64 v[4:5], s[0:1], 0, v[162:163]
	s_add_i32 m0, s31, 0xc000
	ds_read_b128 v[188:191], v178
	ds_read_b128 v[192:195], v178 offset:1024
	ds_read_b128 v[196:199], v178 offset:2048
	ds_read_b128 v[200:203], v178 offset:3072
	ds_read_b128 v[204:207], v178 offset:4096
	ds_read_b128 v[208:211], v178 offset:5120
	ds_read_b128 v[212:215], v178 offset:6144
	ds_read_b128 v[216:219], v178 offset:7168
	global_load_lds_dwordx4 v[4:5], off
	v_lshl_add_u64 v[4:5], s[0:1], 0, v[164:165]
	s_add_i32 m0, s31, 0xe000
	s_nop 0
	global_load_lds_dwordx4 v[4:5], off
	s_waitcnt vmcnt(8)
	s_waitcnt lgkmcnt(0)
	s_barrier
	s_setprio 1
	v_mfma_f32_16x16x32_bf16 v[130:133], v[134:137], v[188:191], v[130:133]
	v_mfma_f32_16x16x32_bf16 v[126:129], v[142:145], v[188:191], v[126:129]
	v_mfma_f32_16x16x32_bf16 v[122:125], v[134:137], v[196:199], v[122:125]
	v_mfma_f32_16x16x32_bf16 v[118:121], v[142:145], v[196:199], v[118:121]
	v_mfma_f32_16x16x32_bf16 v[114:117], v[134:137], v[204:207], v[114:117]
	v_mfma_f32_16x16x32_bf16 v[110:113], v[142:145], v[204:207], v[110:113]
	v_mfma_f32_16x16x32_bf16 v[106:109], v[134:137], v[212:215], v[106:109]
	v_mfma_f32_16x16x32_bf16 v[102:105], v[142:145], v[212:215], v[102:105]
	v_mfma_f32_16x16x32_bf16 v[130:133], v[138:141], v[192:195], v[130:133]
	v_mfma_f32_16x16x32_bf16 v[126:129], v[146:149], v[192:195], v[126:129]
	v_mfma_f32_16x16x32_bf16 v[122:125], v[138:141], v[200:203], v[122:125]
	v_mfma_f32_16x16x32_bf16 v[118:121], v[146:149], v[200:203], v[118:121]
	v_mfma_f32_16x16x32_bf16 v[114:117], v[138:141], v[208:211], v[114:117]
	v_mfma_f32_16x16x32_bf16 v[110:113], v[146:149], v[208:211], v[110:113]
	v_mfma_f32_16x16x32_bf16 v[106:109], v[138:141], v[216:219], v[106:109]
	v_mfma_f32_16x16x32_bf16 v[102:105], v[146:149], v[216:219], v[102:105]
	v_mfma_f32_16x16x32_bf16 v[98:101], v[150:153], v[188:191], v[98:101]
	v_mfma_f32_16x16x32_bf16 v[94:97], v[180:183], v[188:191], v[94:97]
	v_mfma_f32_16x16x32_bf16 v[90:93], v[150:153], v[196:199], v[90:93]
	v_mfma_f32_16x16x32_bf16 v[86:89], v[180:183], v[196:199], v[86:89]
	v_mfma_f32_16x16x32_bf16 v[82:85], v[150:153], v[204:207], v[82:85]
	v_mfma_f32_16x16x32_bf16 v[78:81], v[180:183], v[204:207], v[78:81]
	v_mfma_f32_16x16x32_bf16 v[74:77], v[150:153], v[212:215], v[74:77]
	v_mfma_f32_16x16x32_bf16 v[70:73], v[180:183], v[212:215], v[70:73]
	v_mfma_f32_16x16x32_bf16 v[98:101], v[170:173], v[192:195], v[98:101]
	v_mfma_f32_16x16x32_bf16 v[94:97], v[184:187], v[192:195], v[94:97]
	v_mfma_f32_16x16x32_bf16 v[90:93], v[170:173], v[200:203], v[90:93]
	v_mfma_f32_16x16x32_bf16 v[86:89], v[184:187], v[200:203], v[86:89]
	v_mfma_f32_16x16x32_bf16 v[82:85], v[170:173], v[208:211], v[82:85]
	v_mfma_f32_16x16x32_bf16 v[78:81], v[184:187], v[208:211], v[78:81]
	v_mfma_f32_16x16x32_bf16 v[74:77], v[170:173], v[216:219], v[74:77]
	v_mfma_f32_16x16x32_bf16 v[70:73], v[184:187], v[216:219], v[70:73]
	s_setprio 0
	s_barrier
	s_add_i32 s71, s67, s48
	v_lshl_add_u64 v[174:175], s[28:29], 0, v[156:157]
	s_mov_b32 m0, s71
	ds_read_b128 v[188:191], v178 offset:16384
	ds_read_b128 v[192:195], v178 offset:17408
	ds_read_b128 v[196:199], v178 offset:18432
	ds_read_b128 v[200:203], v178 offset:19456
	ds_read_b128 v[204:207], v178 offset:20480
	ds_read_b128 v[208:211], v178 offset:21504
	ds_read_b128 v[212:215], v178 offset:22528
	ds_read_b128 v[216:219], v178 offset:23552
	global_load_lds_dwordx4 v[174:175], off
	s_add_i32 m0, s71, 0x2000
	s_add_u32 s72, s28, 0x40000
	v_lshl_add_u64 v[222:223], s[28:29], 0, v[160:161]
	s_addc_u32 s73, s29, 0
	s_add_i32 s71, s68, s48
	global_load_lds_dwordx4 v[222:223], off
	v_lshl_add_u64 v[4:5], s[72:73], 0, v[156:157]
	s_mov_b32 m0, s71
	v_lshl_add_u64 v[224:225], s[36:37], 0, v[154:155]
	global_load_lds_dwordx4 v[4:5], off
	v_lshl_add_u64 v[4:5], s[72:73], 0, v[160:161]
	s_add_i32 m0, s71, 0x2000
	v_lshl_add_u64 v[226:227], s[36:37], 0, v[158:159]
	global_load_lds_dwordx4 v[4:5], off
	s_mov_b32 m0, s31
	s_nop 0
	global_load_lds_dwordx4 v[224:225], off
	s_mov_b32 m0, s35
	s_nop 0
	global_load_lds_dwordx4 v[226:227], off
	s_waitcnt vmcnt(8)
	s_waitcnt lgkmcnt(0)
	s_barrier
; #define PG8_STAGE(bufoff, gbase, voff) do { _Pragma("unroll") for (int _i = 0; _i < 2; ++_i) \
;         __builtin_amdgcn_global_load_lds((const unsigned*)((const char*)(gbase) + (voff)[_i]), (PG8_LAS unsigned*)(lds + (bufoff) + ldsw + _i * 8192), 16, 0, 0); } while (0)
; #define PG8_LDA(dst, b, h) do { _Pragma("unroll") for (int m = 0; m < 4; ++m) _Pragma("unroll") for (int k = 0; k < 2; ++k) dst[m][k] = *(const PG8_LAS bf16x8*)(lds + PG8_SA(b, h) + aoff + m * 2048 + k * 1024); } while (0)
; #define PG8_LDB(dst, b, h) do { _Pragma("unroll") for (int n = 0; n < 2; ++n) _Pragma("unroll") for (int k = 0; k < 2; ++k) dst[n][k] = *(const PG8_LAS bf16x8*)(lds + PG8_SB(b, h) + boff + n * 2048 + k * 1024); } while (0)
; #define PG8_MMA(ai, bj, At, Bt) do { __builtin_amdgcn_s_setprio(1); _Pragma("unroll") for (int m = 0; m < 4; ++m) _Pragma("unroll") for (int n = 0; n < 2; ++n) _Pragma("unroll") for (int k = 0; k < 2; ++k) \
;         acc[ai][bj][m][n] = __builtin_amdgcn_mfma_f32_16x16x32_bf16(Bt[n][k], At[m][k], acc[ai][bj][m][n], 0, 0, 0); __builtin_amdgcn_s_setprio(0); } while (0)
; #define PG8_WAIT_V(n) asm volatile("s_waitcnt vmcnt(" #n ")" ::: "memory")
; #define PG8_WAIT_L(n) asm volatile("s_waitcnt lgkmcnt(" #n ")" ::: "memory")
; #define PG8_BAR __builtin_amdgcn_s_barrier()
; #define PG8_SCHED __builtin_amdgcn_sched_barrier(0)
; template <class Epi, class Sched, bool ALIGN_EPI = false, bool SP2 = false>
; __device__ __forceinline__ void gemm_phase(PG8_LAS unsigned char* lds, const Gemm g, const Sched& S, const Epi& E) {
;     ...
;             PG8_WAIT_V(8); PG8_WAIT_L(0); PG8_BAR; PG8_MMA(1, 0, At, B0); PG8_MMA(1, 1, At, B1); PG8_BAR; PG8_SCHED;
;             PG8_LDB(B0, 1, 0); PG8_LDB(B1, 1, 1); PG8_SCHED; PG8_LDA(At, 1, 0); PG8_STAGE(PG8_SA(0, 1), a2 + hstep, voffA);
;             PG8_WAIT_V(8); PG8_WAIT_L(0); PG8_BAR; PG8_MMA(0, 0, At, B0); PG8_MMA(0, 1, At, B1); PG8_BAR; PG8_SCHED;
	s_setprio 1
	v_mfma_f32_16x16x32_bf16 v[66:69], v[134:137], v[188:191], v[66:69]
	v_mfma_f32_16x16x32_bf16 v[62:65], v[142:145], v[188:191], v[62:65]
	v_mfma_f32_16x16x32_bf16 v[58:61], v[134:137], v[196:199], v[58:61]
	v_mfma_f32_16x16x32_bf16 v[54:57], v[142:145], v[196:199], v[54:57]
	v_mfma_f32_16x16x32_bf16 v[50:53], v[134:137], v[204:207], v[50:53]
	v_mfma_f32_16x16x32_bf16 v[46:49], v[142:145], v[204:207], v[46:49]
	v_mfma_f32_16x16x32_bf16 v[42:45], v[134:137], v[212:215], v[42:45]
	v_mfma_f32_16x16x32_bf16 v[38:41], v[142:145], v[212:215], v[38:41]
	v_mfma_f32_16x16x32_bf16 v[66:69], v[138:141], v[192:195], v[66:69]
	v_mfma_f32_16x16x32_bf16 v[62:65], v[146:149], v[192:195], v[62:65]
	v_mfma_f32_16x16x32_bf16 v[58:61], v[138:141], v[200:203], v[58:61]
	v_mfma_f32_16x16x32_bf16 v[54:57], v[146:149], v[200:203], v[54:57]
	v_mfma_f32_16x16x32_bf16 v[50:53], v[138:141], v[208:211], v[50:53]
	v_mfma_f32_16x16x32_bf16 v[46:49], v[146:149], v[208:211], v[46:49]
	v_mfma_f32_16x16x32_bf16 v[42:45], v[138:141], v[216:219], v[42:45]
	v_mfma_f32_16x16x32_bf16 v[38:41], v[146:149], v[216:219], v[38:41]
	v_mfma_f32_16x16x32_bf16 v[34:37], v[150:153], v[188:191], v[34:37]
	v_mfma_f32_16x16x32_bf16 v[30:33], v[180:183], v[188:191], v[30:33]
	v_mfma_f32_16x16x32_bf16 v[26:29], v[150:153], v[196:199], v[26:29]
	v_mfma_f32_16x16x32_bf16 v[22:25], v[180:183], v[196:199], v[22:25]
	v_mfma_f32_16x16x32_bf16 v[18:21], v[150:153], v[204:207], v[18:21]
	v_mfma_f32_16x16x32_bf16 v[14:17], v[180:183], v[204:207], v[14:17]
	v_mfma_f32_16x16x32_bf16 v[10:13], v[150:153], v[212:215], v[10:13]
	v_mfma_f32_16x16x32_bf16 v[4:7], v[180:183], v[212:215], v[6:9]
	v_mfma_f32_16x16x32_bf16 v[34:37], v[170:173], v[192:195], v[34:37]
	v_mfma_f32_16x16x32_bf16 v[30:33], v[184:187], v[192:195], v[30:33]
	v_mfma_f32_16x16x32_bf16 v[26:29], v[170:173], v[200:203], v[26:29]
	v_mfma_f32_16x16x32_bf16 v[22:25], v[184:187], v[200:203], v[22:25]
	v_mfma_f32_16x16x32_bf16 v[18:21], v[170:173], v[208:211], v[18:21]
	v_mfma_f32_16x16x32_bf16 v[14:17], v[184:187], v[208:211], v[14:17]
	v_mfma_f32_16x16x32_bf16 v[10:13], v[170:173], v[216:219], v[10:13]
	v_mfma_f32_16x16x32_bf16 v[4:7], v[184:187], v[216:219], v[4:7]
	s_setprio 0
	s_barrier
	s_add_i32 s71, 0, 0x18000
	v_add_u32_e32 v2, s71, v177
	s_add_i32 s72, 0, 0x1c000
	ds_read_b128 v[134:137], v2
	ds_read_b128 v[138:141], v2 offset:1024
	ds_read_b128 v[142:145], v2 offset:2048
	ds_read_b128 v[146:149], v2 offset:3072
	v_add_u32_e32 v2, s72, v177
	ds_read_b128 v[150:153], v2
	ds_read_b128 v[170:173], v2 offset:1024
	ds_read_b128 v[180:183], v2 offset:2048
	ds_read_b128 v[184:187], v2 offset:3072
	s_add_u32 s36, s36, 0x40000
	s_addc_u32 s37, s37, 0
	s_mov_b32 m0, s49
	v_lshl_add_u64 v[8:9], s[36:37], 0, v[154:155]
	ds_read_b128 v[188:191], v178 offset:32768
	ds_read_b128 v[192:195], v178 offset:33792
	ds_read_b128 v[196:199], v178 offset:34816
	ds_read_b128 v[200:203], v178 offset:35840
	ds_read_b128 v[204:207], v178 offset:36864
	ds_read_b128 v[208:211], v178 offset:37888
	ds_read_b128 v[212:215], v178 offset:38912
	ds_read_b128 v[216:219], v178 offset:39936
	global_load_lds_dwordx4 v[8:9], off
	v_lshl_add_u64 v[8:9], s[36:37], 0, v[158:159]
	s_mov_b32 m0, s50
	s_nop 0
	global_load_lds_dwordx4 v[8:9], off
	s_waitcnt vmcnt(8)
	s_waitcnt lgkmcnt(0)
	s_barrier
	s_setprio 1
	v_mfma_f32_16x16x32_bf16 v[130:133], v[134:137], v[188:191], v[130:133]
	v_mfma_f32_16x16x32_bf16 v[126:129], v[142:145], v[188:191], v[126:129]
	v_mfma_f32_16x16x32_bf16 v[122:125], v[134:137], v[196:199], v[122:125]
	v_mfma_f32_16x16x32_bf16 v[118:121], v[142:145], v[196:199], v[118:121]
	v_mfma_f32_16x16x32_bf16 v[114:117], v[134:137], v[204:207], v[114:117]
	v_mfma_f32_16x16x32_bf16 v[110:113], v[142:145], v[204:207], v[110:113]
	v_mfma_f32_16x16x32_bf16 v[106:109], v[134:137], v[212:215], v[106:109]
	v_mfma_f32_16x16x32_bf16 v[102:105], v[142:145], v[212:215], v[102:105]
	v_mfma_f32_16x16x32_bf16 v[130:133], v[138:141], v[192:195], v[130:133]
	v_mfma_f32_16x16x32_bf16 v[126:129], v[146:149], v[192:195], v[126:129]
	v_mfma_f32_16x16x32_bf16 v[122:125], v[138:141], v[200:203], v[122:125]
	v_mfma_f32_16x16x32_bf16 v[118:121], v[146:149], v[200:203], v[118:121]
	v_mfma_f32_16x16x32_bf16 v[114:117], v[138:141], v[208:211], v[114:117]
	v_mfma_f32_16x16x32_bf16 v[110:113], v[146:149], v[208:211], v[110:113]
	v_mfma_f32_16x16x32_bf16 v[106:109], v[138:141], v[216:219], v[106:109]
	v_mfma_f32_16x16x32_bf16 v[102:105], v[146:149], v[216:219], v[102:105]
	v_mfma_f32_16x16x32_bf16 v[98:101], v[150:153], v[188:191], v[98:101]
	v_mfma_f32_16x16x32_bf16 v[94:97], v[180:183], v[188:191], v[94:97]
	v_mfma_f32_16x16x32_bf16 v[90:93], v[150:153], v[196:199], v[90:93]
	v_mfma_f32_16x16x32_bf16 v[86:89], v[180:183], v[196:199], v[86:89]
	v_mfma_f32_16x16x32_bf16 v[82:85], v[150:153], v[204:207], v[82:85]
	v_mfma_f32_16x16x32_bf16 v[78:81], v[180:183], v[204:207], v[78:81]
	v_mfma_f32_16x16x32_bf16 v[74:77], v[150:153], v[212:215], v[74:77]
	v_mfma_f32_16x16x32_bf16 v[70:73], v[180:183], v[212:215], v[70:73]
	v_mfma_f32_16x16x32_bf16 v[98:101], v[170:173], v[192:195], v[98:101]
	v_mfma_f32_16x16x32_bf16 v[94:97], v[184:187], v[192:195], v[94:97]
	v_mfma_f32_16x16x32_bf16 v[90:93], v[170:173], v[200:203], v[90:93]
	v_mfma_f32_16x16x32_bf16 v[86:89], v[184:187], v[200:203], v[86:89]
	v_mfma_f32_16x16x32_bf16 v[82:85], v[170:173], v[208:211], v[82:85]
	v_mfma_f32_16x16x32_bf16 v[78:81], v[184:187], v[208:211], v[78:81]
	v_mfma_f32_16x16x32_bf16 v[74:77], v[170:173], v[216:219], v[74:77]
	v_mfma_f32_16x16x32_bf16 v[70:73], v[184:187], v[216:219], v[70:73]
	s_setprio 0
	s_barrier
; #define PG8_STAGE(bufoff, gbase, voff) do { _Pragma("unroll") for (int _i = 0; _i < 2; ++_i) \
;         __builtin_amdgcn_global_load_lds((const unsigned*)((const char*)(gbase) + (voff)[_i]), (PG8_LAS unsigned*)(lds + (bufoff) + ldsw + _i * 8192), 16, 0, 0); } while (0)
; #define PG8_LDA(dst, b, h) do { _Pragma("unroll") for (int m = 0; m < 4; ++m) _Pragma("unroll") for (int k = 0; k < 2; ++k) dst[m][k] = *(const PG8_LAS bf16x8*)(lds + PG8_SA(b, h) + aoff + m * 2048 + k * 1024); } while (0)
; #define PG8_WAIT_V(n) asm volatile("s_waitcnt vmcnt(" #n ")" ::: "memory")
; template <class Epi, class Sched, bool ALIGN_EPI = false, bool SP2 = false>
; __device__ __forceinline__ void gemm_phase(PG8_LAS unsigned char* lds, const Gemm g, const Sched& S, const Epi& E) {
;     ...
;             PG8_LDA(At, 1, 1); PG8_STAGE(PG8_SB(1, 0), b3, voffB); PG8_STAGE(PG8_SB(1, 1), b3 + hstep, voffB); PG8_STAGE(PG8_SA(1, 0), a3, voffA);
;             PG8_WAIT_V(8); PG8_WAIT_L(0); PG8_BAR; PG8_MMA(1, 0, At, B0); PG8_MMA(1, 1, At, B1); PG8_BAR; PG8_SCHED;
;             } else {
;             PG8_LDB(B0, 0, 0); PG8_SCHED; PG8_LDA(At, 0, 0); PG8_STAGE(PG8_SA(1, 1), a1 + hstep, voffA);
;             PG8_WAIT_L(8); PG8_BAR; PG8_WAIT_L(0); PG8_MMA(0, 0, At, B0); PG8_BAR; PG8_SCHED;
;             PG8_LDB(B1, 0, 1); PG8_STAGE(PG8_SB(0, 0), b2, voffB);
;             PG8_BAR; PG8_WAIT_L(0); PG8_MMA(0, 1, At, B1); PG8_BAR;
;             PG8_LDA(At, 0, 1); PG8_STAGE(PG8_SA(0, 0), a2, voffA);
;             PG8_BAR; PG8_WAIT_L(0); PG8_MMA(1, 0, At, B0); PG8_BAR; PG8_SCHED;
;             PG8_STAGE(PG8_SB(0, 1), b2 + hstep, voffB);
;             PG8_WAIT_V(6); PG8_BAR; PG8_MMA(1, 1, At, B1); PG8_BAR;
;             PG8_LDB(B0, 1, 0); PG8_SCHED; PG8_LDA(At, 1, 0); PG8_STAGE(PG8_SA(0, 1), a2 + hstep, voffA);
;             PG8_WAIT_L(8); PG8_BAR; PG8_WAIT_L(0); PG8_MMA(0, 0, At, B0); PG8_BAR; PG8_SCHED;
;             PG8_LDB(B1, 1, 1); PG8_STAGE(PG8_SB(1, 0), b3, voffB);
;             PG8_BAR; PG8_WAIT_L(0); PG8_MMA(0, 1, At, B1); PG8_BAR;
;             PG8_LDA(At, 1, 1); PG8_STAGE(PG8_SA(1, 0), a3, voffA);
;             PG8_BAR; PG8_WAIT_L(0); PG8_MMA(1, 0, At, B0); PG8_BAR; PG8_SCHED;
;             PG8_STAGE(PG8_SB(1, 1), b3 + hstep, voffB);
;             PG8_WAIT_V(6); PG8_BAR; PG8_MMA(1, 1, At, B1); PG8_BAR;
;             }
;         }
;         if constexpr (ALIGN_EPI) { if (wr == 0) PG8_BAR; }
	s_add_i32 s36, s71, s48
	v_lshl_add_u64 v[8:9], v[174:175], 0, s[14:15]
	s_mov_b32 m0, s36
	ds_read_b128 v[188:191], v178 offset:49152
	ds_read_b128 v[192:195], v178 offset:50176
	ds_read_b128 v[196:199], v178 offset:51200
	ds_read_b128 v[200:203], v178 offset:52224
	ds_read_b128 v[204:207], v178 offset:53248
	ds_read_b128 v[208:211], v178 offset:54272
	ds_read_b128 v[212:215], v178 offset:55296
	ds_read_b128 v[216:219], v178 offset:56320
	global_load_lds_dwordx4 v[8:9], off
	s_add_i32 m0, s36, 0x2000
	s_add_u32 s28, s28, 0x40080
	v_lshl_add_u64 v[8:9], v[222:223], 0, s[14:15]
	s_addc_u32 s29, s29, 0
	s_add_i32 s36, s72, s48
	global_load_lds_dwordx4 v[8:9], off
	v_lshl_add_u64 v[8:9], s[28:29], 0, v[156:157]
	s_mov_b32 m0, s36
	s_nop 0
	global_load_lds_dwordx4 v[8:9], off
	v_lshl_add_u64 v[8:9], s[28:29], 0, v[160:161]
	s_add_i32 m0, s36, 0x2000
	s_nop 0
	global_load_lds_dwordx4 v[8:9], off
	v_lshl_add_u64 v[8:9], v[224:225], 0, s[14:15]
	s_mov_b32 m0, s58
	s_nop 0
	global_load_lds_dwordx4 v[8:9], off
	v_lshl_add_u64 v[8:9], v[226:227], 0, s[14:15]
	s_mov_b32 m0, s59
	s_nop 0
	global_load_lds_dwordx4 v[8:9], off
	s_waitcnt vmcnt(8)
	s_waitcnt lgkmcnt(0)
	s_barrier
	s_setprio 1
	v_mfma_f32_16x16x32_bf16 v[66:69], v[134:137], v[188:191], v[66:69]
	v_mfma_f32_16x16x32_bf16 v[62:65], v[142:145], v[188:191], v[62:65]
	v_mfma_f32_16x16x32_bf16 v[58:61], v[134:137], v[196:199], v[58:61]
	v_mfma_f32_16x16x32_bf16 v[54:57], v[142:145], v[196:199], v[54:57]
	v_mfma_f32_16x16x32_bf16 v[50:53], v[134:137], v[204:207], v[50:53]
	v_mfma_f32_16x16x32_bf16 v[46:49], v[142:145], v[204:207], v[46:49]
	v_mfma_f32_16x16x32_bf16 v[42:45], v[134:137], v[212:215], v[42:45]
	v_mfma_f32_16x16x32_bf16 v[38:41], v[142:145], v[212:215], v[38:41]
	v_mfma_f32_16x16x32_bf16 v[66:69], v[138:141], v[192:195], v[66:69]
	v_mfma_f32_16x16x32_bf16 v[62:65], v[146:149], v[192:195], v[62:65]
	v_mfma_f32_16x16x32_bf16 v[58:61], v[138:141], v[200:203], v[58:61]
	v_mfma_f32_16x16x32_bf16 v[54:57], v[146:149], v[200:203], v[54:57]
	v_mfma_f32_16x16x32_bf16 v[50:53], v[138:141], v[208:211], v[50:53]
	v_mfma_f32_16x16x32_bf16 v[46:49], v[146:149], v[208:211], v[46:49]
	v_mfma_f32_16x16x32_bf16 v[42:45], v[138:141], v[216:219], v[42:45]
	v_mfma_f32_16x16x32_bf16 v[38:41], v[146:149], v[216:219], v[38:41]
	v_mfma_f32_16x16x32_bf16 v[34:37], v[150:153], v[188:191], v[34:37]
	v_mfma_f32_16x16x32_bf16 v[30:33], v[180:183], v[188:191], v[30:33]
	v_mfma_f32_16x16x32_bf16 v[26:29], v[150:153], v[196:199], v[26:29]
	v_mfma_f32_16x16x32_bf16 v[22:25], v[180:183], v[196:199], v[22:25]
	v_mfma_f32_16x16x32_bf16 v[18:21], v[150:153], v[204:207], v[18:21]
	v_mfma_f32_16x16x32_bf16 v[14:17], v[180:183], v[204:207], v[14:17]
	v_mfma_f32_16x16x32_bf16 v[8:11], v[150:153], v[212:215], v[10:13]
	v_mfma_f32_16x16x32_bf16 v[4:7], v[180:183], v[212:215], v[4:7]
	v_mfma_f32_16x16x32_bf16 v[34:37], v[170:173], v[192:195], v[34:37]
	v_mfma_f32_16x16x32_bf16 v[30:33], v[184:187], v[192:195], v[30:33]
	v_mfma_f32_16x16x32_bf16 v[26:29], v[170:173], v[200:203], v[26:29]
	v_mfma_f32_16x16x32_bf16 v[22:25], v[184:187], v[200:203], v[22:25]
	v_mfma_f32_16x16x32_bf16 v[18:21], v[170:173], v[208:211], v[18:21]
	v_mfma_f32_16x16x32_bf16 v[14:17], v[184:187], v[208:211], v[14:17]
	v_mfma_f32_16x16x32_bf16 v[10:13], v[170:173], v[216:219], v[8:11]
	v_mfma_f32_16x16x32_bf16 v[6:9], v[184:187], v[216:219], v[4:7]
	s_setprio 0
	s_barrier
	s_add_i32 s43, s43, 2
	s_add_u32 s0, s0, 0x100
	s_addc_u32 s1, s1, 0
	s_add_u32 s41, s41, 0x100
	s_addc_u32 s42, s42, 0
	s_cmp_gt_u32 s43, 13
	s_cbranch_scc0 .LBB0_723
	s_and_b64 vcc, exec, s[16:17]
	s_cbranch_vccz .LBB0_726
	s_barrier

; #define PG8_STAGE(bufoff, gbase, voff) do { _Pragma("unroll") for (int _i = 0; _i < 2; ++_i) \
;         __builtin_amdgcn_global_load_lds((const unsigned*)((const char*)(gbase) + (voff)[_i]), (PG8_LAS unsigned*)(lds + (bufoff) + ldsw + _i * 8192), 16, 0, 0); } while (0)
; #define PG8_LDA(dst, b, h) do { _Pragma("unroll") for (int m = 0; m < 4; ++m) _Pragma("unroll") for (int k = 0; k < 2; ++k) dst[m][k] = *(const PG8_LAS bf16x8*)(lds + PG8_SA(b, h) + aoff + m * 2048 + k * 1024); } while (0)
; #define PG8_LDB(dst, b, h) do { _Pragma("unroll") for (int n = 0; n < 2; ++n) _Pragma("unroll") for (int k = 0; k < 2; ++k) dst[n][k] = *(const PG8_LAS bf16x8*)(lds + PG8_SB(b, h) + boff + n * 2048 + k * 1024); } while (0)
; #define PG8_WAIT_V(n) asm volatile("s_waitcnt vmcnt(" #n ")" ::: "memory")
; #define PG8_WAIT_L(n) asm volatile("s_waitcnt lgkmcnt(" #n ")" ::: "memory")
; #define PG8_BAR __builtin_amdgcn_s_barrier()
; #define PG8_SCHED __builtin_amdgcn_sched_barrier(0)
; template <class Epi, class Sched, bool ALIGN_EPI = false, bool SP2 = false>
; __device__ __forceinline__ void gemm_phase(PG8_LAS unsigned char* lds, const Gemm g, const Sched& S, const Epi& E) {
;     ...
;         const char* nA = has_next ? PG8_ABASE(nxt) : cA; const char* nB = has_next ? PG8_BBASE(nxt) : cB;
;         for (int t = 0; t < nt; t += 2) {
;             const bool last = (t == nt - 2);
;             const char* a1 = cA + (size_t)(t + 1) * kstepA;
;             const char* a2 = last ? nA : cA + (size_t)(t + 2) * kstepA; const char* b2 = last ? nB : cB + (size_t)(t + 2) * kstep;
;             const char* a3 = a2 + kstepA; const char* b3 = b2 + kstep;
;             if (last && has_next) S.a_ready(nxt);
;             if constexpr (SP2) {
;             PG8_LDB(B0, 0, 0); PG8_LDB(B1, 0, 1); PG8_SCHED; PG8_LDA(At, 0, 0); PG8_STAGE(PG8_SA(1, 1), a1 + hstep, voffA);
;             PG8_WAIT_V(8); PG8_WAIT_L(0); PG8_BAR; PG8_MMA(0, 0, At, B0); PG8_MMA(0, 1, At, B1); PG8_BAR; PG8_SCHED;
;             if constexpr (Epi::PREFETCH) { if (t == tpf) E.prefetch(cur, wid, lane); }
;             PG8_LDA(At, 0, 1); PG8_STAGE(PG8_SB(0, 0), b2, voffB); PG8_STAGE(PG8_SB(0, 1), b2 + hstep, voffB); PG8_STAGE(PG8_SA(0, 0), a2, voffA);
;             PG8_WAIT_V(8); PG8_WAIT_L(0); PG8_BAR; PG8_MMA(1, 0, At, B0); PG8_MMA(1, 1, At, B1); PG8_BAR; PG8_SCHED;
.LBB0_837:
	s_ashr_i32 s29, s28, 31
	s_lshl_b64 s[30:31], s[28:29], 19
	s_add_u32 s30, s46, s30
	s_addc_u32 s31, s47, s31
	s_and_b64 s[34:35], s[2:3], exec
	s_cselect_b32 s1, s31, s5
	s_cselect_b32 s29, s30, s4
	s_ashr_i32 s27, s26, 31
	s_lshl_b64 s[34:35], s[26:27], 19
	s_add_u32 s34, s48, s34
	s_addc_u32 s35, s49, s35
	s_and_b64 s[36:37], s[2:3], exec
	s_cselect_b32 s27, s35, s7
	s_cselect_b32 s38, s34, s6
	s_add_u32 s4, s4, 0x40080
	s_addc_u32 s5, s5, 0
	s_add_u32 s39, s6, 0x100
	s_addc_u32 s40, s7, 0
	s_mov_b32 s41, -2
	s_waitcnt lgkmcnt(0)
	ds_read_b128 v[50:53], v214
	ds_read_b128 v[54:57], v214 offset:1024
	ds_read_b128 v[66:69], v214 offset:2048
	ds_read_b128 v[70:73], v214 offset:3072
	ds_read_b128 v[146:149], v215
	ds_read_b128 v[150:153], v215 offset:1024
	ds_read_b128 v[172:175], v215 offset:2048
	ds_read_b128 v[176:179], v215 offset:3072
	s_add_u32 s6, s4, 0xfffc0080
	s_addc_u32 s7, s5, -1
	s_cmp_eq_u32 s41, 12
	s_cselect_b32 s37, s1, s7
	s_cselect_b32 s36, s29, s6
	s_cselect_b32 s7, s27, s40
	s_cselect_b32 s6, s38, s39
	v_lshl_add_u64 v[218:219], s[4:5], 0, v[164:165]
	s_add_i32 m0, s51, 0xc000
	ds_read_b128 v[180:183], v216
	ds_read_b128 v[184:187], v216 offset:1024
	ds_read_b128 v[188:191], v216 offset:2048
	ds_read_b128 v[192:195], v216 offset:3072
	ds_read_b128 v[196:199], v216 offset:4096
	ds_read_b128 v[200:203], v216 offset:5120
	ds_read_b128 v[204:207], v216 offset:6144
	ds_read_b128 v[208:211], v216 offset:7168
	global_load_lds_dwordx4 v[218:219], off
	v_lshl_add_u64 v[218:219], s[4:5], 0, v[166:167]
	s_add_i32 m0, s51, 0xe000
	s_nop 0
	global_load_lds_dwordx4 v[218:219], off
	s_waitcnt vmcnt(8)
	s_waitcnt lgkmcnt(0)
	s_barrier
	s_setprio 1
	v_mfma_f32_16x16x32_bf16 v[142:145], v[50:53], v[180:183], 0
	v_mfma_f32_16x16x32_bf16 v[138:141], v[66:69], v[180:183], 0
	v_mfma_f32_16x16x32_bf16 v[126:129], v[50:53], v[188:191], 0
	v_mfma_f32_16x16x32_bf16 v[122:125], v[66:69], v[188:191], 0
	v_mfma_f32_16x16x32_bf16 v[110:113], v[50:53], v[196:199], 0
	v_mfma_f32_16x16x32_bf16 v[106:109], v[66:69], v[196:199], 0
	v_mfma_f32_16x16x32_bf16 v[94:97], v[50:53], v[204:207], 0
	v_mfma_f32_16x16x32_bf16 v[90:93], v[66:69], v[204:207], 0
	v_mfma_f32_16x16x32_bf16 v[142:145], v[54:57], v[184:187], v[142:145]
	v_mfma_f32_16x16x32_bf16 v[138:141], v[70:73], v[184:187], v[138:141]
	v_mfma_f32_16x16x32_bf16 v[126:129], v[54:57], v[192:195], v[126:129]
	v_mfma_f32_16x16x32_bf16 v[122:125], v[70:73], v[192:195], v[122:125]
	v_mfma_f32_16x16x32_bf16 v[110:113], v[54:57], v[200:203], v[110:113]
	v_mfma_f32_16x16x32_bf16 v[106:109], v[70:73], v[200:203], v[106:109]
	v_mfma_f32_16x16x32_bf16 v[94:97], v[54:57], v[208:211], v[94:97]
	v_mfma_f32_16x16x32_bf16 v[90:93], v[70:73], v[208:211], v[90:93]
	v_mfma_f32_16x16x32_bf16 v[134:137], v[146:149], v[180:183], 0
	v_mfma_f32_16x16x32_bf16 v[130:133], v[172:175], v[180:183], 0
	v_mfma_f32_16x16x32_bf16 v[118:121], v[146:149], v[188:191], 0
	v_mfma_f32_16x16x32_bf16 v[114:117], v[172:175], v[188:191], 0
	v_mfma_f32_16x16x32_bf16 v[102:105], v[146:149], v[196:199], 0
	v_mfma_f32_16x16x32_bf16 v[98:101], v[172:175], v[196:199], 0
	v_mfma_f32_16x16x32_bf16 v[86:89], v[146:149], v[204:207], 0
	v_mfma_f32_16x16x32_bf16 v[82:85], v[172:175], v[204:207], 0
	v_mfma_f32_16x16x32_bf16 v[134:137], v[150:153], v[184:187], v[134:137]
	v_mfma_f32_16x16x32_bf16 v[130:133], v[176:179], v[184:187], v[130:133]
	v_mfma_f32_16x16x32_bf16 v[118:121], v[150:153], v[192:195], v[118:121]
	v_mfma_f32_16x16x32_bf16 v[114:117], v[176:179], v[192:195], v[114:117]
	v_mfma_f32_16x16x32_bf16 v[102:105], v[150:153], v[200:203], v[102:105]
	v_mfma_f32_16x16x32_bf16 v[98:101], v[176:179], v[200:203], v[98:101]
	v_mfma_f32_16x16x32_bf16 v[86:89], v[150:153], v[208:211], v[86:89]
	v_mfma_f32_16x16x32_bf16 v[82:85], v[176:179], v[208:211], v[82:85]
	s_setprio 0
	s_barrier
	s_add_i32 s42, s68, s50
	v_lshl_add_u64 v[218:219], s[6:7], 0, v[156:157]
	s_mov_b32 m0, s42
	ds_read_b128 v[180:183], v216 offset:16384
	ds_read_b128 v[184:187], v216 offset:17408
	ds_read_b128 v[188:191], v216 offset:18432
	ds_read_b128 v[192:195], v216 offset:19456
	ds_read_b128 v[196:199], v216 offset:20480
	ds_read_b128 v[200:203], v216 offset:21504
	ds_read_b128 v[204:207], v216 offset:22528
	ds_read_b128 v[208:211], v216 offset:23552
	global_load_lds_dwordx4 v[218:219], off
	s_add_i32 m0, s42, 0x2000
	s_add_u32 s42, s6, 0x40000
	v_lshl_add_u64 v[222:223], s[6:7], 0, v[160:161]
	s_addc_u32 s43, s7, 0
	s_add_i32 s44, s69, s50
	global_load_lds_dwordx4 v[222:223], off
	v_lshl_add_u64 v[224:225], s[42:43], 0, v[156:157]
	s_mov_b32 m0, s44
	v_lshl_add_u64 v[226:227], s[36:37], 0, v[158:159]
	global_load_lds_dwordx4 v[224:225], off
	v_lshl_add_u64 v[224:225], s[42:43], 0, v[160:161]
	s_add_i32 m0, s44, 0x2000
	s_nop 0
	global_load_lds_dwordx4 v[224:225], off
	v_lshl_add_u64 v[224:225], s[36:37], 0, v[154:155]
	s_mov_b32 m0, s51
	s_nop 0
	global_load_lds_dwordx4 v[224:225], off
	s_mov_b32 m0, s52
	s_nop 0
	global_load_lds_dwordx4 v[226:227], off
	s_waitcnt vmcnt(8)
	s_waitcnt lgkmcnt(0)
	s_barrier
; #define PG8_STAGE(bufoff, gbase, voff) do { _Pragma("unroll") for (int _i = 0; _i < 2; ++_i) \
;         __builtin_amdgcn_global_load_lds((const unsigned*)((const char*)(gbase) + (voff)[_i]), (PG8_LAS unsigned*)(lds + (bufoff) + ldsw + _i * 8192), 16, 0, 0); } while (0)
; #define PG8_LDA(dst, b, h) do { _Pragma("unroll") for (int m = 0; m < 4; ++m) _Pragma("unroll") for (int k = 0; k < 2; ++k) dst[m][k] = *(const PG8_LAS bf16x8*)(lds + PG8_SA(b, h) + aoff + m * 2048 + k * 1024); } while (0)
; #define PG8_LDB(dst, b, h) do { _Pragma("unroll") for (int n = 0; n < 2; ++n) _Pragma("unroll") for (int k = 0; k < 2; ++k) dst[n][k] = *(const PG8_LAS bf16x8*)(lds + PG8_SB(b, h) + boff + n * 2048 + k * 1024); } while (0)
; #define PG8_MMA(ai, bj, At, Bt) do { __builtin_amdgcn_s_setprio(1); _Pragma("unroll") for (int m = 0; m < 4; ++m) _Pragma("unroll") for (int n = 0; n < 2; ++n) _Pragma("unroll") for (int k = 0; k < 2; ++k) \
;         acc[ai][bj][m][n] = __builtin_amdgcn_mfma_f32_16x16x32_bf16(Bt[n][k], At[m][k], acc[ai][bj][m][n], 0, 0, 0); __builtin_amdgcn_s_setprio(0); } while (0)
; #define PG8_WAIT_V(n) asm volatile("s_waitcnt vmcnt(" #n ")" ::: "memory")
; #define PG8_WAIT_L(n) asm volatile("s_waitcnt lgkmcnt(" #n ")" ::: "memory")
; #define PG8_BAR __builtin_amdgcn_s_barrier()
; #define PG8_SCHED __builtin_amdgcn_sched_barrier(0)
;     __device__ __forceinline__ void prefetch(const Unit& u, int wid, int lane) const { epi_prefetch(scr, ssq, bias + (size_t)(u.pm >> 5) * NGU + u.pn * BM, u, wid, lane); }
; template <class Epi, class Sched, bool ALIGN_EPI = false, bool SP2 = false>
; __device__ __forceinline__ void gemm_phase(PG8_LAS unsigned char* lds, const Gemm g, const Sched& S, const Epi& E) {
;     ...
;             PG8_LDB(B0, 0, 0); PG8_LDB(B1, 0, 1); PG8_SCHED; PG8_LDA(At, 0, 0); PG8_STAGE(PG8_SA(1, 1), a1 + hstep, voffA);
;             PG8_WAIT_V(8); PG8_WAIT_L(0); PG8_BAR; PG8_MMA(0, 0, At, B0); PG8_MMA(0, 1, At, B1); PG8_BAR; PG8_SCHED;
;             if constexpr (Epi::PREFETCH) { if (t == tpf) E.prefetch(cur, wid, lane); }
;             PG8_LDA(At, 0, 1); PG8_STAGE(PG8_SB(0, 0), b2, voffB); PG8_STAGE(PG8_SB(0, 1), b2 + hstep, voffB); PG8_STAGE(PG8_SA(0, 0), a2, voffA);
;             PG8_WAIT_V(8); PG8_WAIT_L(0); PG8_BAR; PG8_MMA(1, 0, At, B0); PG8_MMA(1, 1, At, B1); PG8_BAR; PG8_SCHED;
	s_setprio 1
	v_mfma_f32_16x16x32_bf16 v[78:81], v[50:53], v[180:183], 0
	v_mfma_f32_16x16x32_bf16 v[74:77], v[66:69], v[180:183], 0
	v_mfma_f32_16x16x32_bf16 v[46:49], v[50:53], v[188:191], 0
	v_mfma_f32_16x16x32_bf16 v[42:45], v[66:69], v[188:191], 0
	v_mfma_f32_16x16x32_bf16 v[30:33], v[50:53], v[196:199], 0
	v_mfma_f32_16x16x32_bf16 v[26:29], v[66:69], v[196:199], 0
	v_mfma_f32_16x16x32_bf16 v[14:17], v[50:53], v[204:207], 0
	v_mfma_f32_16x16x32_bf16 v[10:13], v[66:69], v[204:207], 0
	v_mfma_f32_16x16x32_bf16 v[78:81], v[54:57], v[184:187], v[78:81]
	v_mfma_f32_16x16x32_bf16 v[74:77], v[70:73], v[184:187], v[74:77]
	v_mfma_f32_16x16x32_bf16 v[46:49], v[54:57], v[192:195], v[46:49]
	v_mfma_f32_16x16x32_bf16 v[42:45], v[70:73], v[192:195], v[42:45]
	v_mfma_f32_16x16x32_bf16 v[30:33], v[54:57], v[200:203], v[30:33]
	v_mfma_f32_16x16x32_bf16 v[26:29], v[70:73], v[200:203], v[26:29]
	v_mfma_f32_16x16x32_bf16 v[14:17], v[54:57], v[208:211], v[14:17]
	v_mfma_f32_16x16x32_bf16 v[10:13], v[70:73], v[208:211], v[10:13]
	v_mfma_f32_16x16x32_bf16 v[38:41], v[146:149], v[188:191], 0
	v_mfma_f32_16x16x32_bf16 v[34:37], v[172:175], v[188:191], 0
	v_mfma_f32_16x16x32_bf16 v[22:25], v[146:149], v[196:199], 0
	v_mfma_f32_16x16x32_bf16 v[18:21], v[172:175], v[196:199], 0
	v_mfma_f32_16x16x32_bf16 v[6:9], v[146:149], v[204:207], 0
	v_mfma_f32_16x16x32_bf16 v[2:5], v[172:175], v[204:207], 0
	v_mfma_f32_16x16x32_bf16 v[50:53], v[146:149], v[180:183], 0
	v_mfma_f32_16x16x32_bf16 v[54:57], v[172:175], v[180:183], 0
	v_mfma_f32_16x16x32_bf16 v[38:41], v[150:153], v[192:195], v[38:41]
	v_mfma_f32_16x16x32_bf16 v[34:37], v[176:179], v[192:195], v[34:37]
	v_mfma_f32_16x16x32_bf16 v[22:25], v[150:153], v[200:203], v[22:25]
	v_mfma_f32_16x16x32_bf16 v[18:21], v[176:179], v[200:203], v[18:21]
	v_mfma_f32_16x16x32_bf16 v[6:9], v[150:153], v[208:211], v[6:9]
	v_mfma_f32_16x16x32_bf16 v[2:5], v[176:179], v[208:211], v[2:5]
	v_mfma_f32_16x16x32_bf16 v[50:53], v[150:153], v[184:187], v[50:53]
	v_mfma_f32_16x16x32_bf16 v[54:57], v[176:179], v[184:187], v[54:57]
	s_setprio 0
	s_barrier
	s_branch .Lpz4_mid
.LBB0_838:
	ds_read_b128 v[50:53], v214
	ds_read_b128 v[54:57], v214 offset:1024
	ds_read_b128 v[66:69], v214 offset:2048
	ds_read_b128 v[70:73], v214 offset:3072
	ds_read_b128 v[146:149], v215
	ds_read_b128 v[150:153], v215 offset:1024
	ds_read_b128 v[172:175], v215 offset:2048
	ds_read_b128 v[176:179], v215 offset:3072
	s_add_u32 s6, s4, 0xfffc0080
	s_addc_u32 s7, s5, -1
	s_cmp_eq_u32 s41, 12
	s_cselect_b32 s37, s1, s7
	s_cselect_b32 s36, s29, s6
	s_cselect_b32 s7, s27, s40
	s_cselect_b32 s6, s38, s39
	v_lshl_add_u64 v[218:219], s[4:5], 0, v[164:165]
	s_add_i32 m0, s51, 0xc000
	ds_read_b128 v[180:183], v216
	ds_read_b128 v[184:187], v216 offset:1024
	ds_read_b128 v[188:191], v216 offset:2048
	ds_read_b128 v[192:195], v216 offset:3072
	ds_read_b128 v[196:199], v216 offset:4096
	ds_read_b128 v[200:203], v216 offset:5120
	ds_read_b128 v[204:207], v216 offset:6144
	ds_read_b128 v[208:211], v216 offset:7168
	global_load_lds_dwordx4 v[218:219], off
	v_lshl_add_u64 v[218:219], s[4:5], 0, v[166:167]
	s_add_i32 m0, s51, 0xe000
	s_nop 0
	global_load_lds_dwordx4 v[218:219], off
	s_waitcnt vmcnt(8)
	s_waitcnt lgkmcnt(0)
	s_barrier
	s_setprio 1
	v_mfma_f32_16x16x32_bf16 v[142:145], v[50:53], v[180:183], v[142:145]
	v_mfma_f32_16x16x32_bf16 v[138:141], v[66:69], v[180:183], v[138:141]
	v_mfma_f32_16x16x32_bf16 v[126:129], v[50:53], v[188:191], v[126:129]
	v_mfma_f32_16x16x32_bf16 v[122:125], v[66:69], v[188:191], v[122:125]
	v_mfma_f32_16x16x32_bf16 v[110:113], v[50:53], v[196:199], v[110:113]
	v_mfma_f32_16x16x32_bf16 v[106:109], v[66:69], v[196:199], v[106:109]
	v_mfma_f32_16x16x32_bf16 v[94:97], v[50:53], v[204:207], v[94:97]
	v_mfma_f32_16x16x32_bf16 v[90:93], v[66:69], v[204:207], v[90:93]
	v_mfma_f32_16x16x32_bf16 v[142:145], v[54:57], v[184:187], v[142:145]
	v_mfma_f32_16x16x32_bf16 v[138:141], v[70:73], v[184:187], v[138:141]
	v_mfma_f32_16x16x32_bf16 v[126:129], v[54:57], v[192:195], v[126:129]
	v_mfma_f32_16x16x32_bf16 v[122:125], v[70:73], v[192:195], v[122:125]
	v_mfma_f32_16x16x32_bf16 v[110:113], v[54:57], v[200:203], v[110:113]
	v_mfma_f32_16x16x32_bf16 v[106:109], v[70:73], v[200:203], v[106:109]
	v_mfma_f32_16x16x32_bf16 v[94:97], v[54:57], v[208:211], v[94:97]
	v_mfma_f32_16x16x32_bf16 v[90:93], v[70:73], v[208:211], v[90:93]
	v_mfma_f32_16x16x32_bf16 v[134:137], v[146:149], v[180:183], v[134:137]
	v_mfma_f32_16x16x32_bf16 v[130:133], v[172:175], v[180:183], v[130:133]
	v_mfma_f32_16x16x32_bf16 v[118:121], v[146:149], v[188:191], v[118:121]
	v_mfma_f32_16x16x32_bf16 v[114:117], v[172:175], v[188:191], v[114:117]
	v_mfma_f32_16x16x32_bf16 v[102:105], v[146:149], v[196:199], v[102:105]
	v_mfma_f32_16x16x32_bf16 v[98:101], v[172:175], v[196:199], v[98:101]
	v_mfma_f32_16x16x32_bf16 v[86:89], v[146:149], v[204:207], v[86:89]
	v_mfma_f32_16x16x32_bf16 v[82:85], v[172:175], v[204:207], v[82:85]
	v_mfma_f32_16x16x32_bf16 v[134:137], v[150:153], v[184:187], v[134:137]
	v_mfma_f32_16x16x32_bf16 v[130:133], v[176:179], v[184:187], v[130:133]
	v_mfma_f32_16x16x32_bf16 v[118:121], v[150:153], v[192:195], v[118:121]
	v_mfma_f32_16x16x32_bf16 v[114:117], v[176:179], v[192:195], v[114:117]
	v_mfma_f32_16x16x32_bf16 v[102:105], v[150:153], v[200:203], v[102:105]
	v_mfma_f32_16x16x32_bf16 v[98:101], v[176:179], v[200:203], v[98:101]
	v_mfma_f32_16x16x32_bf16 v[86:89], v[150:153], v[208:211], v[86:89]
	v_mfma_f32_16x16x32_bf16 v[82:85], v[176:179], v[208:211], v[82:85]
	s_setprio 0
	s_barrier
; #define PG8_STAGE(bufoff, gbase, voff) do { _Pragma("unroll") for (int _i = 0; _i < 2; ++_i) \
;         __builtin_amdgcn_global_load_lds((const unsigned*)((const char*)(gbase) + (voff)[_i]), (PG8_LAS unsigned*)(lds + (bufoff) + ldsw + _i * 8192), 16, 0, 0); } while (0)
; #define PG8_LDA(dst, b, h) do { _Pragma("unroll") for (int m = 0; m < 4; ++m) _Pragma("unroll") for (int k = 0; k < 2; ++k) dst[m][k] = *(const PG8_LAS bf16x8*)(lds + PG8_SA(b, h) + aoff + m * 2048 + k * 1024); } while (0)
; #define PG8_LDB(dst, b, h) do { _Pragma("unroll") for (int n = 0; n < 2; ++n) _Pragma("unroll") for (int k = 0; k < 2; ++k) dst[n][k] = *(const PG8_LAS bf16x8*)(lds + PG8_SB(b, h) + boff + n * 2048 + k * 1024); } while (0)
; #define PG8_MMA(ai, bj, At, Bt) do { __builtin_amdgcn_s_setprio(1); _Pragma("unroll") for (int m = 0; m < 4; ++m) _Pragma("unroll") for (int n = 0; n < 2; ++n) _Pragma("unroll") for (int k = 0; k < 2; ++k) \
;         acc[ai][bj][m][n] = __builtin_amdgcn_mfma_f32_16x16x32_bf16(Bt[n][k], At[m][k], acc[ai][bj][m][n], 0, 0, 0); __builtin_amdgcn_s_setprio(0); } while (0)
; #define PG8_WAIT_V(n) asm volatile("s_waitcnt vmcnt(" #n ")" ::: "memory")
; #define PG8_WAIT_L(n) asm volatile("s_waitcnt lgkmcnt(" #n ")" ::: "memory")
; #define PG8_BAR __builtin_amdgcn_s_barrier()
; #define PG8_SCHED __builtin_amdgcn_sched_barrier(0)
; template <class Epi, class Sched, bool ALIGN_EPI = false, bool SP2 = false>
; __device__ __forceinline__ void gemm_phase(PG8_LAS unsigned char* lds, const Gemm g, const Sched& S, const Epi& E) {
;     ...
;             PG8_LDA(At, 0, 1); PG8_STAGE(PG8_SB(0, 0), b2, voffB); PG8_STAGE(PG8_SB(0, 1), b2 + hstep, voffB); PG8_STAGE(PG8_SA(0, 0), a2, voffA);
;             PG8_WAIT_V(8); PG8_WAIT_L(0); PG8_BAR; PG8_MMA(1, 0, At, B0); PG8_MMA(1, 1, At, B1); PG8_BAR; PG8_SCHED;
;             PG8_LDB(B0, 1, 0); PG8_LDB(B1, 1, 1); PG8_SCHED; PG8_LDA(At, 1, 0); PG8_STAGE(PG8_SA(0, 1), a2 + hstep, voffA);
;             PG8_WAIT_V(8); PG8_WAIT_L(0); PG8_BAR; PG8_MMA(0, 0, At, B0); PG8_MMA(0, 1, At, B1); PG8_BAR; PG8_SCHED;
	s_add_i32 s42, s68, s50
	v_lshl_add_u64 v[218:219], s[6:7], 0, v[156:157]
	s_mov_b32 m0, s42
	ds_read_b128 v[180:183], v216 offset:16384
	ds_read_b128 v[184:187], v216 offset:17408
	ds_read_b128 v[188:191], v216 offset:18432
	ds_read_b128 v[192:195], v216 offset:19456
	ds_read_b128 v[196:199], v216 offset:20480
	ds_read_b128 v[200:203], v216 offset:21504
	ds_read_b128 v[204:207], v216 offset:22528
	ds_read_b128 v[208:211], v216 offset:23552
	global_load_lds_dwordx4 v[218:219], off
	s_add_i32 m0, s42, 0x2000
	s_add_u32 s42, s6, 0x40000
	v_lshl_add_u64 v[222:223], s[6:7], 0, v[160:161]
	s_addc_u32 s43, s7, 0
	s_add_i32 s44, s69, s50
	global_load_lds_dwordx4 v[222:223], off
	v_lshl_add_u64 v[224:225], s[42:43], 0, v[156:157]
	s_mov_b32 m0, s44
	v_lshl_add_u64 v[226:227], s[36:37], 0, v[158:159]
	global_load_lds_dwordx4 v[224:225], off
	v_lshl_add_u64 v[224:225], s[42:43], 0, v[160:161]
	s_add_i32 m0, s44, 0x2000
	s_nop 0
	global_load_lds_dwordx4 v[224:225], off
	v_lshl_add_u64 v[224:225], s[36:37], 0, v[154:155]
	s_mov_b32 m0, s51
	s_nop 0
	global_load_lds_dwordx4 v[224:225], off
	s_mov_b32 m0, s52
	s_nop 0
	global_load_lds_dwordx4 v[226:227], off
	s_waitcnt vmcnt(8)
	s_waitcnt lgkmcnt(0)
	s_barrier
	s_setprio 1
	v_mfma_f32_16x16x32_bf16 v[78:81], v[50:53], v[180:183], v[78:81]
	v_mfma_f32_16x16x32_bf16 v[74:77], v[66:69], v[180:183], v[74:77]
	v_mfma_f32_16x16x32_bf16 v[46:49], v[50:53], v[188:191], v[46:49]
	v_mfma_f32_16x16x32_bf16 v[42:45], v[66:69], v[188:191], v[42:45]
	v_mfma_f32_16x16x32_bf16 v[30:33], v[50:53], v[196:199], v[30:33]
	v_mfma_f32_16x16x32_bf16 v[26:29], v[66:69], v[196:199], v[26:29]
	v_mfma_f32_16x16x32_bf16 v[14:17], v[50:53], v[204:207], v[14:17]
	v_mfma_f32_16x16x32_bf16 v[10:13], v[66:69], v[204:207], v[10:13]
	v_mfma_f32_16x16x32_bf16 v[78:81], v[54:57], v[184:187], v[78:81]
	v_mfma_f32_16x16x32_bf16 v[74:77], v[70:73], v[184:187], v[74:77]
	v_mfma_f32_16x16x32_bf16 v[46:49], v[54:57], v[192:195], v[46:49]
	v_mfma_f32_16x16x32_bf16 v[42:45], v[70:73], v[192:195], v[42:45]
	v_mfma_f32_16x16x32_bf16 v[30:33], v[54:57], v[200:203], v[30:33]
	v_mfma_f32_16x16x32_bf16 v[26:29], v[70:73], v[200:203], v[26:29]
	v_mfma_f32_16x16x32_bf16 v[14:17], v[54:57], v[208:211], v[14:17]
	v_mfma_f32_16x16x32_bf16 v[10:13], v[70:73], v[208:211], v[10:13]
	v_mfma_f32_16x16x32_bf16 v[38:41], v[146:149], v[188:191], v[38:41]
	v_mfma_f32_16x16x32_bf16 v[34:37], v[172:175], v[188:191], v[34:37]
	v_mfma_f32_16x16x32_bf16 v[22:25], v[146:149], v[196:199], v[22:25]
	v_mfma_f32_16x16x32_bf16 v[18:21], v[172:175], v[196:199], v[18:21]
	v_mfma_f32_16x16x32_bf16 v[6:9], v[146:149], v[204:207], v[6:9]
	v_mfma_f32_16x16x32_bf16 v[2:5], v[172:175], v[204:207], v[2:5]
	v_mfma_f32_16x16x32_bf16 v[50:53], v[146:149], v[180:183], v[62:65]
	v_mfma_f32_16x16x32_bf16 v[54:57], v[172:175], v[180:183], v[58:61]
	v_mfma_f32_16x16x32_bf16 v[38:41], v[150:153], v[192:195], v[38:41]
	v_mfma_f32_16x16x32_bf16 v[34:37], v[176:179], v[192:195], v[34:37]
	v_mfma_f32_16x16x32_bf16 v[22:25], v[150:153], v[200:203], v[22:25]
	v_mfma_f32_16x16x32_bf16 v[18:21], v[176:179], v[200:203], v[18:21]
	v_mfma_f32_16x16x32_bf16 v[6:9], v[150:153], v[208:211], v[6:9]
	v_mfma_f32_16x16x32_bf16 v[2:5], v[176:179], v[208:211], v[2:5]
	v_mfma_f32_16x16x32_bf16 v[50:53], v[150:153], v[184:187], v[50:53]
	v_mfma_f32_16x16x32_bf16 v[54:57], v[176:179], v[184:187], v[54:57]
	s_setprio 0
	s_barrier
.Lpz4_mid:
	s_add_i32 s42, 0, 0x18000
	s_add_i32 s43, 0, 0x1c000
	v_add_u32_e32 v70, s42, v213
	v_add_u32_e32 v162, s43, v213
	ds_read_b128 v[58:61], v70
	ds_read_b128 v[62:65], v70 offset:1024
	ds_read_b128 v[66:69], v70 offset:2048
	ds_read_b128 v[70:73], v70 offset:3072
	ds_read_b128 v[146:149], v162
	ds_read_b128 v[150:153], v162 offset:1024
	ds_read_b128 v[172:175], v162 offset:2048
	ds_read_b128 v[176:179], v162 offset:3072
	s_add_u32 s36, s36, 0x40000
	s_addc_u32 s37, s37, 0
	s_mov_b32 m0, s53
	v_lshl_add_u64 v[228:229], s[36:37], 0, v[154:155]
	ds_read_b128 v[180:183], v216 offset:32768
	ds_read_b128 v[184:187], v216 offset:33792
	ds_read_b128 v[188:191], v216 offset:34816
	ds_read_b128 v[192:195], v216 offset:35840
	ds_read_b128 v[196:199], v216 offset:36864
	ds_read_b128 v[200:203], v216 offset:37888
	ds_read_b128 v[204:207], v216 offset:38912
	ds_read_b128 v[208:211], v216 offset:39936
	global_load_lds_dwordx4 v[228:229], off
	v_lshl_add_u64 v[228:229], s[36:37], 0, v[158:159]
	s_mov_b32 m0, s54
	s_nop 0
	global_load_lds_dwordx4 v[228:229], off
	s_waitcnt vmcnt(8)
	s_waitcnt lgkmcnt(0)
	s_barrier
; #define PG8_STAGE(bufoff, gbase, voff) do { _Pragma("unroll") for (int _i = 0; _i < 2; ++_i) \
;         __builtin_amdgcn_global_load_lds((const unsigned*)((const char*)(gbase) + (voff)[_i]), (PG8_LAS unsigned*)(lds + (bufoff) + ldsw + _i * 8192), 16, 0, 0); } while (0)
; #define PG8_WAIT_V(n) asm volatile("s_waitcnt vmcnt(" #n ")" ::: "memory")
; #define PG8_WAIT_L(n) asm volatile("s_waitcnt lgkmcnt(" #n ")" ::: "memory")
; template <class Epi, class Sched, bool ALIGN_EPI = false, bool SP2 = false>
; __device__ __forceinline__ void gemm_phase(PG8_LAS unsigned char* lds, const Gemm g, const Sched& S, const Epi& E) {
;     ...
;             PG8_WAIT_V(8); PG8_WAIT_L(0); PG8_BAR; PG8_MMA(0, 0, At, B0); PG8_MMA(0, 1, At, B1); PG8_BAR; PG8_SCHED;
;             PG8_LDA(At, 1, 1); PG8_STAGE(PG8_SB(1, 0), b3, voffB); PG8_STAGE(PG8_SB(1, 1), b3 + hstep, voffB); PG8_STAGE(PG8_SA(1, 0), a3, voffA);
;             PG8_WAIT_V(8); PG8_WAIT_L(0); PG8_BAR; PG8_MMA(1, 0, At, B0); PG8_MMA(1, 1, At, B1); PG8_BAR; PG8_SCHED;
;             } else {
;             PG8_LDB(B0, 0, 0); PG8_SCHED; PG8_LDA(At, 0, 0); PG8_STAGE(PG8_SA(1, 1), a1 + hstep, voffA);
;             PG8_WAIT_L(8); PG8_BAR; PG8_WAIT_L(0); PG8_MMA(0, 0, At, B0); PG8_BAR; PG8_SCHED;
;             PG8_LDB(B1, 0, 1); PG8_STAGE(PG8_SB(0, 0), b2, voffB);
;             PG8_BAR; PG8_WAIT_L(0); PG8_MMA(0, 1, At, B1); PG8_BAR;
;             PG8_LDA(At, 0, 1); PG8_STAGE(PG8_SA(0, 0), a2, voffA);
;             PG8_BAR; PG8_WAIT_L(0); PG8_MMA(1, 0, At, B0); PG8_BAR; PG8_SCHED;
;             PG8_STAGE(PG8_SB(0, 1), b2 + hstep, voffB);
;             PG8_WAIT_V(6); PG8_BAR; PG8_MMA(1, 1, At, B1); PG8_BAR;
;             PG8_LDB(B0, 1, 0); PG8_SCHED; PG8_LDA(At, 1, 0); PG8_STAGE(PG8_SA(0, 1), a2 + hstep, voffA);
;             PG8_WAIT_L(8); PG8_BAR; PG8_WAIT_L(0); PG8_MMA(0, 0, At, B0); PG8_BAR; PG8_SCHED;
;             PG8_LDB(B1, 1, 1); PG8_STAGE(PG8_SB(1, 0), b3, voffB);
;             PG8_BAR; PG8_WAIT_L(0); PG8_MMA(0, 1, At, B1); PG8_BAR;
;             PG8_LDA(At, 1, 1); PG8_STAGE(PG8_SA(1, 0), a3, voffA);
;             PG8_BAR; PG8_WAIT_L(0); PG8_MMA(1, 0, At, B0); PG8_BAR; PG8_SCHED;
;             PG8_STAGE(PG8_SB(1, 1), b3 + hstep, voffB);
;             PG8_WAIT_V(6); PG8_BAR; PG8_MMA(1, 1, At, B1); PG8_BAR;
;             }
;         }
;         if constexpr (ALIGN_EPI) { if (wr == 0) PG8_BAR; }
	s_setprio 1
	v_mfma_f32_16x16x32_bf16 v[142:145], v[58:61], v[180:183], v[142:145]
	v_mfma_f32_16x16x32_bf16 v[138:141], v[66:69], v[180:183], v[138:141]
	v_mfma_f32_16x16x32_bf16 v[126:129], v[58:61], v[188:191], v[126:129]
	v_mfma_f32_16x16x32_bf16 v[122:125], v[66:69], v[188:191], v[122:125]
	v_mfma_f32_16x16x32_bf16 v[110:113], v[58:61], v[196:199], v[110:113]
	v_mfma_f32_16x16x32_bf16 v[106:109], v[66:69], v[196:199], v[106:109]
	v_mfma_f32_16x16x32_bf16 v[94:97], v[58:61], v[204:207], v[94:97]
	v_mfma_f32_16x16x32_bf16 v[90:93], v[66:69], v[204:207], v[90:93]
	v_mfma_f32_16x16x32_bf16 v[142:145], v[62:65], v[184:187], v[142:145]
	v_mfma_f32_16x16x32_bf16 v[138:141], v[70:73], v[184:187], v[138:141]
	v_mfma_f32_16x16x32_bf16 v[126:129], v[62:65], v[192:195], v[126:129]
	v_mfma_f32_16x16x32_bf16 v[122:125], v[70:73], v[192:195], v[122:125]
	v_mfma_f32_16x16x32_bf16 v[110:113], v[62:65], v[200:203], v[110:113]
	v_mfma_f32_16x16x32_bf16 v[106:109], v[70:73], v[200:203], v[106:109]
	v_mfma_f32_16x16x32_bf16 v[94:97], v[62:65], v[208:211], v[94:97]
	v_mfma_f32_16x16x32_bf16 v[90:93], v[70:73], v[208:211], v[90:93]
	v_mfma_f32_16x16x32_bf16 v[134:137], v[146:149], v[180:183], v[134:137]
	v_mfma_f32_16x16x32_bf16 v[130:133], v[172:175], v[180:183], v[130:133]
	v_mfma_f32_16x16x32_bf16 v[118:121], v[146:149], v[188:191], v[118:121]
	v_mfma_f32_16x16x32_bf16 v[114:117], v[172:175], v[188:191], v[114:117]
	v_mfma_f32_16x16x32_bf16 v[102:105], v[146:149], v[196:199], v[102:105]
	v_mfma_f32_16x16x32_bf16 v[98:101], v[172:175], v[196:199], v[98:101]
	v_mfma_f32_16x16x32_bf16 v[86:89], v[146:149], v[204:207], v[86:89]
	v_mfma_f32_16x16x32_bf16 v[82:85], v[172:175], v[204:207], v[82:85]
	v_mfma_f32_16x16x32_bf16 v[134:137], v[150:153], v[184:187], v[134:137]
	v_mfma_f32_16x16x32_bf16 v[130:133], v[176:179], v[184:187], v[130:133]
	v_mfma_f32_16x16x32_bf16 v[118:121], v[150:153], v[192:195], v[118:121]
	v_mfma_f32_16x16x32_bf16 v[114:117], v[176:179], v[192:195], v[114:117]
	v_mfma_f32_16x16x32_bf16 v[102:105], v[150:153], v[200:203], v[102:105]
	v_mfma_f32_16x16x32_bf16 v[98:101], v[176:179], v[200:203], v[98:101]
	v_mfma_f32_16x16x32_bf16 v[86:89], v[150:153], v[208:211], v[86:89]
	v_mfma_f32_16x16x32_bf16 v[82:85], v[176:179], v[208:211], v[82:85]
	s_setprio 0
	s_barrier
	s_add_i32 s36, s42, s50
	v_lshl_add_u64 v[218:219], v[218:219], 0, s[20:21]
	s_mov_b32 m0, s36
	ds_read_b128 v[180:183], v216 offset:49152
	ds_read_b128 v[184:187], v216 offset:50176
	ds_read_b128 v[188:191], v216 offset:51200
	ds_read_b128 v[192:195], v216 offset:52224
	ds_read_b128 v[196:199], v216 offset:53248
	ds_read_b128 v[200:203], v216 offset:54272
	ds_read_b128 v[204:207], v216 offset:55296
	ds_read_b128 v[208:211], v216 offset:56320
	global_load_lds_dwordx4 v[218:219], off
	s_add_i32 m0, s36, 0x2000
	s_add_u32 s6, s6, 0x40080
	v_lshl_add_u64 v[218:219], v[222:223], 0, s[20:21]
	s_addc_u32 s7, s7, 0
	s_add_i32 s36, s43, s50
	global_load_lds_dwordx4 v[218:219], off
	v_lshl_add_u64 v[218:219], s[6:7], 0, v[156:157]
	s_mov_b32 m0, s36
	s_nop 0
	global_load_lds_dwordx4 v[218:219], off
	v_lshl_add_u64 v[218:219], s[6:7], 0, v[160:161]
	s_add_i32 m0, s36, 0x2000
	s_nop 0
	global_load_lds_dwordx4 v[218:219], off
	v_lshl_add_u64 v[218:219], v[224:225], 0, s[20:21]
	s_mov_b32 m0, s63
	s_nop 0
	global_load_lds_dwordx4 v[218:219], off
	v_lshl_add_u64 v[218:219], v[226:227], 0, s[20:21]
	s_mov_b32 m0, s64
	s_nop 0
	global_load_lds_dwordx4 v[218:219], off
	s_waitcnt vmcnt(8)
	s_waitcnt lgkmcnt(0)
	s_barrier
	s_setprio 1
	v_mfma_f32_16x16x32_bf16 v[78:81], v[58:61], v[180:183], v[78:81]
	v_mfma_f32_16x16x32_bf16 v[74:77], v[66:69], v[180:183], v[74:77]
	v_mfma_f32_16x16x32_bf16 v[46:49], v[58:61], v[188:191], v[46:49]
	v_mfma_f32_16x16x32_bf16 v[42:45], v[66:69], v[188:191], v[42:45]
	v_mfma_f32_16x16x32_bf16 v[30:33], v[58:61], v[196:199], v[30:33]
	v_mfma_f32_16x16x32_bf16 v[26:29], v[66:69], v[196:199], v[26:29]
	v_mfma_f32_16x16x32_bf16 v[14:17], v[58:61], v[204:207], v[14:17]
	v_mfma_f32_16x16x32_bf16 v[10:13], v[66:69], v[204:207], v[10:13]
	v_mfma_f32_16x16x32_bf16 v[78:81], v[62:65], v[184:187], v[78:81]
	v_mfma_f32_16x16x32_bf16 v[74:77], v[70:73], v[184:187], v[74:77]
	v_mfma_f32_16x16x32_bf16 v[46:49], v[62:65], v[192:195], v[46:49]
	v_mfma_f32_16x16x32_bf16 v[42:45], v[70:73], v[192:195], v[42:45]
	v_mfma_f32_16x16x32_bf16 v[30:33], v[62:65], v[200:203], v[30:33]
	v_mfma_f32_16x16x32_bf16 v[26:29], v[70:73], v[200:203], v[26:29]
	v_mfma_f32_16x16x32_bf16 v[14:17], v[62:65], v[208:211], v[14:17]
	v_mfma_f32_16x16x32_bf16 v[10:13], v[70:73], v[208:211], v[10:13]
	v_mfma_f32_16x16x32_bf16 v[50:53], v[146:149], v[180:183], v[50:53]
	v_mfma_f32_16x16x32_bf16 v[62:65], v[150:153], v[184:187], v[50:53]
	v_mfma_f32_16x16x32_bf16 v[50:53], v[172:175], v[180:183], v[54:57]
	v_mfma_f32_16x16x32_bf16 v[38:41], v[146:149], v[188:191], v[38:41]
	v_mfma_f32_16x16x32_bf16 v[34:37], v[172:175], v[188:191], v[34:37]
	v_mfma_f32_16x16x32_bf16 v[22:25], v[146:149], v[196:199], v[22:25]
	v_mfma_f32_16x16x32_bf16 v[18:21], v[172:175], v[196:199], v[18:21]
	v_mfma_f32_16x16x32_bf16 v[6:9], v[146:149], v[204:207], v[6:9]
	v_mfma_f32_16x16x32_bf16 v[2:5], v[172:175], v[204:207], v[2:5]
	v_mfma_f32_16x16x32_bf16 v[58:61], v[176:179], v[184:187], v[50:53]
	v_mfma_f32_16x16x32_bf16 v[38:41], v[150:153], v[192:195], v[38:41]
	v_mfma_f32_16x16x32_bf16 v[34:37], v[176:179], v[192:195], v[34:37]
	v_mfma_f32_16x16x32_bf16 v[22:25], v[150:153], v[200:203], v[22:25]
	v_mfma_f32_16x16x32_bf16 v[18:21], v[176:179], v[200:203], v[18:21]
	v_mfma_f32_16x16x32_bf16 v[6:9], v[150:153], v[208:211], v[6:9]
	v_mfma_f32_16x16x32_bf16 v[2:5], v[176:179], v[208:211], v[2:5]
	s_setprio 0
	s_barrier
	s_add_i32 s41, s41, 2
	s_add_u32 s4, s4, 0x100
	s_addc_u32 s5, s5, 0
	s_add_u32 s39, s39, 0x100
	s_addc_u32 s40, s40, 0
	s_cmp_gt_u32 s41, 13
	s_cbranch_scc0 .LBB0_838
	s_and_b64 vcc, exec, s[22:23]
	s_cbranch_vccz .LBB0_841
	s_barrier

;     __host__ __device__ bool next(int i, Unit& u) const { if (!b.next(i >> 1, u)) return false; u.sel = i & 1; return true; }
; #define PG8_STAGE(bufoff, gbase, voff) do { _Pragma("unroll") for (int _i = 0; _i < 2; ++_i) \
;         __builtin_amdgcn_global_load_lds((const unsigned*)((const char*)(gbase) + (voff)[_i]), (PG8_LAS unsigned*)(lds + (bufoff) + ldsw + _i * 8192), 16, 0, 0); } while (0)
; #define PG8_LDA(dst, b, h) do { _Pragma("unroll") for (int m = 0; m < 4; ++m) _Pragma("unroll") for (int k = 0; k < 2; ++k) dst[m][k] = *(const PG8_LAS bf16x8*)(lds + PG8_SA(b, h) + aoff + m * 2048 + k * 1024); } while (0)
; #define PG8_WAIT_V(n) asm volatile("s_waitcnt vmcnt(" #n ")" ::: "memory")
;     __host__ __device__ bool next(int i, Unit& u) const {
;         const long L = (long)i * G + c; if (L >= nwg) return false;
;         int wgid = (int)L; { const int q = nwg / NXCD, r = nwg % NXCD, xcd = wgid % NXCD, off = wgid / NXCD; wgid = (xcd < r ? xcd * (q + 1) : r * (q + 1) + (xcd - r) * q) + off; }
;         const int nig = WGM * nN, gid = wgid / nig, fm = gid * WGM, gsz = (nM - fm) < WGM ? (nM - fm) : WGM;
;         u.pm = fm + ((wgid % nig) % gsz); u.pn = (wgid % nig) / gsz; u.sel = 0; return true;
; template <class Epi, class Sched, bool ALIGN_EPI = false, bool SP2 = false>
; __device__ __forceinline__ void gemm_phase(PG8_LAS unsigned char* lds, const Gemm g, const Sched& S, const Epi& E) {
;     ...
;         const bool has_next = S.next(ui + 1, nxt);
;         const char* nA = has_next ? PG8_ABASE(nxt) : cA; const char* nB = has_next ? PG8_BBASE(nxt) : cB;
;         for (int t = 0; t < nt; t += 2) {
;             const bool last = (t == nt - 2);
;             const char* a1 = cA + (size_t)(t + 1) * kstepA;
;             const char* a2 = last ? nA : cA + (size_t)(t + 2) * kstepA; const char* b2 = last ? nB : cB + (size_t)(t + 2) * kstep;
;             const char* a3 = a2 + kstepA; const char* b3 = b2 + kstep;
;             if (last && has_next) S.a_ready(nxt);
;             if constexpr (SP2) {
;             PG8_LDB(B0, 0, 0); PG8_LDB(B1, 0, 1); PG8_SCHED; PG8_LDA(At, 0, 0); PG8_STAGE(PG8_SA(1, 1), a1 + hstep, voffA);
;             PG8_WAIT_V(8); PG8_WAIT_L(0); PG8_BAR; PG8_MMA(0, 0, At, B0); PG8_MMA(0, 1, At, B1); PG8_BAR; PG8_SCHED;
;             if constexpr (Epi::PREFETCH) { if (t == tpf) E.prefetch(cur, wid, lane); }
.LBB0_982:
	s_ashr_i32 s29, s28, 31
	s_lshl_b32 s34, s34, 8
	s_lshl_b64 s[36:37], s[28:29], 14
	s_ashr_i32 s29, s28, 5
	s_ashr_i32 s35, s34, 31
	s_add_u32 s36, s10, s36
	s_mul_hi_i32 s38, s29, 0x5800
	s_mulk_i32 s29, 0x5800
	s_addc_u32 s37, s69, s37
	s_add_u32 s29, s62, s29
	s_addc_u32 s42, s63, s38
	s_lshl_b64 s[38:39], s[34:35], 2
	s_add_u32 s38, s29, s38
	s_addc_u32 s39, s42, s39
	s_add_u32 s29, s40, 0x100
	v_lshl_add_u64 v[188:189], s[30:31], 0, v[180:181]
	v_lshl_add_u64 v[190:191], s[30:31], 0, v[182:183]
	s_addc_u32 s35, s41, 0
	s_mov_b32 s83, 0
	s_mov_b64 s[40:41], 0
	ds_read_b128 v[154:157], v195
	ds_read_b128 v[158:161], v195 offset:1024
	ds_read_b128 v[162:165], v195 offset:2048
	ds_read_b128 v[166:169], v195 offset:3072
	ds_read_b128 v[138:141], v196
	ds_read_b128 v[142:145], v196 offset:1024
	ds_read_b128 v[146:149], v196 offset:2048
	ds_read_b128 v[150:153], v196 offset:3072
	v_lshl_add_u64 v[98:99], v[188:189], 0, s[40:41]
	s_add_i32 m0, s54, 0xc000
	ds_read_b128 v[200:203], v197
	ds_read_b128 v[204:207], v197 offset:1024
	ds_read_b128 v[208:211], v197 offset:2048
	ds_read_b128 v[212:215], v197 offset:3072
	ds_read_b128 v[216:219], v197 offset:4096
	ds_read_b128 v[220:223], v197 offset:5120
	ds_read_b128 v[224:227], v197 offset:6144
	ds_read_b128 v[228:231], v197 offset:7168
	global_load_lds_dwordx4 v[98:99], off
	v_lshl_add_u64 v[98:99], v[190:191], 0, s[40:41]
	s_add_i32 m0, s54, 0xe000
	s_nop 0
	global_load_lds_dwordx4 v[98:99], off
	s_add_i32 s11, s11, 1
	s_mul_i32 s2, s11, s68
	s_mul_hi_u32 s3, s11, s33
	s_add_i32 s3, s3, s2
	s_mul_i32 s2, s11, s33
	s_add_u32 s24, s2, s87
	s_addc_u32 s25, s3, s52
	v_cmp_lt_i64_e64 s[2:3], s[24:25], v[184:185]
	s_ashr_i32 s20, s24, 31
	s_lshr_b32 s20, s20, 29
	s_add_i32 s20, s24, s20
	s_ashr_i32 s21, s20, 3
	s_and_b32 s20, s20, -8
	s_sub_i32 s20, s24, s20
	s_cmp_lt_i32 s20, 0
	s_cselect_b32 s22, s53, 0x160
	s_mul_i32 s20, s20, s22
	s_add_i32 s20, s20, s21
	s_mul_hi_i32 s21, s20, 0x2e8ba2e9
	s_lshr_b32 s22, s21, 31
	s_ashr_i32 s21, s21, 3
	s_add_i32 s21, s21, s22
	s_lshl_b32 s22, s21, 1
	s_mul_i32 s21, s21, 44
	s_sub_i32 s21, s20, s21
	s_lshr_b32 s20, s21, 1
	s_and_b32 s21, s21, 1
	s_add_i32 s22, s22, s21
	s_ashr_i32 s23, s22, 31
	s_lshl_b64 s[24:25], s[22:23], 19
	s_add_u32 s24, s47, s24
	s_addc_u32 s25, s48, s25
	s_and_b64 s[26:27], s[2:3], exec
	s_cselect_b32 s23, s25, s48
	s_cselect_b32 s81, s24, s47
	s_ashr_i32 s21, s20, 31
	s_lshl_b64 s[26:27], s[20:21], 19
	s_add_u32 s26, s49, s26
	s_addc_u32 s27, s50, s27
	s_and_b64 s[98:99], s[2:3], exec
	s_cselect_b32 s21, s27, s50
	s_cselect_b32 s82, s26, s49
	s_waitcnt vmcnt(8)
	s_waitcnt lgkmcnt(0)
	s_barrier
	s_setprio 1
	v_mfma_f32_16x16x32_bf16 v[98:101], v[154:157], v[200:203], 0
	v_mfma_f32_16x16x32_bf16 v[106:109], v[162:165], v[200:203], 0
	v_mfma_f32_16x16x32_bf16 v[118:121], v[154:157], v[208:211], 0
	v_mfma_f32_16x16x32_bf16 v[114:117], v[162:165], v[208:211], 0
	v_mfma_f32_16x16x32_bf16 v[94:97], v[154:157], v[216:219], 0
	v_mfma_f32_16x16x32_bf16 v[90:93], v[162:165], v[216:219], 0
	v_mfma_f32_16x16x32_bf16 v[78:81], v[154:157], v[224:227], 0
	v_mfma_f32_16x16x32_bf16 v[74:77], v[162:165], v[224:227], 0
	v_mfma_f32_16x16x32_bf16 v[98:101], v[158:161], v[204:207], v[98:101]
	v_mfma_f32_16x16x32_bf16 v[106:109], v[166:169], v[204:207], v[106:109]
	v_mfma_f32_16x16x32_bf16 v[118:121], v[158:161], v[212:215], v[118:121]
	v_mfma_f32_16x16x32_bf16 v[114:117], v[166:169], v[212:215], v[114:117]
	v_mfma_f32_16x16x32_bf16 v[94:97], v[158:161], v[220:223], v[94:97]
	v_mfma_f32_16x16x32_bf16 v[90:93], v[166:169], v[220:223], v[90:93]
	v_mfma_f32_16x16x32_bf16 v[78:81], v[158:161], v[228:231], v[78:81]
	v_mfma_f32_16x16x32_bf16 v[74:77], v[166:169], v[228:231], v[74:77]
	v_mfma_f32_16x16x32_bf16 v[126:129], v[138:141], v[200:203], 0
	v_mfma_f32_16x16x32_bf16 v[122:125], v[146:149], v[200:203], 0
	v_mfma_f32_16x16x32_bf16 v[110:113], v[138:141], v[208:211], 0
	v_mfma_f32_16x16x32_bf16 v[102:105], v[146:149], v[208:211], 0
	v_mfma_f32_16x16x32_bf16 v[86:89], v[138:141], v[216:219], 0
	v_mfma_f32_16x16x32_bf16 v[82:85], v[146:149], v[216:219], 0
	v_mfma_f32_16x16x32_bf16 v[70:73], v[138:141], v[224:227], 0
	v_mfma_f32_16x16x32_bf16 v[66:69], v[146:149], v[224:227], 0
	v_mfma_f32_16x16x32_bf16 v[126:129], v[142:145], v[204:207], v[126:129]
	v_mfma_f32_16x16x32_bf16 v[122:125], v[150:153], v[204:207], v[122:125]
	v_mfma_f32_16x16x32_bf16 v[110:113], v[142:145], v[212:215], v[110:113]
	v_mfma_f32_16x16x32_bf16 v[102:105], v[150:153], v[212:215], v[102:105]
	v_mfma_f32_16x16x32_bf16 v[86:89], v[142:145], v[220:223], v[86:89]
	v_mfma_f32_16x16x32_bf16 v[82:85], v[150:153], v[220:223], v[82:85]
	v_mfma_f32_16x16x32_bf16 v[70:73], v[142:145], v[228:231], v[70:73]
	v_mfma_f32_16x16x32_bf16 v[66:69], v[150:153], v[228:231], v[66:69]
	s_setprio 0
	s_barrier
	s_cmp_lg_u32 s46, s83
	s_cbranch_scc1 .Lpz5_a
	v_mov_b32_e32 v178, v194
	s_add_i32 m0, s79, 0x20000
	v_lshl_add_u64 v[130:131], s[36:37], 0, v[178:179]
	global_load_lds_dwordx4 v178, s[36:37]
	v_lshl_add_u64 v[130:131], v[130:131], 0, s[18:19]
	s_add_i32 m0, s79, 0x20400
	s_andn2_b64 vcc, exec, s[14:15]
	global_load_lds_dwordx4 v[130:131], off
	s_cbranch_vccnz .Lpz5_a
	v_lshl_add_u64 v[130:131], s[38:39], 0, v[178:179]
	s_add_i32 m0, 0, 0x24000
	s_nop 0
	global_load_lds_dwordx4 v[130:131], off
	s_branch .Lpz5_a
; #define PG8_STAGE(bufoff, gbase, voff) do { _Pragma("unroll") for (int _i = 0; _i < 2; ++_i) \
;         __builtin_amdgcn_global_load_lds((const unsigned*)((const char*)(gbase) + (voff)[_i]), (PG8_LAS unsigned*)(lds + (bufoff) + ldsw + _i * 8192), 16, 0, 0); } while (0)
; #define PG8_LDA(dst, b, h) do { _Pragma("unroll") for (int m = 0; m < 4; ++m) _Pragma("unroll") for (int k = 0; k < 2; ++k) dst[m][k] = *(const PG8_LAS bf16x8*)(lds + PG8_SA(b, h) + aoff + m * 2048 + k * 1024); } while (0)
; #define PG8_LDB(dst, b, h) do { _Pragma("unroll") for (int n = 0; n < 2; ++n) _Pragma("unroll") for (int k = 0; k < 2; ++k) dst[n][k] = *(const PG8_LAS bf16x8*)(lds + PG8_SB(b, h) + boff + n * 2048 + k * 1024); } while (0)
; #define PG8_MMA(ai, bj, At, Bt) do { __builtin_amdgcn_s_setprio(1); _Pragma("unroll") for (int m = 0; m < 4; ++m) _Pragma("unroll") for (int n = 0; n < 2; ++n) _Pragma("unroll") for (int k = 0; k < 2; ++k) \
;         acc[ai][bj][m][n] = __builtin_amdgcn_mfma_f32_16x16x32_bf16(Bt[n][k], At[m][k], acc[ai][bj][m][n], 0, 0, 0); __builtin_amdgcn_s_setprio(0); } while (0)
; #define PG8_WAIT_V(n) asm volatile("s_waitcnt vmcnt(" #n ")" ::: "memory")
; #define PG8_BAR __builtin_amdgcn_s_barrier()
; template <class Epi, class Sched, bool ALIGN_EPI = false, bool SP2 = false>
; __device__ __forceinline__ void gemm_phase(PG8_LAS unsigned char* lds, const Gemm g, const Sched& S, const Epi& E) {
;     ...
;             const char* a1 = cA + (size_t)(t + 1) * kstepA;
;             const char* a2 = last ? nA : cA + (size_t)(t + 2) * kstepA; const char* b2 = last ? nB : cB + (size_t)(t + 2) * kstep;
;             const char* a3 = a2 + kstepA; const char* b3 = b2 + kstep;
;             if (last && has_next) S.a_ready(nxt);
;             if constexpr (SP2) {
;             PG8_LDB(B0, 0, 0); PG8_LDB(B1, 0, 1); PG8_SCHED; PG8_LDA(At, 0, 0); PG8_STAGE(PG8_SA(1, 1), a1 + hstep, voffA);
;             PG8_WAIT_V(8); PG8_WAIT_L(0); PG8_BAR; PG8_MMA(0, 0, At, B0); PG8_MMA(0, 1, At, B1); PG8_BAR; PG8_SCHED;
;             if constexpr (Epi::PREFETCH) { if (t == tpf) E.prefetch(cur, wid, lane); }
;             PG8_LDA(At, 0, 1); PG8_STAGE(PG8_SB(0, 0), b2, voffB); PG8_STAGE(PG8_SB(0, 1), b2 + hstep, voffB); PG8_STAGE(PG8_SA(0, 0), a2, voffA);
;             PG8_WAIT_V(8); PG8_WAIT_L(0); PG8_BAR; PG8_MMA(1, 0, At, B0); PG8_MMA(1, 1, At, B1); PG8_BAR; PG8_SCHED;
.Lpz5_a:
	s_add_u32 s42, s30, s40
	s_addc_u32 s43, s31, s41
	s_add_u32 s42, s42, 0x100
	s_addc_u32 s43, s43, 0
	s_add_u32 s84, s29, s40
	s_addc_u32 s85, s35, s41
	s_cmpk_eq_i32 s40, 0x700
	s_cselect_b32 s45, s23, s43
	s_cselect_b32 s44, s81, s42
	s_cselect_b32 s43, s21, s85
	s_cselect_b32 s42, s82, s84
	s_mov_b32 m0, s55
	v_lshl_add_u64 v[232:233], s[42:43], 0, v[174:175]
	s_add_u32 s84, s42, 0x40000
	ds_read_b128 v[130:133], v197 offset:16384
	ds_read_b128 v[134:137], v197 offset:17408
	ds_read_b128 v[200:203], v197 offset:18432
	ds_read_b128 v[204:207], v197 offset:19456
	ds_read_b128 v[208:211], v197 offset:20480
	ds_read_b128 v[212:215], v197 offset:21504
	ds_read_b128 v[216:219], v197 offset:22528
	ds_read_b128 v[220:223], v197 offset:23552
	global_load_lds_dwordx4 v[232:233], off
	v_lshl_add_u64 v[234:235], s[42:43], 0, v[170:171]
	s_mov_b32 m0, s56
	s_addc_u32 s85, s43, 0
	global_load_lds_dwordx4 v[234:235], off
	v_lshl_add_u64 v[224:225], s[84:85], 0, v[174:175]
	s_mov_b32 m0, s57
	v_lshl_add_u64 v[236:237], s[44:45], 0, v[176:177]
	global_load_lds_dwordx4 v[224:225], off
	v_lshl_add_u64 v[224:225], s[84:85], 0, v[170:171]
	s_mov_b32 m0, s58
	v_lshl_add_u64 v[238:239], s[44:45], 0, v[172:173]
	global_load_lds_dwordx4 v[224:225], off
	s_mov_b32 m0, s54
	s_nop 0
	global_load_lds_dwordx4 v[236:237], off
	s_mov_b32 m0, s59
	s_nop 0
	global_load_lds_dwordx4 v[238:239], off
	s_waitcnt vmcnt(8)
	s_waitcnt lgkmcnt(0)
	s_barrier
	s_setprio 1
	v_mfma_f32_16x16x32_bf16 v[62:65], v[154:157], v[130:133], 0
	v_mfma_f32_16x16x32_bf16 v[58:61], v[162:165], v[130:133], 0
	v_mfma_f32_16x16x32_bf16 v[46:49], v[154:157], v[200:203], 0
	v_mfma_f32_16x16x32_bf16 v[42:45], v[162:165], v[200:203], 0
	v_mfma_f32_16x16x32_bf16 v[30:33], v[154:157], v[208:211], 0
	v_mfma_f32_16x16x32_bf16 v[26:29], v[162:165], v[208:211], 0
	v_mfma_f32_16x16x32_bf16 v[14:17], v[154:157], v[216:219], 0
	v_mfma_f32_16x16x32_bf16 v[10:13], v[162:165], v[216:219], 0
	v_mfma_f32_16x16x32_bf16 v[62:65], v[158:161], v[134:137], v[62:65]
	v_mfma_f32_16x16x32_bf16 v[58:61], v[166:169], v[134:137], v[58:61]
	v_mfma_f32_16x16x32_bf16 v[46:49], v[158:161], v[204:207], v[46:49]
	v_mfma_f32_16x16x32_bf16 v[42:45], v[166:169], v[204:207], v[42:45]
	v_mfma_f32_16x16x32_bf16 v[30:33], v[158:161], v[212:215], v[30:33]
	v_mfma_f32_16x16x32_bf16 v[26:29], v[166:169], v[212:215], v[26:29]
	v_mfma_f32_16x16x32_bf16 v[14:17], v[158:161], v[220:223], v[14:17]
	v_mfma_f32_16x16x32_bf16 v[10:13], v[166:169], v[220:223], v[10:13]
	v_mfma_f32_16x16x32_bf16 v[54:57], v[138:141], v[130:133], 0
	v_mfma_f32_16x16x32_bf16 v[50:53], v[146:149], v[130:133], 0
	v_mfma_f32_16x16x32_bf16 v[38:41], v[138:141], v[200:203], 0
	v_mfma_f32_16x16x32_bf16 v[34:37], v[146:149], v[200:203], 0
	v_mfma_f32_16x16x32_bf16 v[22:25], v[138:141], v[208:211], 0
	v_mfma_f32_16x16x32_bf16 v[18:21], v[146:149], v[208:211], 0
	v_mfma_f32_16x16x32_bf16 v[6:9], v[138:141], v[216:219], 0
	v_mfma_f32_16x16x32_bf16 v[2:5], v[146:149], v[216:219], 0
	v_mfma_f32_16x16x32_bf16 v[54:57], v[142:145], v[134:137], v[54:57]
	v_mfma_f32_16x16x32_bf16 v[50:53], v[150:153], v[134:137], v[50:53]
	v_mfma_f32_16x16x32_bf16 v[38:41], v[142:145], v[204:207], v[38:41]
	v_mfma_f32_16x16x32_bf16 v[34:37], v[150:153], v[204:207], v[34:37]
	v_mfma_f32_16x16x32_bf16 v[22:25], v[142:145], v[212:215], v[22:25]
	v_mfma_f32_16x16x32_bf16 v[18:21], v[150:153], v[212:215], v[18:21]
	v_mfma_f32_16x16x32_bf16 v[6:9], v[142:145], v[220:223], v[6:9]
	v_mfma_f32_16x16x32_bf16 v[2:5], v[150:153], v[220:223], v[2:5]
	s_setprio 0
	s_barrier
	s_branch .Lpz5_mid
.LBB0_985:
	s_add_u32 s42, s30, s40
	s_addc_u32 s43, s31, s41
	s_add_u32 s42, s42, 0x100
	s_addc_u32 s43, s43, 0
	s_add_u32 s84, s29, s40
	s_addc_u32 s85, s35, s41
	s_cmpk_eq_i32 s40, 0x700
	s_cselect_b32 s45, s23, s43
	s_cselect_b32 s44, s81, s42
	s_cselect_b32 s43, s21, s85
	s_cselect_b32 s42, s82, s84
	s_mov_b32 m0, s55
	v_lshl_add_u64 v[232:233], s[42:43], 0, v[174:175]
	s_add_u32 s84, s42, 0x40000
	ds_read_b128 v[130:133], v197 offset:16384
	ds_read_b128 v[134:137], v197 offset:17408
	ds_read_b128 v[200:203], v197 offset:18432
	ds_read_b128 v[204:207], v197 offset:19456
	ds_read_b128 v[208:211], v197 offset:20480
	ds_read_b128 v[212:215], v197 offset:21504
	ds_read_b128 v[216:219], v197 offset:22528
	ds_read_b128 v[220:223], v197 offset:23552
	global_load_lds_dwordx4 v[232:233], off
	v_lshl_add_u64 v[234:235], s[42:43], 0, v[170:171]
	s_mov_b32 m0, s56
	s_addc_u32 s85, s43, 0
	global_load_lds_dwordx4 v[234:235], off
	v_lshl_add_u64 v[224:225], s[84:85], 0, v[174:175]
	s_mov_b32 m0, s57
	v_lshl_add_u64 v[236:237], s[44:45], 0, v[176:177]
	global_load_lds_dwordx4 v[224:225], off
	v_lshl_add_u64 v[224:225], s[84:85], 0, v[170:171]
	s_mov_b32 m0, s58
	v_lshl_add_u64 v[238:239], s[44:45], 0, v[172:173]
	global_load_lds_dwordx4 v[224:225], off
	s_mov_b32 m0, s54
	s_nop 0
	global_load_lds_dwordx4 v[236:237], off
	s_mov_b32 m0, s59
	s_nop 0
	global_load_lds_dwordx4 v[238:239], off
	s_waitcnt vmcnt(8)
	s_waitcnt lgkmcnt(0)
	s_barrier
; #define PG8_STAGE(bufoff, gbase, voff) do { _Pragma("unroll") for (int _i = 0; _i < 2; ++_i) \
;         __builtin_amdgcn_global_load_lds((const unsigned*)((const char*)(gbase) + (voff)[_i]), (PG8_LAS unsigned*)(lds + (bufoff) + ldsw + _i * 8192), 16, 0, 0); } while (0)
; #define PG8_LDA(dst, b, h) do { _Pragma("unroll") for (int m = 0; m < 4; ++m) _Pragma("unroll") for (int k = 0; k < 2; ++k) dst[m][k] = *(const PG8_LAS bf16x8*)(lds + PG8_SA(b, h) + aoff + m * 2048 + k * 1024); } while (0)
; #define PG8_LDB(dst, b, h) do { _Pragma("unroll") for (int n = 0; n < 2; ++n) _Pragma("unroll") for (int k = 0; k < 2; ++k) dst[n][k] = *(const PG8_LAS bf16x8*)(lds + PG8_SB(b, h) + boff + n * 2048 + k * 1024); } while (0)
; #define PG8_MMA(ai, bj, At, Bt) do { __builtin_amdgcn_s_setprio(1); _Pragma("unroll") for (int m = 0; m < 4; ++m) _Pragma("unroll") for (int n = 0; n < 2; ++n) _Pragma("unroll") for (int k = 0; k < 2; ++k) \
;         acc[ai][bj][m][n] = __builtin_amdgcn_mfma_f32_16x16x32_bf16(Bt[n][k], At[m][k], acc[ai][bj][m][n], 0, 0, 0); __builtin_amdgcn_s_setprio(0); } while (0)
; #define PG8_WAIT_V(n) asm volatile("s_waitcnt vmcnt(" #n ")" ::: "memory")
; #define PG8_WAIT_L(n) asm volatile("s_waitcnt lgkmcnt(" #n ")" ::: "memory")
; #define PG8_BAR __builtin_amdgcn_s_barrier()
; #define PG8_SCHED __builtin_amdgcn_sched_barrier(0)
; template <class Epi, class Sched, bool ALIGN_EPI = false, bool SP2 = false>
; __device__ __forceinline__ void gemm_phase(PG8_LAS unsigned char* lds, const Gemm g, const Sched& S, const Epi& E) {
;     ...
;             PG8_LDA(At, 0, 1); PG8_STAGE(PG8_SB(0, 0), b2, voffB); PG8_STAGE(PG8_SB(0, 1), b2 + hstep, voffB); PG8_STAGE(PG8_SA(0, 0), a2, voffA);
;             PG8_WAIT_V(8); PG8_WAIT_L(0); PG8_BAR; PG8_MMA(1, 0, At, B0); PG8_MMA(1, 1, At, B1); PG8_BAR; PG8_SCHED;
;             PG8_LDB(B0, 1, 0); PG8_LDB(B1, 1, 1); PG8_SCHED; PG8_LDA(At, 1, 0); PG8_STAGE(PG8_SA(0, 1), a2 + hstep, voffA);
;             PG8_WAIT_V(8); PG8_WAIT_L(0); PG8_BAR; PG8_MMA(0, 0, At, B0); PG8_MMA(0, 1, At, B1); PG8_BAR; PG8_SCHED;
	s_setprio 1
	v_mfma_f32_16x16x32_bf16 v[62:65], v[154:157], v[130:133], v[62:65]
	v_mfma_f32_16x16x32_bf16 v[58:61], v[162:165], v[130:133], v[58:61]
	v_mfma_f32_16x16x32_bf16 v[46:49], v[154:157], v[200:203], v[46:49]
	v_mfma_f32_16x16x32_bf16 v[42:45], v[162:165], v[200:203], v[42:45]
	v_mfma_f32_16x16x32_bf16 v[30:33], v[154:157], v[208:211], v[30:33]
	v_mfma_f32_16x16x32_bf16 v[26:29], v[162:165], v[208:211], v[26:29]
	v_mfma_f32_16x16x32_bf16 v[14:17], v[154:157], v[216:219], v[14:17]
	v_mfma_f32_16x16x32_bf16 v[10:13], v[162:165], v[216:219], v[10:13]
	v_mfma_f32_16x16x32_bf16 v[62:65], v[158:161], v[134:137], v[62:65]
	v_mfma_f32_16x16x32_bf16 v[58:61], v[166:169], v[134:137], v[58:61]
	v_mfma_f32_16x16x32_bf16 v[46:49], v[158:161], v[204:207], v[46:49]
	v_mfma_f32_16x16x32_bf16 v[42:45], v[166:169], v[204:207], v[42:45]
	v_mfma_f32_16x16x32_bf16 v[30:33], v[158:161], v[212:215], v[30:33]
	v_mfma_f32_16x16x32_bf16 v[26:29], v[166:169], v[212:215], v[26:29]
	v_mfma_f32_16x16x32_bf16 v[14:17], v[158:161], v[220:223], v[14:17]
	v_mfma_f32_16x16x32_bf16 v[10:13], v[166:169], v[220:223], v[10:13]
	v_mfma_f32_16x16x32_bf16 v[54:57], v[138:141], v[130:133], v[54:57]
	v_mfma_f32_16x16x32_bf16 v[50:53], v[146:149], v[130:133], v[50:53]
	v_mfma_f32_16x16x32_bf16 v[38:41], v[138:141], v[200:203], v[38:41]
	v_mfma_f32_16x16x32_bf16 v[34:37], v[146:149], v[200:203], v[34:37]
	v_mfma_f32_16x16x32_bf16 v[22:25], v[138:141], v[208:211], v[22:25]
	v_mfma_f32_16x16x32_bf16 v[18:21], v[146:149], v[208:211], v[18:21]
	v_mfma_f32_16x16x32_bf16 v[6:9], v[138:141], v[216:219], v[6:9]
	v_mfma_f32_16x16x32_bf16 v[2:5], v[146:149], v[216:219], v[2:5]
	v_mfma_f32_16x16x32_bf16 v[54:57], v[142:145], v[134:137], v[54:57]
	v_mfma_f32_16x16x32_bf16 v[50:53], v[150:153], v[134:137], v[50:53]
	v_mfma_f32_16x16x32_bf16 v[38:41], v[142:145], v[204:207], v[38:41]
	v_mfma_f32_16x16x32_bf16 v[34:37], v[150:153], v[204:207], v[34:37]
	v_mfma_f32_16x16x32_bf16 v[22:25], v[142:145], v[212:215], v[22:25]
	v_mfma_f32_16x16x32_bf16 v[18:21], v[150:153], v[212:215], v[18:21]
	v_mfma_f32_16x16x32_bf16 v[6:9], v[142:145], v[220:223], v[6:9]
	v_mfma_f32_16x16x32_bf16 v[2:5], v[150:153], v[220:223], v[2:5]
	s_setprio 0
	s_barrier
.Lpz5_mid:
	s_add_i32 s84, 0, 0x18000
	v_add_u32_e32 v130, s84, v193
	s_add_i32 s85, 0, 0x1c000
	ds_read_b128 v[138:141], v130
	ds_read_b128 v[142:145], v130 offset:1024
	ds_read_b128 v[146:149], v130 offset:2048
	ds_read_b128 v[150:153], v130 offset:3072
	v_add_u32_e32 v130, s85, v193
	ds_read_b128 v[154:157], v130
	ds_read_b128 v[158:161], v130 offset:1024
	ds_read_b128 v[162:165], v130 offset:2048
	ds_read_b128 v[166:169], v130 offset:3072
	s_add_u32 s44, s44, 0x40000
	s_addc_u32 s45, s45, 0
	s_mov_b32 m0, s60
	v_lshl_add_u64 v[130:131], s[44:45], 0, v[176:177]
	ds_read_b128 v[200:203], v197 offset:32768
	ds_read_b128 v[204:207], v197 offset:33792
	ds_read_b128 v[208:211], v197 offset:34816
	ds_read_b128 v[212:215], v197 offset:35840
	ds_read_b128 v[216:219], v197 offset:36864
	ds_read_b128 v[220:223], v197 offset:37888
	ds_read_b128 v[224:227], v197 offset:38912
	ds_read_b128 v[228:231], v197 offset:39936
	global_load_lds_dwordx4 v[130:131], off
	v_lshl_add_u64 v[130:131], s[44:45], 0, v[172:173]
	s_mov_b32 m0, s61
	s_nop 0
	global_load_lds_dwordx4 v[130:131], off
	s_waitcnt vmcnt(8)
	s_waitcnt lgkmcnt(0)
	s_barrier
	s_setprio 1
	v_mfma_f32_16x16x32_bf16 v[98:101], v[138:141], v[200:203], v[98:101]
	v_mfma_f32_16x16x32_bf16 v[134:137], v[142:145], v[204:207], v[98:101]
	v_mfma_f32_16x16x32_bf16 v[98:101], v[146:149], v[200:203], v[106:109]
	v_mfma_f32_16x16x32_bf16 v[130:133], v[150:153], v[204:207], v[98:101]
	v_mfma_f32_16x16x32_bf16 v[98:101], v[138:141], v[208:211], v[118:121]
	v_mfma_f32_16x16x32_bf16 v[118:121], v[142:145], v[212:215], v[98:101]
	v_mfma_f32_16x16x32_bf16 v[98:101], v[146:149], v[208:211], v[114:117]
	v_mfma_f32_16x16x32_bf16 v[94:97], v[138:141], v[216:219], v[94:97]
	v_mfma_f32_16x16x32_bf16 v[90:93], v[146:149], v[216:219], v[90:93]
	v_mfma_f32_16x16x32_bf16 v[78:81], v[138:141], v[224:227], v[78:81]
	v_mfma_f32_16x16x32_bf16 v[74:77], v[146:149], v[224:227], v[74:77]
	v_mfma_f32_16x16x32_bf16 v[114:117], v[150:153], v[212:215], v[98:101]
	v_mfma_f32_16x16x32_bf16 v[94:97], v[142:145], v[220:223], v[94:97]
	v_mfma_f32_16x16x32_bf16 v[90:93], v[150:153], v[220:223], v[90:93]
	v_mfma_f32_16x16x32_bf16 v[78:81], v[142:145], v[228:231], v[78:81]
	v_mfma_f32_16x16x32_bf16 v[74:77], v[150:153], v[228:231], v[74:77]
	v_mfma_f32_16x16x32_bf16 v[98:101], v[154:157], v[200:203], v[126:129]
	v_mfma_f32_16x16x32_bf16 v[126:129], v[158:161], v[204:207], v[98:101]
	v_mfma_f32_16x16x32_bf16 v[98:101], v[162:165], v[200:203], v[122:125]
	v_mfma_f32_16x16x32_bf16 v[122:125], v[166:169], v[204:207], v[98:101]
	v_mfma_f32_16x16x32_bf16 v[98:101], v[154:157], v[208:211], v[110:113]
	v_mfma_f32_16x16x32_bf16 v[110:113], v[158:161], v[212:215], v[98:101]
	v_mfma_f32_16x16x32_bf16 v[98:101], v[162:165], v[208:211], v[102:105]
	v_mfma_f32_16x16x32_bf16 v[86:89], v[154:157], v[216:219], v[86:89]
	v_mfma_f32_16x16x32_bf16 v[82:85], v[162:165], v[216:219], v[82:85]
	v_mfma_f32_16x16x32_bf16 v[70:73], v[154:157], v[224:227], v[70:73]
	v_mfma_f32_16x16x32_bf16 v[66:69], v[162:165], v[224:227], v[66:69]
	v_mfma_f32_16x16x32_bf16 v[102:105], v[166:169], v[212:215], v[98:101]
	v_mfma_f32_16x16x32_bf16 v[86:89], v[158:161], v[220:223], v[86:89]
	v_mfma_f32_16x16x32_bf16 v[82:85], v[166:169], v[220:223], v[82:85]
	v_mfma_f32_16x16x32_bf16 v[70:73], v[158:161], v[228:231], v[70:73]
	v_mfma_f32_16x16x32_bf16 v[66:69], v[166:169], v[228:231], v[66:69]
	s_setprio 0
	s_barrier
; #define PG8_STAGE(bufoff, gbase, voff) do { _Pragma("unroll") for (int _i = 0; _i < 2; ++_i) \
;         __builtin_amdgcn_global_load_lds((const unsigned*)((const char*)(gbase) + (voff)[_i]), (PG8_LAS unsigned*)(lds + (bufoff) + ldsw + _i * 8192), 16, 0, 0); } while (0)
; #define PG8_LDA(dst, b, h) do { _Pragma("unroll") for (int m = 0; m < 4; ++m) _Pragma("unroll") for (int k = 0; k < 2; ++k) dst[m][k] = *(const PG8_LAS bf16x8*)(lds + PG8_SA(b, h) + aoff + m * 2048 + k * 1024); } while (0)
; #define PG8_MMA(ai, bj, At, Bt) do { __builtin_amdgcn_s_setprio(1); _Pragma("unroll") for (int m = 0; m < 4; ++m) _Pragma("unroll") for (int n = 0; n < 2; ++n) _Pragma("unroll") for (int k = 0; k < 2; ++k) \
;         acc[ai][bj][m][n] = __builtin_amdgcn_mfma_f32_16x16x32_bf16(Bt[n][k], At[m][k], acc[ai][bj][m][n], 0, 0, 0); __builtin_amdgcn_s_setprio(0); } while (0)
; #define PG8_WAIT_V(n) asm volatile("s_waitcnt vmcnt(" #n ")" ::: "memory")
; #define PG8_WAIT_L(n) asm volatile("s_waitcnt lgkmcnt(" #n ")" ::: "memory")
; #define PG8_BAR __builtin_amdgcn_s_barrier()
; #define PG8_SCHED __builtin_amdgcn_sched_barrier(0)
; template <class Epi, class Sched, bool ALIGN_EPI = false, bool SP2 = false>
; __device__ __forceinline__ void gemm_phase(PG8_LAS unsigned char* lds, const Gemm g, const Sched& S, const Epi& E) {
;     ...
;             PG8_LDA(At, 1, 1); PG8_STAGE(PG8_SB(1, 0), b3, voffB); PG8_STAGE(PG8_SB(1, 1), b3 + hstep, voffB); PG8_STAGE(PG8_SA(1, 0), a3, voffA);
;             PG8_WAIT_V(8); PG8_WAIT_L(0); PG8_BAR; PG8_MMA(1, 0, At, B0); PG8_MMA(1, 1, At, B1); PG8_BAR; PG8_SCHED;
	s_add_i32 s44, s84, s51
	v_lshl_add_u64 v[224:225], v[232:233], 0, s[8:9]
	s_mov_b32 m0, s44
	ds_read_b128 v[98:101], v197 offset:49152
	ds_read_b128 v[106:109], v197 offset:50176
	ds_read_b128 v[200:203], v197 offset:51200
	ds_read_b128 v[204:207], v197 offset:52224
	ds_read_b128 v[208:211], v197 offset:53248
	ds_read_b128 v[212:215], v197 offset:54272
	ds_read_b128 v[216:219], v197 offset:55296
	ds_read_b128 v[220:223], v197 offset:56320
	global_load_lds_dwordx4 v[224:225], off
	s_add_i32 m0, s44, 0x2000
	s_add_u32 s42, s42, 0x40080
	v_lshl_add_u64 v[224:225], v[234:235], 0, s[8:9]
	s_addc_u32 s43, s43, 0
	s_add_i32 s44, s85, s51
	global_load_lds_dwordx4 v[224:225], off
	v_lshl_add_u64 v[224:225], s[42:43], 0, v[174:175]
	s_mov_b32 m0, s44
	s_nop 0
	global_load_lds_dwordx4 v[224:225], off
	v_lshl_add_u64 v[224:225], s[42:43], 0, v[170:171]
	s_add_i32 m0, s44, 0x2000
	s_nop 0
	global_load_lds_dwordx4 v[224:225], off
	v_lshl_add_u64 v[224:225], v[236:237], 0, s[8:9]
	s_mov_b32 m0, s65
	s_nop 0
	global_load_lds_dwordx4 v[224:225], off
	v_lshl_add_u64 v[224:225], v[238:239], 0, s[8:9]
	s_mov_b32 m0, s66
	s_nop 0
	global_load_lds_dwordx4 v[224:225], off
	s_waitcnt vmcnt(8)
	s_waitcnt lgkmcnt(0)
	s_barrier
	s_setprio 1
	v_mfma_f32_16x16x32_bf16 v[62:65], v[138:141], v[98:101], v[62:65]
	v_mfma_f32_16x16x32_bf16 v[58:61], v[146:149], v[98:101], v[58:61]
	v_mfma_f32_16x16x32_bf16 v[46:49], v[138:141], v[200:203], v[46:49]
	v_mfma_f32_16x16x32_bf16 v[42:45], v[146:149], v[200:203], v[42:45]
	v_mfma_f32_16x16x32_bf16 v[30:33], v[138:141], v[208:211], v[30:33]
	v_mfma_f32_16x16x32_bf16 v[26:29], v[146:149], v[208:211], v[26:29]
	v_mfma_f32_16x16x32_bf16 v[14:17], v[138:141], v[216:219], v[14:17]
	v_mfma_f32_16x16x32_bf16 v[10:13], v[146:149], v[216:219], v[10:13]
	v_mfma_f32_16x16x32_bf16 v[62:65], v[142:145], v[106:109], v[62:65]
	v_mfma_f32_16x16x32_bf16 v[58:61], v[150:153], v[106:109], v[58:61]
	v_mfma_f32_16x16x32_bf16 v[46:49], v[142:145], v[204:207], v[46:49]
	v_mfma_f32_16x16x32_bf16 v[42:45], v[150:153], v[204:207], v[42:45]
	v_mfma_f32_16x16x32_bf16 v[30:33], v[142:145], v[212:215], v[30:33]
	v_mfma_f32_16x16x32_bf16 v[26:29], v[150:153], v[212:215], v[26:29]
	v_mfma_f32_16x16x32_bf16 v[14:17], v[142:145], v[220:223], v[14:17]
	v_mfma_f32_16x16x32_bf16 v[10:13], v[150:153], v[220:223], v[10:13]
	v_mfma_f32_16x16x32_bf16 v[54:57], v[154:157], v[98:101], v[54:57]
	v_mfma_f32_16x16x32_bf16 v[50:53], v[162:165], v[98:101], v[50:53]
	v_mfma_f32_16x16x32_bf16 v[38:41], v[154:157], v[200:203], v[38:41]
	v_mfma_f32_16x16x32_bf16 v[34:37], v[162:165], v[200:203], v[34:37]
	v_mfma_f32_16x16x32_bf16 v[22:25], v[154:157], v[208:211], v[22:25]
	v_mfma_f32_16x16x32_bf16 v[18:21], v[162:165], v[208:211], v[18:21]
	v_mfma_f32_16x16x32_bf16 v[6:9], v[154:157], v[216:219], v[6:9]
	v_mfma_f32_16x16x32_bf16 v[2:5], v[162:165], v[216:219], v[2:5]
	v_mfma_f32_16x16x32_bf16 v[54:57], v[158:161], v[106:109], v[54:57]
	v_mfma_f32_16x16x32_bf16 v[50:53], v[166:169], v[106:109], v[50:53]
	v_mfma_f32_16x16x32_bf16 v[38:41], v[158:161], v[204:207], v[38:41]
	v_mfma_f32_16x16x32_bf16 v[34:37], v[166:169], v[204:207], v[34:37]
	v_mfma_f32_16x16x32_bf16 v[22:25], v[158:161], v[212:215], v[22:25]
	v_mfma_f32_16x16x32_bf16 v[18:21], v[166:169], v[212:215], v[18:21]
	v_mfma_f32_16x16x32_bf16 v[6:9], v[158:161], v[220:223], v[6:9]
	v_mfma_f32_16x16x32_bf16 v[2:5], v[166:169], v[220:223], v[2:5]
	s_setprio 0
	s_barrier
	s_add_i32 s42, s83, 2
	s_add_u32 s40, s40, 0x100
	s_addc_u32 s41, s41, 0
	s_cmp_gt_u32 s83, 13
	s_mov_b32 s83, s42
	s_cbranch_scc1 .LBB0_989
; #define PG8_LAS __attribute__((address_space(3)))
; #define PG8_STAGE(bufoff, gbase, voff) do { _Pragma("unroll") for (int _i = 0; _i < 2; ++_i) \
;         __builtin_amdgcn_global_load_lds((const unsigned*)((const char*)(gbase) + (voff)[_i]), (PG8_LAS unsigned*)(lds + (bufoff) + ldsw + _i * 8192), 16, 0, 0); } while (0)
; #define PG8_LDA(dst, b, h) do { _Pragma("unroll") for (int m = 0; m < 4; ++m) _Pragma("unroll") for (int k = 0; k < 2; ++k) dst[m][k] = *(const PG8_LAS bf16x8*)(lds + PG8_SA(b, h) + aoff + m * 2048 + k * 1024); } while (0)
; #define PG8_LDB(dst, b, h) do { _Pragma("unroll") for (int n = 0; n < 2; ++n) _Pragma("unroll") for (int k = 0; k < 2; ++k) dst[n][k] = *(const PG8_LAS bf16x8*)(lds + PG8_SB(b, h) + boff + n * 2048 + k * 1024); } while (0)
; #define PG8_MMA(ai, bj, At, Bt) do { __builtin_amdgcn_s_setprio(1); _Pragma("unroll") for (int m = 0; m < 4; ++m) _Pragma("unroll") for (int n = 0; n < 2; ++n) _Pragma("unroll") for (int k = 0; k < 2; ++k) \
;         acc[ai][bj][m][n] = __builtin_amdgcn_mfma_f32_16x16x32_bf16(Bt[n][k], At[m][k], acc[ai][bj][m][n], 0, 0, 0); __builtin_amdgcn_s_setprio(0); } while (0)
; #define PG8_WAIT_V(n) asm volatile("s_waitcnt vmcnt(" #n ")" ::: "memory")
; template <class Epi, class Sched, bool ALIGN_EPI = false, bool SP2 = false>
; __device__ __forceinline__ void gemm_phase(PG8_LAS unsigned char* lds, const Gemm g, const Sched& S, const Epi& E) {
;     ...
;             PG8_LDB(B0, 0, 0); PG8_LDB(B1, 0, 1); PG8_SCHED; PG8_LDA(At, 0, 0); PG8_STAGE(PG8_SA(1, 1), a1 + hstep, voffA);
;             PG8_WAIT_V(8); PG8_WAIT_L(0); PG8_BAR; PG8_MMA(0, 0, At, B0); PG8_MMA(0, 1, At, B1); PG8_BAR; PG8_SCHED;
;             if constexpr (Epi::PREFETCH) { if (t == tpf) E.prefetch(cur, wid, lane); }
; __device__ __forceinline__ void epi_prefetch(PG8_LAS unsigned char* scr, const float* ssq, const float* bias_tile, const Unit& u, int wid, int lane) {
;     unsigned lo = (unsigned)lane * 16u; asm volatile("" : "+v"(lo));
;     const char* src = (const char*)(ssq + (size_t)u.pm * BM * 16 + wid * 512);
; #pragma unroll
;     for (int j = 0; j < 2; ++j) __builtin_amdgcn_global_load_lds((const unsigned*)(src + j * 1024 + lo), (PG8_LAS unsigned*)(scr + (wid * 2 + j) * 1024), 16, 0, 0);
;     if (wid == 0) __builtin_amdgcn_global_load_lds((const unsigned*)((const char*)bias_tile + lo), (PG8_LAS unsigned*)(scr + 16384), 16, 0, 0);
; }
.LBB0_986:
	ds_read_b128 v[154:157], v195
	ds_read_b128 v[158:161], v195 offset:1024
	ds_read_b128 v[162:165], v195 offset:2048
	ds_read_b128 v[166:169], v195 offset:3072
	ds_read_b128 v[138:141], v196
	ds_read_b128 v[142:145], v196 offset:1024
	ds_read_b128 v[146:149], v196 offset:2048
	ds_read_b128 v[150:153], v196 offset:3072
	v_lshl_add_u64 v[98:99], v[188:189], 0, s[40:41]
	s_add_i32 m0, s54, 0xc000
	ds_read_b128 v[200:203], v197
	ds_read_b128 v[204:207], v197 offset:1024
	ds_read_b128 v[208:211], v197 offset:2048
	ds_read_b128 v[212:215], v197 offset:3072
	ds_read_b128 v[216:219], v197 offset:4096
	ds_read_b128 v[220:223], v197 offset:5120
	ds_read_b128 v[224:227], v197 offset:6144
	ds_read_b128 v[228:231], v197 offset:7168
	global_load_lds_dwordx4 v[98:99], off
	v_lshl_add_u64 v[98:99], v[190:191], 0, s[40:41]
	s_add_i32 m0, s54, 0xe000
	s_nop 0
	global_load_lds_dwordx4 v[98:99], off
	s_waitcnt vmcnt(8)
	s_waitcnt lgkmcnt(0)
	s_barrier
	s_setprio 1
	v_mfma_f32_16x16x32_bf16 v[98:101], v[154:157], v[200:203], v[134:137]
	v_mfma_f32_16x16x32_bf16 v[106:109], v[162:165], v[200:203], v[130:133]
	v_mfma_f32_16x16x32_bf16 v[118:121], v[154:157], v[208:211], v[118:121]
	v_mfma_f32_16x16x32_bf16 v[114:117], v[162:165], v[208:211], v[114:117]
	v_mfma_f32_16x16x32_bf16 v[94:97], v[154:157], v[216:219], v[94:97]
	v_mfma_f32_16x16x32_bf16 v[90:93], v[162:165], v[216:219], v[90:93]
	v_mfma_f32_16x16x32_bf16 v[78:81], v[154:157], v[224:227], v[78:81]
	v_mfma_f32_16x16x32_bf16 v[74:77], v[162:165], v[224:227], v[74:77]
	v_mfma_f32_16x16x32_bf16 v[98:101], v[158:161], v[204:207], v[98:101]
	v_mfma_f32_16x16x32_bf16 v[106:109], v[166:169], v[204:207], v[106:109]
	v_mfma_f32_16x16x32_bf16 v[118:121], v[158:161], v[212:215], v[118:121]
	v_mfma_f32_16x16x32_bf16 v[114:117], v[166:169], v[212:215], v[114:117]
	v_mfma_f32_16x16x32_bf16 v[94:97], v[158:161], v[220:223], v[94:97]
	v_mfma_f32_16x16x32_bf16 v[90:93], v[166:169], v[220:223], v[90:93]
	v_mfma_f32_16x16x32_bf16 v[78:81], v[158:161], v[228:231], v[78:81]
	v_mfma_f32_16x16x32_bf16 v[74:77], v[166:169], v[228:231], v[74:77]
	v_mfma_f32_16x16x32_bf16 v[126:129], v[138:141], v[200:203], v[126:129]
	v_mfma_f32_16x16x32_bf16 v[122:125], v[146:149], v[200:203], v[122:125]
	v_mfma_f32_16x16x32_bf16 v[110:113], v[138:141], v[208:211], v[110:113]
	v_mfma_f32_16x16x32_bf16 v[102:105], v[146:149], v[208:211], v[102:105]
	v_mfma_f32_16x16x32_bf16 v[86:89], v[138:141], v[216:219], v[86:89]
	v_mfma_f32_16x16x32_bf16 v[82:85], v[146:149], v[216:219], v[82:85]
	v_mfma_f32_16x16x32_bf16 v[70:73], v[138:141], v[224:227], v[70:73]
	v_mfma_f32_16x16x32_bf16 v[66:69], v[146:149], v[224:227], v[66:69]
	v_mfma_f32_16x16x32_bf16 v[126:129], v[142:145], v[204:207], v[126:129]
	v_mfma_f32_16x16x32_bf16 v[122:125], v[150:153], v[204:207], v[122:125]
	v_mfma_f32_16x16x32_bf16 v[110:113], v[142:145], v[212:215], v[110:113]
	v_mfma_f32_16x16x32_bf16 v[102:105], v[150:153], v[212:215], v[102:105]
	v_mfma_f32_16x16x32_bf16 v[86:89], v[142:145], v[220:223], v[86:89]
	v_mfma_f32_16x16x32_bf16 v[82:85], v[150:153], v[220:223], v[82:85]
	v_mfma_f32_16x16x32_bf16 v[70:73], v[142:145], v[228:231], v[70:73]
	v_mfma_f32_16x16x32_bf16 v[66:69], v[150:153], v[228:231], v[66:69]
	s_setprio 0
	s_barrier
	s_cmp_lg_u32 s46, s83
	s_cbranch_scc1 .LBB0_985
	v_mov_b32_e32 v178, v194
	s_add_i32 m0, s79, 0x20000
	v_lshl_add_u64 v[130:131], s[36:37], 0, v[178:179]
	global_load_lds_dwordx4 v178, s[36:37]
	v_lshl_add_u64 v[130:131], v[130:131], 0, s[18:19]
	s_add_i32 m0, s79, 0x20400
	s_andn2_b64 vcc, exec, s[14:15]
	global_load_lds_dwordx4 v[130:131], off
	s_cbranch_vccnz .LBB0_985
	v_lshl_add_u64 v[130:131], s[38:39], 0, v[178:179]
	s_add_i32 m0, 0, 0x24000
	s_nop 0
	global_load_lds_dwordx4 v[130:131], off
	s_branch .LBB0_985

; #define PG8_STAGE(bufoff, gbase, voff) do { _Pragma("unroll") for (int _i = 0; _i < 2; ++_i) \
;         __builtin_amdgcn_global_load_lds((const unsigned*)((const char*)(gbase) + (voff)[_i]), (PG8_LAS unsigned*)(lds + (bufoff) + ldsw + _i * 8192), 16, 0, 0); } while (0)
; #define PG8_LDA(dst, b, h) do { _Pragma("unroll") for (int m = 0; m < 4; ++m) _Pragma("unroll") for (int k = 0; k < 2; ++k) dst[m][k] = *(const PG8_LAS bf16x8*)(lds + PG8_SA(b, h) + aoff + m * 2048 + k * 1024); } while (0)
; #define PG8_LDB(dst, b, h) do { _Pragma("unroll") for (int n = 0; n < 2; ++n) _Pragma("unroll") for (int k = 0; k < 2; ++k) dst[n][k] = *(const PG8_LAS bf16x8*)(lds + PG8_SB(b, h) + boff + n * 2048 + k * 1024); } while (0)
; #define PG8_MMA(ai, bj, At, Bt) do { __builtin_amdgcn_s_setprio(1); _Pragma("unroll") for (int m = 0; m < 4; ++m) _Pragma("unroll") for (int n = 0; n < 2; ++n) _Pragma("unroll") for (int k = 0; k < 2; ++k) \
;         acc[ai][bj][m][n] = __builtin_amdgcn_mfma_f32_16x16x32_bf16(Bt[n][k], At[m][k], acc[ai][bj][m][n], 0, 0, 0); __builtin_amdgcn_s_setprio(0); } while (0)
; #define PG8_WAIT_V(n) asm volatile("s_waitcnt vmcnt(" #n ")" ::: "memory")
; template <class Epi, class Sched, bool ALIGN_EPI = false, bool SP2 = false>
; __device__ __forceinline__ void gemm_phase(PG8_LAS unsigned char* lds, const Gemm g, const Sched& S, const Epi& E) {
;     ...
;             const bool last = (t == nt - 2);
;             const char* a1 = cA + (size_t)(t + 1) * kstepA;
;             const char* a2 = last ? nA : cA + (size_t)(t + 2) * kstepA; const char* b2 = last ? nB : cB + (size_t)(t + 2) * kstep;
;             const char* a3 = a2 + kstepA; const char* b3 = b2 + kstep;
;             if (last && has_next) S.a_ready(nxt);
;             if constexpr (SP2) {
;             PG8_LDB(B0, 0, 0); PG8_LDB(B1, 0, 1); PG8_SCHED; PG8_LDA(At, 0, 0); PG8_STAGE(PG8_SA(1, 1), a1 + hstep, voffA);
;             PG8_WAIT_V(8); PG8_WAIT_L(0); PG8_BAR; PG8_MMA(0, 0, At, B0); PG8_MMA(0, 1, At, B1); PG8_BAR; PG8_SCHED;
;             if constexpr (Epi::PREFETCH) { if (t == tpf) E.prefetch(cur, wid, lane); }
;             PG8_LDA(At, 0, 1); PG8_STAGE(PG8_SB(0, 0), b2, voffB); PG8_STAGE(PG8_SB(0, 1), b2 + hstep, voffB); PG8_STAGE(PG8_SA(0, 0), a2, voffA);
;             PG8_WAIT_V(8); PG8_WAIT_L(0); PG8_BAR; PG8_MMA(1, 0, At, B0); PG8_MMA(1, 1, At, B1); PG8_BAR; PG8_SCHED;
.LBB0_1068:
	s_add_u32 s35, s6, 0x100
	s_addc_u32 s36, s7, 0
	s_mov_b32 s37, -2
	s_waitcnt lgkmcnt(0)
	ds_read_b128 v[130:133], v192
	ds_read_b128 v[134:137], v192 offset:1024
	ds_read_b128 v[156:159], v192 offset:2048
	ds_read_b128 v[160:163], v192 offset:3072
	ds_read_b128 v[164:167], v193
	ds_read_b128 v[168:171], v193 offset:1024
	ds_read_b128 v[172:175], v193 offset:2048
	ds_read_b128 v[176:179], v193 offset:3072
	s_add_u32 s0, s4, 0x200
	s_addc_u32 s1, s5, 0
	s_cmp_eq_u32 s37, 40
	s_cselect_b32 s31, s27, s1
	s_cselect_b32 s30, s26, s0
	s_cselect_b32 s7, s29, s36
	s_cselect_b32 s6, s28, s35
	v_lshl_add_u64 v[188:189], s[4:5], 0, v[148:149]
	s_add_i32 m0, s45, 0xc000
	ds_read_b128 v[180:183], v194
	ds_read_b128 v[184:187], v194 offset:1024
	ds_read_b128 v[196:199], v194 offset:2048
	ds_read_b128 v[200:203], v194 offset:3072
	ds_read_b128 v[204:207], v194 offset:4096
	ds_read_b128 v[208:211], v194 offset:5120
	ds_read_b128 v[212:215], v194 offset:6144
	ds_read_b128 v[216:219], v194 offset:7168
	global_load_lds_dwordx4 v[188:189], off
	v_lshl_add_u64 v[188:189], s[4:5], 0, v[150:151]
	s_add_i32 m0, s45, 0xe000
	s_nop 0
	global_load_lds_dwordx4 v[188:189], off
	s_waitcnt vmcnt(8)
	s_waitcnt lgkmcnt(0)
	s_barrier
	s_setprio 1
	v_mfma_f32_16x16x32_bf16 v[126:129], v[130:133], v[180:183], 0
	v_mfma_f32_16x16x32_bf16 v[122:125], v[156:159], v[180:183], 0
	v_mfma_f32_16x16x32_bf16 v[110:113], v[130:133], v[196:199], 0
	v_mfma_f32_16x16x32_bf16 v[106:109], v[156:159], v[196:199], 0
	v_mfma_f32_16x16x32_bf16 v[94:97], v[130:133], v[204:207], 0
	v_mfma_f32_16x16x32_bf16 v[90:93], v[156:159], v[204:207], 0
	v_mfma_f32_16x16x32_bf16 v[78:81], v[130:133], v[212:215], 0
	v_mfma_f32_16x16x32_bf16 v[74:77], v[156:159], v[212:215], 0
	v_mfma_f32_16x16x32_bf16 v[126:129], v[134:137], v[184:187], v[126:129]
	v_mfma_f32_16x16x32_bf16 v[122:125], v[160:163], v[184:187], v[122:125]
	v_mfma_f32_16x16x32_bf16 v[110:113], v[134:137], v[200:203], v[110:113]
	v_mfma_f32_16x16x32_bf16 v[106:109], v[160:163], v[200:203], v[106:109]
	v_mfma_f32_16x16x32_bf16 v[94:97], v[134:137], v[208:211], v[94:97]
	v_mfma_f32_16x16x32_bf16 v[90:93], v[160:163], v[208:211], v[90:93]
	v_mfma_f32_16x16x32_bf16 v[78:81], v[134:137], v[216:219], v[78:81]
	v_mfma_f32_16x16x32_bf16 v[74:77], v[160:163], v[216:219], v[74:77]
	v_mfma_f32_16x16x32_bf16 v[118:121], v[164:167], v[180:183], 0
	v_mfma_f32_16x16x32_bf16 v[114:117], v[172:175], v[180:183], 0
	v_mfma_f32_16x16x32_bf16 v[102:105], v[164:167], v[196:199], 0
	v_mfma_f32_16x16x32_bf16 v[98:101], v[172:175], v[196:199], 0
	v_mfma_f32_16x16x32_bf16 v[86:89], v[164:167], v[204:207], 0
	v_mfma_f32_16x16x32_bf16 v[82:85], v[172:175], v[204:207], 0
	v_mfma_f32_16x16x32_bf16 v[70:73], v[164:167], v[212:215], 0
	v_mfma_f32_16x16x32_bf16 v[66:69], v[172:175], v[212:215], 0
	v_mfma_f32_16x16x32_bf16 v[118:121], v[168:171], v[184:187], v[118:121]
	v_mfma_f32_16x16x32_bf16 v[114:117], v[176:179], v[184:187], v[114:117]
	v_mfma_f32_16x16x32_bf16 v[102:105], v[168:171], v[200:203], v[102:105]
	v_mfma_f32_16x16x32_bf16 v[98:101], v[176:179], v[200:203], v[98:101]
	v_mfma_f32_16x16x32_bf16 v[86:89], v[168:171], v[208:211], v[86:89]
	v_mfma_f32_16x16x32_bf16 v[82:85], v[176:179], v[208:211], v[82:85]
	v_mfma_f32_16x16x32_bf16 v[70:73], v[168:171], v[216:219], v[70:73]
	v_mfma_f32_16x16x32_bf16 v[66:69], v[176:179], v[216:219], v[66:69]
	s_setprio 0
	s_barrier
	s_add_i32 s4, s61, s44
	v_lshl_add_u64 v[188:189], s[6:7], 0, v[140:141]
	s_mov_b32 m0, s4
	ds_read_b128 v[180:183], v194 offset:16384
	ds_read_b128 v[184:187], v194 offset:17408
	ds_read_b128 v[196:199], v194 offset:18432
	ds_read_b128 v[200:203], v194 offset:19456
	ds_read_b128 v[204:207], v194 offset:20480
	ds_read_b128 v[208:211], v194 offset:21504
	ds_read_b128 v[212:215], v194 offset:22528
	ds_read_b128 v[216:219], v194 offset:23552
	global_load_lds_dwordx4 v[188:189], off
	s_add_i32 m0, s4, 0x2000
	s_add_u32 s4, s6, 0xb0000
	v_lshl_add_u64 v[220:221], s[6:7], 0, v[144:145]
	s_addc_u32 s5, s7, 0
	s_add_i32 s38, s62, s44
	global_load_lds_dwordx4 v[220:221], off
	v_lshl_add_u64 v[222:223], s[4:5], 0, v[140:141]
	s_mov_b32 m0, s38
	v_lshl_add_u64 v[224:225], s[30:31], 0, v[142:143]
	global_load_lds_dwordx4 v[222:223], off
	v_lshl_add_u64 v[222:223], s[4:5], 0, v[144:145]
	s_add_i32 m0, s38, 0x2000
	s_nop 0
	global_load_lds_dwordx4 v[222:223], off
	v_lshl_add_u64 v[222:223], s[30:31], 0, v[138:139]
	s_mov_b32 m0, s45
	s_nop 0
	global_load_lds_dwordx4 v[222:223], off
	s_mov_b32 m0, s46
	s_nop 0
	global_load_lds_dwordx4 v[224:225], off
	s_waitcnt vmcnt(8)
	s_waitcnt lgkmcnt(0)
	s_barrier
	s_setprio 1
	v_mfma_f32_16x16x32_bf16 v[62:65], v[130:133], v[180:183], 0
	v_mfma_f32_16x16x32_bf16 v[58:61], v[156:159], v[180:183], 0
	v_mfma_f32_16x16x32_bf16 v[46:49], v[130:133], v[196:199], 0
	v_mfma_f32_16x16x32_bf16 v[42:45], v[156:159], v[196:199], 0
	v_mfma_f32_16x16x32_bf16 v[30:33], v[130:133], v[204:207], 0
	v_mfma_f32_16x16x32_bf16 v[26:29], v[156:159], v[204:207], 0
	v_mfma_f32_16x16x32_bf16 v[14:17], v[130:133], v[212:215], 0
	v_mfma_f32_16x16x32_bf16 v[10:13], v[156:159], v[212:215], 0
	v_mfma_f32_16x16x32_bf16 v[62:65], v[134:137], v[184:187], v[62:65]
	v_mfma_f32_16x16x32_bf16 v[58:61], v[160:163], v[184:187], v[58:61]
	v_mfma_f32_16x16x32_bf16 v[46:49], v[134:137], v[200:203], v[46:49]
	v_mfma_f32_16x16x32_bf16 v[42:45], v[160:163], v[200:203], v[42:45]
	v_mfma_f32_16x16x32_bf16 v[30:33], v[134:137], v[208:211], v[30:33]
	v_mfma_f32_16x16x32_bf16 v[26:29], v[160:163], v[208:211], v[26:29]
	v_mfma_f32_16x16x32_bf16 v[14:17], v[134:137], v[216:219], v[14:17]
	v_mfma_f32_16x16x32_bf16 v[10:13], v[160:163], v[216:219], v[10:13]
	v_mfma_f32_16x16x32_bf16 v[54:57], v[164:167], v[180:183], 0
	v_mfma_f32_16x16x32_bf16 v[50:53], v[172:175], v[180:183], 0
	v_mfma_f32_16x16x32_bf16 v[38:41], v[164:167], v[196:199], 0
	v_mfma_f32_16x16x32_bf16 v[34:37], v[172:175], v[196:199], 0
	v_mfma_f32_16x16x32_bf16 v[22:25], v[164:167], v[204:207], 0
	v_mfma_f32_16x16x32_bf16 v[18:21], v[172:175], v[204:207], 0
	v_mfma_f32_16x16x32_bf16 v[6:9], v[164:167], v[212:215], 0
	v_mfma_f32_16x16x32_bf16 v[2:5], v[172:175], v[212:215], 0
	v_mfma_f32_16x16x32_bf16 v[54:57], v[168:171], v[184:187], v[54:57]
	v_mfma_f32_16x16x32_bf16 v[50:53], v[176:179], v[184:187], v[50:53]
	v_mfma_f32_16x16x32_bf16 v[38:41], v[168:171], v[200:203], v[38:41]
	v_mfma_f32_16x16x32_bf16 v[34:37], v[176:179], v[200:203], v[34:37]
	v_mfma_f32_16x16x32_bf16 v[22:25], v[168:171], v[208:211], v[22:25]
	v_mfma_f32_16x16x32_bf16 v[18:21], v[176:179], v[208:211], v[18:21]
	v_mfma_f32_16x16x32_bf16 v[6:9], v[168:171], v[216:219], v[6:9]
	v_mfma_f32_16x16x32_bf16 v[2:5], v[176:179], v[216:219], v[2:5]
	s_setprio 0
	s_barrier
	s_branch .Lpz6_mid
; #define PG8_STAGE(bufoff, gbase, voff) do { _Pragma("unroll") for (int _i = 0; _i < 2; ++_i) \
;         __builtin_amdgcn_global_load_lds((const unsigned*)((const char*)(gbase) + (voff)[_i]), (PG8_LAS unsigned*)(lds + (bufoff) + ldsw + _i * 8192), 16, 0, 0); } while (0)
; #define PG8_LDA(dst, b, h) do { _Pragma("unroll") for (int m = 0; m < 4; ++m) _Pragma("unroll") for (int k = 0; k < 2; ++k) dst[m][k] = *(const PG8_LAS bf16x8*)(lds + PG8_SA(b, h) + aoff + m * 2048 + k * 1024); } while (0)
; #define PG8_LDB(dst, b, h) do { _Pragma("unroll") for (int n = 0; n < 2; ++n) _Pragma("unroll") for (int k = 0; k < 2; ++k) dst[n][k] = *(const PG8_LAS bf16x8*)(lds + PG8_SB(b, h) + boff + n * 2048 + k * 1024); } while (0)
; #define PG8_MMA(ai, bj, At, Bt) do { __builtin_amdgcn_s_setprio(1); _Pragma("unroll") for (int m = 0; m < 4; ++m) _Pragma("unroll") for (int n = 0; n < 2; ++n) _Pragma("unroll") for (int k = 0; k < 2; ++k) \
;         acc[ai][bj][m][n] = __builtin_amdgcn_mfma_f32_16x16x32_bf16(Bt[n][k], At[m][k], acc[ai][bj][m][n], 0, 0, 0); __builtin_amdgcn_s_setprio(0); } while (0)
; #define PG8_WAIT_V(n) asm volatile("s_waitcnt vmcnt(" #n ")" ::: "memory")
; #define PG8_WAIT_L(n) asm volatile("s_waitcnt lgkmcnt(" #n ")" ::: "memory")
; #define PG8_BAR __builtin_amdgcn_s_barrier()
; #define PG8_SCHED __builtin_amdgcn_sched_barrier(0)
;     __device__ __forceinline__ void prefetch(const Unit& u, int wid, int lane) const { epi_prefetch(scr, ssq, bias + (size_t)(u.pm >> 5) * NGU + u.pn * BM, u, wid, lane); }
; template <class Epi, class Sched, bool ALIGN_EPI = false, bool SP2 = false>
; __device__ __forceinline__ void gemm_phase(PG8_LAS unsigned char* lds, const Gemm g, const Sched& S, const Epi& E) {
;     ...
;             PG8_LDB(B0, 0, 0); PG8_LDB(B1, 0, 1); PG8_SCHED; PG8_LDA(At, 0, 0); PG8_STAGE(PG8_SA(1, 1), a1 + hstep, voffA);
;             PG8_WAIT_V(8); PG8_WAIT_L(0); PG8_BAR; PG8_MMA(0, 0, At, B0); PG8_MMA(0, 1, At, B1); PG8_BAR; PG8_SCHED;
;             if constexpr (Epi::PREFETCH) { if (t == tpf) E.prefetch(cur, wid, lane); }
;             PG8_LDA(At, 0, 1); PG8_STAGE(PG8_SB(0, 0), b2, voffB); PG8_STAGE(PG8_SB(0, 1), b2 + hstep, voffB); PG8_STAGE(PG8_SA(0, 0), a2, voffA);
;             PG8_WAIT_V(8); PG8_WAIT_L(0); PG8_BAR; PG8_MMA(1, 0, At, B0); PG8_MMA(1, 1, At, B1); PG8_BAR; PG8_SCHED;
.LBB0_1069:
	ds_read_b128 v[130:133], v192
	ds_read_b128 v[134:137], v192 offset:1024
	ds_read_b128 v[156:159], v192 offset:2048
	ds_read_b128 v[160:163], v192 offset:3072
	ds_read_b128 v[164:167], v193
	ds_read_b128 v[168:171], v193 offset:1024
	ds_read_b128 v[172:175], v193 offset:2048
	ds_read_b128 v[176:179], v193 offset:3072
	s_add_u32 s0, s4, 0x200
	s_addc_u32 s1, s5, 0
	s_cmp_eq_u32 s37, 40
	s_cselect_b32 s31, s27, s1
	s_cselect_b32 s30, s26, s0
	s_cselect_b32 s7, s29, s36
	s_cselect_b32 s6, s28, s35
	v_lshl_add_u64 v[188:189], s[4:5], 0, v[148:149]
	s_add_i32 m0, s45, 0xc000
	ds_read_b128 v[180:183], v194
	ds_read_b128 v[184:187], v194 offset:1024
	ds_read_b128 v[196:199], v194 offset:2048
	ds_read_b128 v[200:203], v194 offset:3072
	ds_read_b128 v[204:207], v194 offset:4096
	ds_read_b128 v[208:211], v194 offset:5120
	ds_read_b128 v[212:215], v194 offset:6144
	ds_read_b128 v[216:219], v194 offset:7168
	global_load_lds_dwordx4 v[188:189], off
	v_lshl_add_u64 v[188:189], s[4:5], 0, v[150:151]
	s_add_i32 m0, s45, 0xe000
	s_nop 0
	global_load_lds_dwordx4 v[188:189], off
	s_waitcnt vmcnt(8)
	s_waitcnt lgkmcnt(0)
	s_barrier
	s_setprio 1
	v_mfma_f32_16x16x32_bf16 v[126:129], v[130:133], v[180:183], v[126:129]
	v_mfma_f32_16x16x32_bf16 v[122:125], v[156:159], v[180:183], v[122:125]
	v_mfma_f32_16x16x32_bf16 v[110:113], v[130:133], v[196:199], v[110:113]
	v_mfma_f32_16x16x32_bf16 v[106:109], v[156:159], v[196:199], v[106:109]
	v_mfma_f32_16x16x32_bf16 v[94:97], v[130:133], v[204:207], v[94:97]
	v_mfma_f32_16x16x32_bf16 v[90:93], v[156:159], v[204:207], v[90:93]
	v_mfma_f32_16x16x32_bf16 v[78:81], v[130:133], v[212:215], v[78:81]
	v_mfma_f32_16x16x32_bf16 v[74:77], v[156:159], v[212:215], v[74:77]
	v_mfma_f32_16x16x32_bf16 v[126:129], v[134:137], v[184:187], v[126:129]
	v_mfma_f32_16x16x32_bf16 v[122:125], v[160:163], v[184:187], v[122:125]
	v_mfma_f32_16x16x32_bf16 v[110:113], v[134:137], v[200:203], v[110:113]
	v_mfma_f32_16x16x32_bf16 v[106:109], v[160:163], v[200:203], v[106:109]
	v_mfma_f32_16x16x32_bf16 v[94:97], v[134:137], v[208:211], v[94:97]
	v_mfma_f32_16x16x32_bf16 v[90:93], v[160:163], v[208:211], v[90:93]
	v_mfma_f32_16x16x32_bf16 v[78:81], v[134:137], v[216:219], v[78:81]
	v_mfma_f32_16x16x32_bf16 v[74:77], v[160:163], v[216:219], v[74:77]
	v_mfma_f32_16x16x32_bf16 v[118:121], v[164:167], v[180:183], v[118:121]
	v_mfma_f32_16x16x32_bf16 v[114:117], v[172:175], v[180:183], v[114:117]
	v_mfma_f32_16x16x32_bf16 v[102:105], v[164:167], v[196:199], v[102:105]
	v_mfma_f32_16x16x32_bf16 v[98:101], v[172:175], v[196:199], v[98:101]
	v_mfma_f32_16x16x32_bf16 v[86:89], v[164:167], v[204:207], v[86:89]
	v_mfma_f32_16x16x32_bf16 v[82:85], v[172:175], v[204:207], v[82:85]
	v_mfma_f32_16x16x32_bf16 v[70:73], v[164:167], v[212:215], v[70:73]
	v_mfma_f32_16x16x32_bf16 v[66:69], v[172:175], v[212:215], v[66:69]
	v_mfma_f32_16x16x32_bf16 v[118:121], v[168:171], v[184:187], v[118:121]
	v_mfma_f32_16x16x32_bf16 v[114:117], v[176:179], v[184:187], v[114:117]
	v_mfma_f32_16x16x32_bf16 v[102:105], v[168:171], v[200:203], v[102:105]
	v_mfma_f32_16x16x32_bf16 v[98:101], v[176:179], v[200:203], v[98:101]
	v_mfma_f32_16x16x32_bf16 v[86:89], v[168:171], v[208:211], v[86:89]
	v_mfma_f32_16x16x32_bf16 v[82:85], v[176:179], v[208:211], v[82:85]
	v_mfma_f32_16x16x32_bf16 v[70:73], v[168:171], v[216:219], v[70:73]
	v_mfma_f32_16x16x32_bf16 v[66:69], v[176:179], v[216:219], v[66:69]
	s_setprio 0
	s_barrier
	s_add_i32 s4, s61, s44
	v_lshl_add_u64 v[188:189], s[6:7], 0, v[140:141]
	s_mov_b32 m0, s4
	ds_read_b128 v[180:183], v194 offset:16384
	ds_read_b128 v[184:187], v194 offset:17408
	ds_read_b128 v[196:199], v194 offset:18432
	ds_read_b128 v[200:203], v194 offset:19456
	ds_read_b128 v[204:207], v194 offset:20480
	ds_read_b128 v[208:211], v194 offset:21504
	ds_read_b128 v[212:215], v194 offset:22528
	ds_read_b128 v[216:219], v194 offset:23552
	global_load_lds_dwordx4 v[188:189], off
	s_add_i32 m0, s4, 0x2000
	s_add_u32 s4, s6, 0xb0000
	v_lshl_add_u64 v[220:221], s[6:7], 0, v[144:145]
	s_addc_u32 s5, s7, 0
	s_add_i32 s38, s62, s44
	global_load_lds_dwordx4 v[220:221], off
	v_lshl_add_u64 v[222:223], s[4:5], 0, v[140:141]
	s_mov_b32 m0, s38
	v_lshl_add_u64 v[224:225], s[30:31], 0, v[142:143]
	global_load_lds_dwordx4 v[222:223], off
	v_lshl_add_u64 v[222:223], s[4:5], 0, v[144:145]
	s_add_i32 m0, s38, 0x2000
	s_nop 0
	global_load_lds_dwordx4 v[222:223], off
	v_lshl_add_u64 v[222:223], s[30:31], 0, v[138:139]
	s_mov_b32 m0, s45
	s_nop 0
	global_load_lds_dwordx4 v[222:223], off
	s_mov_b32 m0, s46
	s_nop 0
	global_load_lds_dwordx4 v[224:225], off
	s_waitcnt vmcnt(8)
	s_waitcnt lgkmcnt(0)
	s_barrier
	s_setprio 1
	v_mfma_f32_16x16x32_bf16 v[62:65], v[130:133], v[180:183], v[62:65]
	v_mfma_f32_16x16x32_bf16 v[58:61], v[156:159], v[180:183], v[58:61]
	v_mfma_f32_16x16x32_bf16 v[46:49], v[130:133], v[196:199], v[46:49]
	v_mfma_f32_16x16x32_bf16 v[42:45], v[156:159], v[196:199], v[42:45]
	v_mfma_f32_16x16x32_bf16 v[30:33], v[130:133], v[204:207], v[30:33]
	v_mfma_f32_16x16x32_bf16 v[26:29], v[156:159], v[204:207], v[26:29]
	v_mfma_f32_16x16x32_bf16 v[14:17], v[130:133], v[212:215], v[14:17]
	v_mfma_f32_16x16x32_bf16 v[10:13], v[156:159], v[212:215], v[10:13]
	v_mfma_f32_16x16x32_bf16 v[62:65], v[134:137], v[184:187], v[62:65]
	v_mfma_f32_16x16x32_bf16 v[58:61], v[160:163], v[184:187], v[58:61]
	v_mfma_f32_16x16x32_bf16 v[46:49], v[134:137], v[200:203], v[46:49]
	v_mfma_f32_16x16x32_bf16 v[42:45], v[160:163], v[200:203], v[42:45]
	v_mfma_f32_16x16x32_bf16 v[30:33], v[134:137], v[208:211], v[30:33]
	v_mfma_f32_16x16x32_bf16 v[26:29], v[160:163], v[208:211], v[26:29]
	v_mfma_f32_16x16x32_bf16 v[14:17], v[134:137], v[216:219], v[14:17]
	v_mfma_f32_16x16x32_bf16 v[10:13], v[160:163], v[216:219], v[10:13]
	v_mfma_f32_16x16x32_bf16 v[54:57], v[164:167], v[180:183], v[54:57]
	v_mfma_f32_16x16x32_bf16 v[50:53], v[172:175], v[180:183], v[50:53]
	v_mfma_f32_16x16x32_bf16 v[38:41], v[164:167], v[196:199], v[38:41]
	v_mfma_f32_16x16x32_bf16 v[34:37], v[172:175], v[196:199], v[34:37]
	v_mfma_f32_16x16x32_bf16 v[22:25], v[164:167], v[204:207], v[22:25]
	v_mfma_f32_16x16x32_bf16 v[18:21], v[172:175], v[204:207], v[18:21]
	v_mfma_f32_16x16x32_bf16 v[6:9], v[164:167], v[212:215], v[6:9]
	v_mfma_f32_16x16x32_bf16 v[2:5], v[172:175], v[212:215], v[2:5]
	v_mfma_f32_16x16x32_bf16 v[54:57], v[168:171], v[184:187], v[54:57]
	v_mfma_f32_16x16x32_bf16 v[50:53], v[176:179], v[184:187], v[50:53]
	v_mfma_f32_16x16x32_bf16 v[38:41], v[168:171], v[200:203], v[38:41]
	v_mfma_f32_16x16x32_bf16 v[34:37], v[176:179], v[200:203], v[34:37]
	v_mfma_f32_16x16x32_bf16 v[22:25], v[168:171], v[208:211], v[22:25]
	v_mfma_f32_16x16x32_bf16 v[18:21], v[176:179], v[208:211], v[18:21]
	v_mfma_f32_16x16x32_bf16 v[6:9], v[168:171], v[216:219], v[6:9]
	v_mfma_f32_16x16x32_bf16 v[2:5], v[176:179], v[216:219], v[2:5]
	s_setprio 0
	s_barrier
; #define PG8_STAGE(bufoff, gbase, voff) do { _Pragma("unroll") for (int _i = 0; _i < 2; ++_i) \
;         __builtin_amdgcn_global_load_lds((const unsigned*)((const char*)(gbase) + (voff)[_i]), (PG8_LAS unsigned*)(lds + (bufoff) + ldsw + _i * 8192), 16, 0, 0); } while (0)
; #define PG8_LDA(dst, b, h) do { _Pragma("unroll") for (int m = 0; m < 4; ++m) _Pragma("unroll") for (int k = 0; k < 2; ++k) dst[m][k] = *(const PG8_LAS bf16x8*)(lds + PG8_SA(b, h) + aoff + m * 2048 + k * 1024); } while (0)
; #define PG8_LDB(dst, b, h) do { _Pragma("unroll") for (int n = 0; n < 2; ++n) _Pragma("unroll") for (int k = 0; k < 2; ++k) dst[n][k] = *(const PG8_LAS bf16x8*)(lds + PG8_SB(b, h) + boff + n * 2048 + k * 1024); } while (0)
; #define PG8_MMA(ai, bj, At, Bt) do { __builtin_amdgcn_s_setprio(1); _Pragma("unroll") for (int m = 0; m < 4; ++m) _Pragma("unroll") for (int n = 0; n < 2; ++n) _Pragma("unroll") for (int k = 0; k < 2; ++k) \
;         acc[ai][bj][m][n] = __builtin_amdgcn_mfma_f32_16x16x32_bf16(Bt[n][k], At[m][k], acc[ai][bj][m][n], 0, 0, 0); __builtin_amdgcn_s_setprio(0); } while (0)
; #define PG8_WAIT_V(n) asm volatile("s_waitcnt vmcnt(" #n ")" ::: "memory")
; #define PG8_WAIT_L(n) asm volatile("s_waitcnt lgkmcnt(" #n ")" ::: "memory")
; #define PG8_BAR __builtin_amdgcn_s_barrier()
; #define PG8_SCHED __builtin_amdgcn_sched_barrier(0)
; template <class Epi, class Sched, bool ALIGN_EPI = false, bool SP2 = false>
; __device__ __forceinline__ void gemm_phase(PG8_LAS unsigned char* lds, const Gemm g, const Sched& S, const Epi& E) {
;     ...
;             PG8_LDB(B0, 1, 0); PG8_LDB(B1, 1, 1); PG8_SCHED; PG8_LDA(At, 1, 0); PG8_STAGE(PG8_SA(0, 1), a2 + hstep, voffA);
;             PG8_WAIT_V(8); PG8_WAIT_L(0); PG8_BAR; PG8_MMA(0, 0, At, B0); PG8_MMA(0, 1, At, B1); PG8_BAR; PG8_SCHED;
.Lpz6_mid:
	s_add_i32 s38, 0, 0x18000
	v_add_u32_e32 v146, s38, v191
	s_add_i32 s39, 0, 0x1c000
	ds_read_b128 v[130:133], v146
	ds_read_b128 v[134:137], v146 offset:1024
	ds_read_b128 v[156:159], v146 offset:2048
	ds_read_b128 v[160:163], v146 offset:3072
	v_add_u32_e32 v146, s39, v191
	ds_read_b128 v[164:167], v146
	ds_read_b128 v[168:171], v146 offset:1024
	ds_read_b128 v[172:175], v146 offset:2048
	ds_read_b128 v[176:179], v146 offset:3072
	s_add_u32 s4, s30, 0xb0000
	s_addc_u32 s5, s31, 0
	s_mov_b32 m0, s47
	v_lshl_add_u64 v[226:227], s[4:5], 0, v[138:139]
	ds_read_b128 v[180:183], v194 offset:32768
	ds_read_b128 v[184:187], v194 offset:33792
	ds_read_b128 v[196:199], v194 offset:34816
	ds_read_b128 v[200:203], v194 offset:35840
	ds_read_b128 v[204:207], v194 offset:36864
	ds_read_b128 v[208:211], v194 offset:37888
	ds_read_b128 v[212:215], v194 offset:38912
	ds_read_b128 v[216:219], v194 offset:39936
	global_load_lds_dwordx4 v[226:227], off
	v_lshl_add_u64 v[226:227], s[4:5], 0, v[142:143]
	s_mov_b32 m0, s48
	s_nop 0
	global_load_lds_dwordx4 v[226:227], off
	s_waitcnt vmcnt(8)
	s_waitcnt lgkmcnt(0)
	s_barrier
	s_setprio 1
	v_mfma_f32_16x16x32_bf16 v[126:129], v[130:133], v[180:183], v[126:129]
	v_mfma_f32_16x16x32_bf16 v[122:125], v[156:159], v[180:183], v[122:125]
	v_mfma_f32_16x16x32_bf16 v[110:113], v[130:133], v[196:199], v[110:113]
	v_mfma_f32_16x16x32_bf16 v[106:109], v[156:159], v[196:199], v[106:109]
	v_mfma_f32_16x16x32_bf16 v[94:97], v[130:133], v[204:207], v[94:97]
	v_mfma_f32_16x16x32_bf16 v[90:93], v[156:159], v[204:207], v[90:93]
	v_mfma_f32_16x16x32_bf16 v[78:81], v[130:133], v[212:215], v[78:81]
	v_mfma_f32_16x16x32_bf16 v[74:77], v[156:159], v[212:215], v[74:77]
	v_mfma_f32_16x16x32_bf16 v[126:129], v[134:137], v[184:187], v[126:129]
	v_mfma_f32_16x16x32_bf16 v[122:125], v[160:163], v[184:187], v[122:125]
	v_mfma_f32_16x16x32_bf16 v[110:113], v[134:137], v[200:203], v[110:113]
	v_mfma_f32_16x16x32_bf16 v[106:109], v[160:163], v[200:203], v[106:109]
	v_mfma_f32_16x16x32_bf16 v[94:97], v[134:137], v[208:211], v[94:97]
	v_mfma_f32_16x16x32_bf16 v[90:93], v[160:163], v[208:211], v[90:93]
	v_mfma_f32_16x16x32_bf16 v[78:81], v[134:137], v[216:219], v[78:81]
	v_mfma_f32_16x16x32_bf16 v[74:77], v[160:163], v[216:219], v[74:77]
	v_mfma_f32_16x16x32_bf16 v[118:121], v[164:167], v[180:183], v[118:121]
	v_mfma_f32_16x16x32_bf16 v[114:117], v[172:175], v[180:183], v[114:117]
	v_mfma_f32_16x16x32_bf16 v[102:105], v[164:167], v[196:199], v[102:105]
	v_mfma_f32_16x16x32_bf16 v[98:101], v[172:175], v[196:199], v[98:101]
	v_mfma_f32_16x16x32_bf16 v[86:89], v[164:167], v[204:207], v[86:89]
	v_mfma_f32_16x16x32_bf16 v[82:85], v[172:175], v[204:207], v[82:85]
	v_mfma_f32_16x16x32_bf16 v[70:73], v[164:167], v[212:215], v[70:73]
	v_mfma_f32_16x16x32_bf16 v[66:69], v[172:175], v[212:215], v[66:69]
	v_mfma_f32_16x16x32_bf16 v[118:121], v[168:171], v[184:187], v[118:121]
	v_mfma_f32_16x16x32_bf16 v[114:117], v[176:179], v[184:187], v[114:117]
	v_mfma_f32_16x16x32_bf16 v[102:105], v[168:171], v[200:203], v[102:105]
	v_mfma_f32_16x16x32_bf16 v[98:101], v[176:179], v[200:203], v[98:101]
	v_mfma_f32_16x16x32_bf16 v[86:89], v[168:171], v[208:211], v[86:89]
	v_mfma_f32_16x16x32_bf16 v[82:85], v[176:179], v[208:211], v[82:85]
	v_mfma_f32_16x16x32_bf16 v[70:73], v[168:171], v[216:219], v[70:73]
	v_mfma_f32_16x16x32_bf16 v[66:69], v[176:179], v[216:219], v[66:69]
	s_setprio 0
	s_barrier
; #define PG8_STAGE(bufoff, gbase, voff) do { _Pragma("unroll") for (int _i = 0; _i < 2; ++_i) \
;         __builtin_amdgcn_global_load_lds((const unsigned*)((const char*)(gbase) + (voff)[_i]), (PG8_LAS unsigned*)(lds + (bufoff) + ldsw + _i * 8192), 16, 0, 0); } while (0)
; #define PG8_LDA(dst, b, h) do { _Pragma("unroll") for (int m = 0; m < 4; ++m) _Pragma("unroll") for (int k = 0; k < 2; ++k) dst[m][k] = *(const PG8_LAS bf16x8*)(lds + PG8_SA(b, h) + aoff + m * 2048 + k * 1024); } while (0)
; #define PG8_MMA(ai, bj, At, Bt) do { __builtin_amdgcn_s_setprio(1); _Pragma("unroll") for (int m = 0; m < 4; ++m) _Pragma("unroll") for (int n = 0; n < 2; ++n) _Pragma("unroll") for (int k = 0; k < 2; ++k) \
;         acc[ai][bj][m][n] = __builtin_amdgcn_mfma_f32_16x16x32_bf16(Bt[n][k], At[m][k], acc[ai][bj][m][n], 0, 0, 0); __builtin_amdgcn_s_setprio(0); } while (0)
; #define PG8_WAIT_V(n) asm volatile("s_waitcnt vmcnt(" #n ")" ::: "memory")
; #define PG8_WAIT_L(n) asm volatile("s_waitcnt lgkmcnt(" #n ")" ::: "memory")
; #define PG8_BAR __builtin_amdgcn_s_barrier()
; #define PG8_SCHED __builtin_amdgcn_sched_barrier(0)
; template <class Epi, class Sched, bool ALIGN_EPI = false, bool SP2 = false>
; __device__ __forceinline__ void gemm_phase(PG8_LAS unsigned char* lds, const Gemm g, const Sched& S, const Epi& E) {
;     ...
;             PG8_LDA(At, 1, 1); PG8_STAGE(PG8_SB(1, 0), b3, voffB); PG8_STAGE(PG8_SB(1, 1), b3 + hstep, voffB); PG8_STAGE(PG8_SA(1, 0), a3, voffA);
;             PG8_WAIT_V(8); PG8_WAIT_L(0); PG8_BAR; PG8_MMA(1, 0, At, B0); PG8_MMA(1, 1, At, B1); PG8_BAR; PG8_SCHED;
;     ...
;         if constexpr (ALIGN_EPI) { if (wr == 0) PG8_BAR; }
	s_add_i32 s4, s38, s44
	v_lshl_add_u64 v[188:189], v[188:189], 0, s[18:19]
	s_mov_b32 m0, s4
	ds_read_b128 v[180:183], v194 offset:49152
	ds_read_b128 v[184:187], v194 offset:50176
	ds_read_b128 v[196:199], v194 offset:51200
	ds_read_b128 v[200:203], v194 offset:52224
	ds_read_b128 v[204:207], v194 offset:53248
	ds_read_b128 v[208:211], v194 offset:54272
	ds_read_b128 v[212:215], v194 offset:55296
	ds_read_b128 v[216:219], v194 offset:56320
	global_load_lds_dwordx4 v[188:189], off
	s_add_i32 m0, s4, 0x2000
	s_add_u32 s4, s6, 0xb0080
	v_lshl_add_u64 v[188:189], v[220:221], 0, s[18:19]
	s_addc_u32 s5, s7, 0
	s_add_i32 s6, s39, s44
	global_load_lds_dwordx4 v[188:189], off
	v_lshl_add_u64 v[188:189], s[4:5], 0, v[140:141]
	s_mov_b32 m0, s6
	s_nop 0
	global_load_lds_dwordx4 v[188:189], off
	v_lshl_add_u64 v[188:189], s[4:5], 0, v[144:145]
	s_add_i32 m0, s6, 0x2000
	s_nop 0
	global_load_lds_dwordx4 v[188:189], off
	v_lshl_add_u64 v[188:189], v[222:223], 0, s[20:21]
	s_mov_b32 m0, s55
	s_nop 0
	global_load_lds_dwordx4 v[188:189], off
	v_lshl_add_u64 v[188:189], v[224:225], 0, s[20:21]
	s_mov_b32 m0, s56
	s_nop 0
	global_load_lds_dwordx4 v[188:189], off
	s_waitcnt vmcnt(8)
	s_waitcnt lgkmcnt(0)
	s_barrier
	s_setprio 1
	v_mfma_f32_16x16x32_bf16 v[62:65], v[130:133], v[180:183], v[62:65]
	v_mfma_f32_16x16x32_bf16 v[58:61], v[156:159], v[180:183], v[58:61]
	v_mfma_f32_16x16x32_bf16 v[46:49], v[130:133], v[196:199], v[46:49]
	v_mfma_f32_16x16x32_bf16 v[42:45], v[156:159], v[196:199], v[42:45]
	v_mfma_f32_16x16x32_bf16 v[30:33], v[130:133], v[204:207], v[30:33]
	v_mfma_f32_16x16x32_bf16 v[26:29], v[156:159], v[204:207], v[26:29]
	v_mfma_f32_16x16x32_bf16 v[14:17], v[130:133], v[212:215], v[14:17]
	v_mfma_f32_16x16x32_bf16 v[10:13], v[156:159], v[212:215], v[10:13]
	v_mfma_f32_16x16x32_bf16 v[62:65], v[134:137], v[184:187], v[62:65]
	v_mfma_f32_16x16x32_bf16 v[58:61], v[160:163], v[184:187], v[58:61]
	v_mfma_f32_16x16x32_bf16 v[46:49], v[134:137], v[200:203], v[46:49]
	v_mfma_f32_16x16x32_bf16 v[42:45], v[160:163], v[200:203], v[42:45]
	v_mfma_f32_16x16x32_bf16 v[30:33], v[134:137], v[208:211], v[30:33]
	v_mfma_f32_16x16x32_bf16 v[26:29], v[160:163], v[208:211], v[26:29]
	v_mfma_f32_16x16x32_bf16 v[14:17], v[134:137], v[216:219], v[14:17]
	v_mfma_f32_16x16x32_bf16 v[10:13], v[160:163], v[216:219], v[10:13]
	v_mfma_f32_16x16x32_bf16 v[54:57], v[164:167], v[180:183], v[54:57]
	v_mfma_f32_16x16x32_bf16 v[50:53], v[172:175], v[180:183], v[50:53]
	v_mfma_f32_16x16x32_bf16 v[38:41], v[164:167], v[196:199], v[38:41]
	v_mfma_f32_16x16x32_bf16 v[34:37], v[172:175], v[196:199], v[34:37]
	v_mfma_f32_16x16x32_bf16 v[22:25], v[164:167], v[204:207], v[22:25]
	v_mfma_f32_16x16x32_bf16 v[18:21], v[172:175], v[204:207], v[18:21]
	v_mfma_f32_16x16x32_bf16 v[6:9], v[164:167], v[212:215], v[6:9]
	v_mfma_f32_16x16x32_bf16 v[2:5], v[172:175], v[212:215], v[2:5]
	v_mfma_f32_16x16x32_bf16 v[54:57], v[168:171], v[184:187], v[54:57]
	v_mfma_f32_16x16x32_bf16 v[50:53], v[176:179], v[184:187], v[50:53]
	v_mfma_f32_16x16x32_bf16 v[38:41], v[168:171], v[200:203], v[38:41]
	v_mfma_f32_16x16x32_bf16 v[34:37], v[176:179], v[200:203], v[34:37]
	v_mfma_f32_16x16x32_bf16 v[22:25], v[168:171], v[208:211], v[22:25]
	v_mfma_f32_16x16x32_bf16 v[18:21], v[176:179], v[208:211], v[18:21]
	v_mfma_f32_16x16x32_bf16 v[6:9], v[168:171], v[216:219], v[6:9]
	v_mfma_f32_16x16x32_bf16 v[2:5], v[176:179], v[216:219], v[2:5]
	s_setprio 0
	s_barrier
	s_add_i32 s37, s37, 2
	s_add_u32 s35, s35, 0x100
	s_addc_u32 s36, s36, 0
	s_cmp_gt_u32 s37, 41
	s_mov_b64 s[4:5], s[0:1]
	s_cbranch_scc0 .LBB0_1069
	s_and_b64 vcc, exec, s[22:23]
	s_cbranch_vccz .LBB0_1072
	s_barrier
